# G1 epilogue + attention write-out stores write-through (sc1) so the full barriers' wbl2 is short, on stack16
# speedup vs baseline: 1.0039x; 1.0039x over previous
; __device__ __forceinline__ unsigned cvt_pk_bf16(float lo, float hi) { unsigned r; asm volatile("v_cvt_pk_bf16_f32 %0, %1, %2" : "=v"(r) : "v"(lo), "v"(hi)); return r; }
;     __device__ __forceinline__ void operator()(const f32x4 (&acc)[2][2][4][2], const Unit& u, int wr, int wc, int fr, int fq) const {
;     ...
;                 const int row = row0 + ai * HALF + m * 16; const float rs = tb[ai * 64 + m * 16 + fr];
;                 f32x4 v[2][2]; float ss = 0.f;
; #pragma unroll
;                 for (int bj = 0; bj < 2; ++bj)
; #pragma unroll
;                     for (int n = 0; n < 2; ++n) { v[bj][n] = acc[ai][bj][m][n] * rs; const f32x4 t = v[bj][n]; ss += (t[0] * t[0] + t[1] * t[1]) + (t[2] * t[2] + t[3] * t[3]); }
;                 ss += __shfl_xor(ss, 16); ss += __shfl_xor(ss, 32);
;                 const float hr = __builtin_amdgcn_rsqf(ss * (1.0f / 64.0f) + 1e-6f);
; #pragma unroll
;                 for (int bj = 0; bj < 2; ++bj)
; #pragma unroll
;                     for (int n = 0; n < 2; ++n) v[bj][n] = v[bj][n] * hr * gv[bj][n];
; #pragma unroll
;                 for (int n = 0; n < 2; ++n) {
;                     const f32x4 c = rc[m][n], s = rsn[m][n];
;                     f32x4 mine = v[0][n], other;
; #pragma unroll
;                     for (int e = 0; e < 4; ++e) other[e] = __shfl_xor(mine[e], 16);
;                     if (fq == 0) v[0][n] = mine * c - other * s;
;                     else if (fq == 1) v[0][n] = mine * c + other * s;
;                 }
;                 bf16_t* rowp = dst + (size_t)row * 1024 + head * 64 + 8 * fq;
; #pragma unroll
;                 for (int bj = 0; bj < 2; ++bj) { u32x4 w; w.x = cvt_pk_bf16(v[bj][0][0], v[bj][0][1]); w.y = cvt_pk_bf16(v[bj][0][2], v[bj][0][3]);
;                     w.z = cvt_pk_bf16(v[bj][1][0], v[bj][1][1]); w.w = cvt_pk_bf16(v[bj][1][2], v[bj][1][3]); *(u32x4*)(rowp + bj * 32) = w; }
.LBB0_159:
	s_or_b64 exec, exec, s[4:5]
	s_lshl_b32 s4, s29, 2
	s_and_b32 s30, s4, 12
	s_and_b64 s[4:5], vcc, exec
	s_brev_b32 s4, 16
	s_cselect_b32 s4, s4, 0xa000000
	s_add_u32 s4, s38, s4
	s_addc_u32 s5, s39, 0
	s_or_b32 s30, s30, s23
	s_lshl_b32 s30, s30, 7
	s_add_u32 s4, s4, s30
	v_mov_b32_e32 v152, v214
	v_mov_b32_e32 v153, v214
	v_pk_mul_f32 v[174:175], v[214:215], v[144:145]
	s_addc_u32 s5, s5, 0
	v_lshlrev_b32_e32 v144, 1, v202
	v_mov_b32_e32 v145, v177
	s_waitcnt lgkmcnt(6)
	v_pk_mul_f32 v[172:173], v[152:153], v[150:151]
	s_waitcnt lgkmcnt(0)
	v_pk_mul_f32 v[168:169], v[214:215], v[148:149]
	v_lshl_add_u64 v[214:215], s[4:5], 0, v[144:145]
	v_pk_mul_f32 v[144:145], v[224:225], v[236:237]
	v_pk_mul_f32 v[170:171], v[152:153], v[146:147]
	v_pk_mul_f32 v[146:147], v[220:221], v[226:227]
	v_pk_mul_f32 v[148:149], v[172:173], v[144:145]
	v_pk_mul_f32 v[144:145], v[222:223], v[236:237]
	v_ashrrev_i32_e32 v209, 31, v208
	v_pk_mul_f32 v[150:151], v[168:169], v[146:147]
	v_pk_mul_f32 v[146:147], v[218:219], v[226:227]
	v_pk_mul_f32 v[152:153], v[170:171], v[144:145]
	v_lshlrev_b64 v[144:145], 11, v[208:209]
	v_pk_mul_f32 v[154:155], v[174:175], v[146:147]
	v_lshl_add_u64 v[156:157], v[214:215], 0, v[144:145]
	v_cvt_pk_bf16_f32 v144, v234, v235
	v_cvt_pk_bf16_f32 v145, v232, v233
	v_cvt_pk_bf16_f32 v146, v230, v231
	v_cvt_pk_bf16_f32 v147, v228, v229
	flat_store_dwordx4 v[156:157], v[144:147] sc1
	v_cmp_lt_i32_e32 vcc, 0, v203
	s_nop 0
	v_cvt_pk_bf16_f32 v144, v150, v151
	v_cvt_pk_bf16_f32 v145, v148, v149
	v_cvt_pk_bf16_f32 v146, v154, v155
	v_cvt_pk_bf16_f32 v147, v152, v153
	flat_store_dwordx4 v[156:157], v[144:147] offset:64 sc1
	ds_read_b32 v144, v250 offset:64
	s_waitcnt lgkmcnt(0)
	v_pk_mul_f32 v[158:159], v[108:109], v[144:145] op_sel_hi:[1,0]
	v_pk_mul_f32 v[146:147], v[110:111], v[144:145] op_sel_hi:[1,0]
	v_pk_mul_f32 v[150:151], v[158:159], v[158:159]
	v_pk_mul_f32 v[148:149], v[146:147], v[146:147]
	v_pk_mul_f32 v[220:221], v[106:107], v[144:145] op_sel_hi:[1,0]
	v_pk_mov_b32 v[152:153], v[150:151], v[148:149] op_sel:[1,0]
	v_mov_b32_e32 v151, v149
	v_pk_add_f32 v[148:149], v[152:153], v[150:151]
	v_pk_mul_f32 v[218:219], v[104:105], v[144:145] op_sel_hi:[1,0]
	v_pk_add_f32 v[156:157], v[148:149], v[148:149] op_sel_hi:[0,1]
	v_pk_mul_f32 v[148:149], v[220:221], v[220:221]
	v_pk_mul_f32 v[150:151], v[218:219], v[218:219]
	v_pk_mul_f32 v[154:155], v[98:99], v[144:145] op_sel_hi:[1,0]
	v_pk_mov_b32 v[152:153], v[150:151], v[148:149] op_sel:[1,0]
	v_mov_b32_e32 v151, v149
	v_pk_add_f32 v[148:149], v[152:153], v[150:151]
	v_pk_mul_f32 v[150:151], v[102:103], v[144:145] op_sel_hi:[1,0]
	v_pk_add_f32 v[160:161], v[148:149], v[148:149] op_sel_hi:[0,1]
	v_pk_mul_f32 v[148:149], v[100:101], v[144:145] op_sel_hi:[1,0]
	v_mul_f32_e32 v156, v154, v154
	v_mul_f32_e32 v152, v148, v148
	v_pk_fma_f32 v[162:163], v[148:149], v[148:149], v[152:153] op_sel_hi:[1,1,0]
	v_mul_f32_e32 v152, v150, v150
	v_pk_fma_f32 v[222:223], v[150:151], v[150:151], v[152:153] op_sel_hi:[1,1,0]
	v_pk_mul_f32 v[152:153], v[96:97], v[144:145] op_sel_hi:[1,0]
	v_mul_f32_e32 v160, v155, v155
	v_mul_f32_e32 v162, v152, v152
	v_mul_f32_e32 v222, v153, v153
	v_pk_add_f32 v[144:145], v[162:163], v[222:223]
	v_pk_add_f32 v[156:157], v[156:157], v[160:161]
	s_nop 0
	v_pk_add_f32 v[144:145], v[144:145], v[156:157]
	s_nop 0
	v_add_f32_e32 v144, v144, v145
	ds_bpermute_b32 v145, v243, v144
	s_waitcnt lgkmcnt(0)
	v_add_f32_e32 v144, v144, v145
	ds_bpermute_b32 v145, v242, v144
	s_waitcnt lgkmcnt(0)
	v_add_f32_e32 v144, v144, v145
	v_fmamk_f32 v144, v144, 0x3c800000, v241
	v_rsq_f32_e32 v156, v144
	s_nop 0
	v_mov_b32_e32 v157, v156
	v_pk_mul_f32 v[144:145], v[158:159], v[156:157] op_sel_hi:[1,0]
	v_pk_mul_f32 v[146:147], v[146:147], v[156:157] op_sel_hi:[1,0]
	v_pk_mul_f32 v[160:161], v[210:211], v[144:145]
	v_pk_mul_f32 v[158:159], v[212:213], v[146:147]
	ds_bpermute_b32 v144, v243, v160
	ds_bpermute_b32 v145, v243, v161
	ds_bpermute_b32 v222, v243, v158
	ds_bpermute_b32 v223, v243, v159
	v_mov_b32_e32 v162, v156
	v_mov_b32_e32 v163, v156
	s_and_saveexec_b64 s[4:5], vcc
	s_xor_b64 s[4:5], exec, s[4:5]
	s_cbranch_execz .LBB0_163
	v_cmp_eq_u32_e32 vcc, 1, v203
	s_and_saveexec_b64 s[34:35], vcc
	s_cbranch_execz .LBB0_162
	v_pk_mul_f32 v[142:143], v[142:143], v[158:159]
	v_pk_mul_f32 v[140:141], v[140:141], v[160:161]
	s_waitcnt lgkmcnt(0)
	v_pk_fma_f32 v[158:159], v[138:139], v[222:223], v[142:143]
	v_pk_fma_f32 v[160:161], v[136:137], v[144:145], v[140:141]

; __device__ __forceinline__ unsigned cvt_pk_bf16(float lo, float hi) { unsigned r; asm volatile("v_cvt_pk_bf16_f32 %0, %1, %2" : "=v"(r) : "v"(lo), "v"(hi)); return r; }
;     __device__ __forceinline__ void operator()(const f32x4 (&acc)[2][2][4][2], const Unit& u, int wr, int wc, int fr, int fq) const {
;     ...
;             f32x4 rc[4][2], rsn[4][2];
; #pragma unroll
;             for (int m = 2 * (aim & 1); m < 2 * (aim & 1) + 2; ++m)
; #pragma unroll
;                 for (int n = 0; n < 2; ++n) { const int pos = (row0 + ai * HALF + m * 16) & 8191; rc[m][n] = *(const f32x4*)(ropeC + pos * 8 + 4 * n); rsn[m][n] = *(const f32x4*)(ropeS + pos * 8 + 4 * n); }
;             asm volatile("" ::: "memory");
; #pragma unroll
;             for (int m = 2 * (aim & 1); m < 2 * (aim & 1) + 2; ++m) {
;                 const int row = row0 + ai * HALF + m * 16; const float rs = tb[ai * 64 + m * 16 + fr];
;                 f32x4 v[2][2]; float ss = 0.f;
; #pragma unroll
;                 for (int bj = 0; bj < 2; ++bj)
; #pragma unroll
;                     for (int n = 0; n < 2; ++n) { v[bj][n] = acc[ai][bj][m][n] * rs; const f32x4 t = v[bj][n]; ss += (t[0] * t[0] + t[1] * t[1]) + (t[2] * t[2] + t[3] * t[3]); }
;                 ss += __shfl_xor(ss, 16); ss += __shfl_xor(ss, 32);
;                 const float hr = __builtin_amdgcn_rsqf(ss * (1.0f / 64.0f) + 1e-6f);
; #pragma unroll
;                 for (int bj = 0; bj < 2; ++bj)
; #pragma unroll
;                     for (int n = 0; n < 2; ++n) v[bj][n] = v[bj][n] * hr * gv[bj][n];
; #pragma unroll
;                 for (int n = 0; n < 2; ++n) {
;                     const f32x4 c = rc[m][n], s = rsn[m][n];
;                     f32x4 mine = v[0][n], other;
; #pragma unroll
;                     for (int e = 0; e < 4; ++e) other[e] = __shfl_xor(mine[e], 16);
;                     if (fq == 0) v[0][n] = mine * c - other * s;
;                     else if (fq == 1) v[0][n] = mine * c + other * s;
;                 }
;                 bf16_t* rowp = dst + (size_t)row * 1024 + head * 64 + 8 * fq;
; #pragma unroll
;                 for (int bj = 0; bj < 2; ++bj) { u32x4 w; w.x = cvt_pk_bf16(v[bj][0][0], v[bj][0][1]); w.y = cvt_pk_bf16(v[bj][0][2], v[bj][0][3]);
;                     w.z = cvt_pk_bf16(v[bj][1][0], v[bj][1][1]); w.w = cvt_pk_bf16(v[bj][1][2], v[bj][1][3]); *(u32x4*)(rowp + bj * 32) = w; }
.LBB0_171:
	s_or_b64 exec, exec, s[4:5]
	v_pk_mul_f32 v[128:129], v[150:151], v[162:163]
	v_pk_mul_f32 v[130:131], v[148:149], v[156:157]
	v_pk_mul_f32 v[132:133], v[172:173], v[128:129]
	v_pk_mul_f32 v[128:129], v[154:155], v[162:163]
	v_pk_mul_f32 v[134:135], v[168:169], v[130:131]
	v_pk_mul_f32 v[136:137], v[170:171], v[128:129]
	v_or_b32_e32 v128, 16, v208
	v_ashrrev_i32_e32 v129, 31, v128
	v_lshlrev_b64 v[128:129], 11, v[128:129]
	v_pk_mul_f32 v[130:131], v[152:153], v[156:157]
	s_waitcnt lgkmcnt(0)
	v_lshl_add_u64 v[144:145], v[214:215], 0, v[128:129]
	v_cvt_pk_bf16_f32 v128, v160, v161
	v_cvt_pk_bf16_f32 v129, v158, v159
	v_pk_mul_f32 v[138:139], v[174:175], v[130:131]
	v_cvt_pk_bf16_f32 v130, v142, v143
	v_cvt_pk_bf16_f32 v131, v140, v141
	flat_store_dwordx4 v[144:145], v[128:131] sc1
	v_cmp_lt_i32_e32 vcc, 0, v203
	s_nop 0
	v_cvt_pk_bf16_f32 v128, v134, v135
	v_cvt_pk_bf16_f32 v129, v132, v133
	v_cvt_pk_bf16_f32 v130, v138, v139
	v_cvt_pk_bf16_f32 v131, v136, v137
	flat_store_dwordx4 v[144:145], v[128:131] offset:64 sc1
	s_nop 1
	v_or_b32_e32 v128, 0x400, v216
	v_mov_b32_e32 v129, v177
	v_lshl_add_u64 v[130:131], s[40:41], 0, v[128:129]
	v_lshl_add_u64 v[128:129], s[42:43], 0, v[128:129]
	flat_load_dwordx4 v[156:159], v[130:131]
	flat_load_dwordx4 v[144:147], v[130:131] offset:16
	flat_load_dwordx4 v[152:155], v[128:129]
	flat_load_dwordx4 v[148:151], v[128:129] offset:16
	v_or_b32_e32 v128, 0x600, v216
	v_mov_b32_e32 v129, v177
	v_lshl_add_u64 v[130:131], s[40:41], 0, v[128:129]
	v_lshl_add_u64 v[132:133], s[42:43], 0, v[128:129]
	flat_load_dwordx4 v[140:143], v[130:131]
	s_nop 0
	flat_load_dwordx4 v[128:131], v[130:131] offset:16
	s_nop 0
	flat_load_dwordx4 v[136:139], v[132:133]
	s_nop 0
	flat_load_dwordx4 v[132:135], v[132:133] offset:16
	ds_read_b32 v160, v250 offset:128
	s_waitcnt lgkmcnt(0)
	v_pk_mul_f32 v[162:163], v[94:95], v[160:161] op_sel_hi:[1,0]
	v_pk_mul_f32 v[226:227], v[92:93], v[160:161] op_sel_hi:[1,0]
	v_pk_mul_f32 v[216:217], v[162:163], v[162:163]
	v_pk_mul_f32 v[218:219], v[226:227], v[226:227]
	v_pk_mul_f32 v[234:235], v[90:91], v[160:161] op_sel_hi:[1,0]
	v_pk_mov_b32 v[220:221], v[218:219], v[216:217] op_sel:[1,0]
	v_mov_b32_e32 v219, v217
	v_pk_add_f32 v[216:217], v[220:221], v[218:219]
	v_pk_mul_f32 v[232:233], v[88:89], v[160:161] op_sel_hi:[1,0]
	v_pk_add_f32 v[224:225], v[216:217], v[216:217] op_sel_hi:[0,1]
	v_pk_mul_f32 v[216:217], v[234:235], v[234:235]
	v_pk_mul_f32 v[218:219], v[232:233], v[232:233]
	v_pk_mul_f32 v[222:223], v[82:83], v[160:161] op_sel_hi:[1,0]
	v_pk_mov_b32 v[220:221], v[218:219], v[216:217] op_sel:[1,0]
	v_mov_b32_e32 v219, v217
	v_pk_add_f32 v[216:217], v[220:221], v[218:219]
	v_pk_mul_f32 v[218:219], v[86:87], v[160:161] op_sel_hi:[1,0]
	v_pk_add_f32 v[228:229], v[216:217], v[216:217] op_sel_hi:[0,1]
	v_pk_mul_f32 v[216:217], v[84:85], v[160:161] op_sel_hi:[1,0]
	v_mul_f32_e32 v224, v222, v222
	v_mul_f32_e32 v220, v216, v216
	v_pk_fma_f32 v[230:231], v[216:217], v[216:217], v[220:221] op_sel_hi:[1,1,0]
	v_mul_f32_e32 v220, v218, v218
	v_pk_fma_f32 v[236:237], v[218:219], v[218:219], v[220:221] op_sel_hi:[1,1,0]
	v_pk_mul_f32 v[220:221], v[80:81], v[160:161] op_sel_hi:[1,0]
	v_mul_f32_e32 v228, v223, v223
	v_mul_f32_e32 v230, v220, v220
	v_mul_f32_e32 v236, v221, v221
	v_pk_add_f32 v[160:161], v[230:231], v[236:237]
	v_pk_add_f32 v[224:225], v[224:225], v[228:229]
	s_nop 0
	v_pk_add_f32 v[160:161], v[160:161], v[224:225]
	s_nop 0
	v_add_f32_e32 v160, v160, v161
	ds_bpermute_b32 v161, v243, v160
	s_waitcnt lgkmcnt(0)
	v_add_f32_e32 v160, v160, v161
	ds_bpermute_b32 v161, v242, v160
	s_waitcnt lgkmcnt(0)
	v_add_f32_e32 v160, v160, v161
	v_fmamk_f32 v160, v160, 0x3c800000, v241
	v_rsq_f32_e32 v224, v160
	s_nop 0
	v_mov_b32_e32 v225, v224
	v_pk_mul_f32 v[160:161], v[226:227], v[224:225] op_sel_hi:[1,0]
	v_pk_mul_f32 v[162:163], v[162:163], v[224:225] op_sel_hi:[1,0]
	v_pk_mul_f32 v[228:229], v[210:211], v[160:161]
	v_pk_mul_f32 v[226:227], v[212:213], v[162:163]
	ds_bpermute_b32 v160, v243, v228
	ds_bpermute_b32 v161, v243, v229
	ds_bpermute_b32 v236, v243, v226
	ds_bpermute_b32 v237, v243, v227
	v_mov_b32_e32 v230, v224
	v_mov_b32_e32 v231, v224
	s_and_saveexec_b64 s[4:5], vcc
	s_xor_b64 s[4:5], exec, s[4:5]
	s_cbranch_execz .LBB0_175
	v_cmp_eq_u32_e32 vcc, 1, v203
	s_and_saveexec_b64 s[34:35], vcc
	s_cbranch_execz .LBB0_174
	s_waitcnt vmcnt(0)
	v_pk_mul_f32 v[158:159], v[158:159], v[226:227]
	v_pk_mul_f32 v[156:157], v[156:157], v[228:229]
	s_waitcnt lgkmcnt(0)
	v_pk_fma_f32 v[226:227], v[154:155], v[236:237], v[158:159]
	v_pk_fma_f32 v[228:229], v[152:153], v[160:161], v[156:157]

; __device__ __forceinline__ unsigned cvt_pk_bf16(float lo, float hi) { unsigned r; asm volatile("v_cvt_pk_bf16_f32 %0, %1, %2" : "=v"(r) : "v"(lo), "v"(hi)); return r; }
;     __device__ __forceinline__ void operator()(const f32x4 (&acc)[2][2][4][2], const Unit& u, int wr, int wc, int fr, int fq) const {
;     ...
;                 const int row = row0 + ai * HALF + m * 16; const float rs = tb[ai * 64 + m * 16 + fr];
;                 f32x4 v[2][2]; float ss = 0.f;
; #pragma unroll
;                 for (int bj = 0; bj < 2; ++bj)
; #pragma unroll
;                     for (int n = 0; n < 2; ++n) { v[bj][n] = acc[ai][bj][m][n] * rs; const f32x4 t = v[bj][n]; ss += (t[0] * t[0] + t[1] * t[1]) + (t[2] * t[2] + t[3] * t[3]); }
;                 ss += __shfl_xor(ss, 16); ss += __shfl_xor(ss, 32);
;                 const float hr = __builtin_amdgcn_rsqf(ss * (1.0f / 64.0f) + 1e-6f);
; #pragma unroll
;                 for (int bj = 0; bj < 2; ++bj)
; #pragma unroll
;                     for (int n = 0; n < 2; ++n) v[bj][n] = v[bj][n] * hr * gv[bj][n];
; #pragma unroll
;                 for (int n = 0; n < 2; ++n) {
;                     const f32x4 c = rc[m][n], s = rsn[m][n];
;                     f32x4 mine = v[0][n], other;
; #pragma unroll
;                     for (int e = 0; e < 4; ++e) other[e] = __shfl_xor(mine[e], 16);
;                     if (fq == 0) v[0][n] = mine * c - other * s;
;                     else if (fq == 1) v[0][n] = mine * c + other * s;
;                 }
;                 bf16_t* rowp = dst + (size_t)row * 1024 + head * 64 + 8 * fq;
; #pragma unroll
;                 for (int bj = 0; bj < 2; ++bj) { u32x4 w; w.x = cvt_pk_bf16(v[bj][0][0], v[bj][0][1]); w.y = cvt_pk_bf16(v[bj][0][2], v[bj][0][3]);
;                     w.z = cvt_pk_bf16(v[bj][1][0], v[bj][1][1]); w.w = cvt_pk_bf16(v[bj][1][2], v[bj][1][3]); *(u32x4*)(rowp + bj * 32) = w; }
.LBB0_183:
	s_or_b64 exec, exec, s[4:5]
	v_pk_mul_f32 v[144:145], v[218:219], v[230:231]
	v_pk_mul_f32 v[146:147], v[216:217], v[224:225]
	v_pk_mul_f32 v[148:149], v[172:173], v[144:145]
	v_pk_mul_f32 v[144:145], v[222:223], v[230:231]
	v_pk_mul_f32 v[150:151], v[168:169], v[146:147]
	s_waitcnt lgkmcnt(2)
	v_pk_mul_f32 v[152:153], v[170:171], v[144:145]
	v_or_b32_e32 v144, 32, v208
	v_ashrrev_i32_e32 v145, 31, v144
	v_pk_mul_f32 v[146:147], v[220:221], v[224:225]
	v_lshlrev_b64 v[144:145], 11, v[144:145]
	v_pk_mul_f32 v[154:155], v[174:175], v[146:147]
	s_waitcnt lgkmcnt(0)
	v_lshl_add_u64 v[160:161], v[214:215], 0, v[144:145]
	v_cvt_pk_bf16_f32 v144, v228, v229
	v_cvt_pk_bf16_f32 v145, v226, v227
	v_cvt_pk_bf16_f32 v146, v158, v159
	v_cvt_pk_bf16_f32 v147, v156, v157
	flat_store_dwordx4 v[160:161], v[144:147] sc1
	v_cmp_lt_i32_e32 vcc, 0, v203
	s_nop 0
	v_cvt_pk_bf16_f32 v144, v150, v151
	v_cvt_pk_bf16_f32 v145, v148, v149
	v_cvt_pk_bf16_f32 v146, v154, v155
	v_cvt_pk_bf16_f32 v147, v152, v153
	flat_store_dwordx4 v[160:161], v[144:147] offset:64 sc1
	ds_read_b32 v144, v250 offset:192
	s_waitcnt lgkmcnt(0)
	v_pk_mul_f32 v[158:159], v[76:77], v[144:145] op_sel_hi:[1,0]
	v_pk_mul_f32 v[146:147], v[78:79], v[144:145] op_sel_hi:[1,0]
	v_pk_mul_f32 v[150:151], v[158:159], v[158:159]
	v_pk_mul_f32 v[148:149], v[146:147], v[146:147]
	v_pk_mul_f32 v[218:219], v[74:75], v[144:145] op_sel_hi:[1,0]
	v_pk_mov_b32 v[152:153], v[150:151], v[148:149] op_sel:[1,0]
	v_mov_b32_e32 v151, v149
	v_pk_add_f32 v[148:149], v[152:153], v[150:151]
	v_pk_mul_f32 v[216:217], v[72:73], v[144:145] op_sel_hi:[1,0]
	v_pk_add_f32 v[156:157], v[148:149], v[148:149] op_sel_hi:[0,1]
	v_pk_mul_f32 v[148:149], v[218:219], v[218:219]
	v_pk_mul_f32 v[150:151], v[216:217], v[216:217]
	v_pk_mul_f32 v[154:155], v[66:67], v[144:145] op_sel_hi:[1,0]
	v_pk_mov_b32 v[152:153], v[150:151], v[148:149] op_sel:[1,0]
	v_mov_b32_e32 v151, v149
	v_pk_add_f32 v[148:149], v[152:153], v[150:151]
	v_pk_mul_f32 v[150:151], v[70:71], v[144:145] op_sel_hi:[1,0]
	v_pk_add_f32 v[160:161], v[148:149], v[148:149] op_sel_hi:[0,1]
	v_pk_mul_f32 v[148:149], v[68:69], v[144:145] op_sel_hi:[1,0]
	v_mul_f32_e32 v156, v154, v154
	v_mul_f32_e32 v152, v148, v148
	v_pk_fma_f32 v[162:163], v[148:149], v[148:149], v[152:153] op_sel_hi:[1,1,0]
	v_mul_f32_e32 v152, v150, v150
	v_pk_fma_f32 v[220:221], v[150:151], v[150:151], v[152:153] op_sel_hi:[1,1,0]
	v_pk_mul_f32 v[152:153], v[64:65], v[144:145] op_sel_hi:[1,0]
	v_mul_f32_e32 v160, v155, v155
	v_mul_f32_e32 v162, v152, v152
	v_mul_f32_e32 v220, v153, v153
	v_pk_add_f32 v[144:145], v[162:163], v[220:221]
	v_pk_add_f32 v[156:157], v[156:157], v[160:161]
	s_nop 0
	v_pk_add_f32 v[144:145], v[144:145], v[156:157]
	s_nop 0
	v_add_f32_e32 v144, v144, v145
	ds_bpermute_b32 v145, v243, v144
	s_waitcnt lgkmcnt(0)
	v_add_f32_e32 v144, v144, v145
	ds_bpermute_b32 v145, v242, v144
	s_waitcnt lgkmcnt(0)
	v_add_f32_e32 v144, v144, v145
	v_fmamk_f32 v144, v144, 0x3c800000, v241
	v_rsq_f32_e32 v156, v144
	s_nop 0
	v_mov_b32_e32 v157, v156
	v_pk_mul_f32 v[144:145], v[158:159], v[156:157] op_sel_hi:[1,0]
	v_pk_mul_f32 v[146:147], v[146:147], v[156:157] op_sel_hi:[1,0]
	v_pk_mul_f32 v[160:161], v[210:211], v[144:145]
	v_pk_mul_f32 v[158:159], v[212:213], v[146:147]
	ds_bpermute_b32 v144, v243, v160
	ds_bpermute_b32 v145, v243, v161
	ds_bpermute_b32 v220, v243, v158
	ds_bpermute_b32 v221, v243, v159
	v_mov_b32_e32 v162, v156
	v_mov_b32_e32 v163, v156
	s_and_saveexec_b64 s[4:5], vcc
	s_xor_b64 s[4:5], exec, s[4:5]
	s_cbranch_execz .LBB0_187
	v_cmp_eq_u32_e32 vcc, 1, v203
	s_and_saveexec_b64 s[34:35], vcc
	s_cbranch_execz .LBB0_186
	v_pk_mul_f32 v[142:143], v[142:143], v[158:159]
	v_pk_mul_f32 v[140:141], v[140:141], v[160:161]
	s_waitcnt lgkmcnt(0)
	v_pk_fma_f32 v[158:159], v[138:139], v[220:221], v[142:143]
	v_pk_fma_f32 v[160:161], v[136:137], v[144:145], v[140:141]

; __device__ __forceinline__ unsigned cvt_pk_bf16(float lo, float hi) { unsigned r; asm volatile("v_cvt_pk_bf16_f32 %0, %1, %2" : "=v"(r) : "v"(lo), "v"(hi)); return r; }
;     __device__ __forceinline__ void operator()(const f32x4 (&acc)[2][2][4][2], const Unit& u, int wr, int wc, int fr, int fq) const {
;     ...
;             f32x4 rc[4][2], rsn[4][2];
; #pragma unroll
;             for (int m = 2 * (aim & 1); m < 2 * (aim & 1) + 2; ++m)
; #pragma unroll
;                 for (int n = 0; n < 2; ++n) { const int pos = (row0 + ai * HALF + m * 16) & 8191; rc[m][n] = *(const f32x4*)(ropeC + pos * 8 + 4 * n); rsn[m][n] = *(const f32x4*)(ropeS + pos * 8 + 4 * n); }
;             asm volatile("" ::: "memory");
; #pragma unroll
;             for (int m = 2 * (aim & 1); m < 2 * (aim & 1) + 2; ++m) {
;                 const int row = row0 + ai * HALF + m * 16; const float rs = tb[ai * 64 + m * 16 + fr];
;                 f32x4 v[2][2]; float ss = 0.f;
; #pragma unroll
;                 for (int bj = 0; bj < 2; ++bj)
; #pragma unroll
;                     for (int n = 0; n < 2; ++n) { v[bj][n] = acc[ai][bj][m][n] * rs; const f32x4 t = v[bj][n]; ss += (t[0] * t[0] + t[1] * t[1]) + (t[2] * t[2] + t[3] * t[3]); }
;                 ss += __shfl_xor(ss, 16); ss += __shfl_xor(ss, 32);
;                 const float hr = __builtin_amdgcn_rsqf(ss * (1.0f / 64.0f) + 1e-6f);
; #pragma unroll
;                 for (int bj = 0; bj < 2; ++bj)
; #pragma unroll
;                     for (int n = 0; n < 2; ++n) v[bj][n] = v[bj][n] * hr * gv[bj][n];
; #pragma unroll
;                 for (int n = 0; n < 2; ++n) {
;                     const f32x4 c = rc[m][n], s = rsn[m][n];
;                     f32x4 mine = v[0][n], other;
; #pragma unroll
;                     for (int e = 0; e < 4; ++e) other[e] = __shfl_xor(mine[e], 16);
;                     if (fq == 0) v[0][n] = mine * c - other * s;
;                     else if (fq == 1) v[0][n] = mine * c + other * s;
;                 }
;                 bf16_t* rowp = dst + (size_t)row * 1024 + head * 64 + 8 * fq;
; #pragma unroll
;                 for (int bj = 0; bj < 2; ++bj) { u32x4 w; w.x = cvt_pk_bf16(v[bj][0][0], v[bj][0][1]); w.y = cvt_pk_bf16(v[bj][0][2], v[bj][0][3]);
;                     w.z = cvt_pk_bf16(v[bj][1][0], v[bj][1][1]); w.w = cvt_pk_bf16(v[bj][1][2], v[bj][1][3]); *(u32x4*)(rowp + bj * 32) = w; }
.LBB0_195:
	s_or_b64 exec, exec, s[4:5]
	v_pk_mul_f32 v[128:129], v[150:151], v[162:163]
	v_pk_mul_f32 v[130:131], v[148:149], v[156:157]
	v_pk_mul_f32 v[132:133], v[172:173], v[128:129]
	v_pk_mul_f32 v[128:129], v[154:155], v[162:163]
	v_pk_mul_f32 v[134:135], v[168:169], v[130:131]
	v_pk_mul_f32 v[136:137], v[170:171], v[128:129]
	v_or_b32_e32 v128, 48, v208
	v_ashrrev_i32_e32 v129, 31, v128
	v_lshlrev_b64 v[128:129], 11, v[128:129]
	v_pk_mul_f32 v[130:131], v[152:153], v[156:157]
	s_waitcnt lgkmcnt(0)
	v_lshl_add_u64 v[144:145], v[214:215], 0, v[128:129]
	v_cvt_pk_bf16_f32 v128, v160, v161
	v_pk_mul_f32 v[138:139], v[174:175], v[130:131]
	v_cvt_pk_bf16_f32 v129, v158, v159
	v_cvt_pk_bf16_f32 v130, v142, v143
	v_cvt_pk_bf16_f32 v131, v140, v141
	flat_store_dwordx4 v[144:145], v[128:131] sc1
	v_cmp_lt_i32_e32 vcc, 0, v203
	s_nop 0
	v_cvt_pk_bf16_f32 v128, v134, v135
	v_cvt_pk_bf16_f32 v129, v132, v133
	v_cvt_pk_bf16_f32 v130, v138, v139
	v_cvt_pk_bf16_f32 v131, v136, v137
	flat_store_dwordx4 v[144:145], v[128:131] offset:64 sc1
	s_nop 1
	v_add_u32_e32 v128, 0x400, v178
	v_and_b32_e32 v128, 0xfe78, v128
	v_lshlrev_b32_e32 v128, 2, v128
	v_mov_b32_e32 v129, v177
	v_lshl_add_u64 v[130:131], s[40:41], 0, v[128:129]
	v_lshl_add_u64 v[128:129], s[42:43], 0, v[128:129]
	flat_load_dwordx4 v[156:159], v[130:131]
	flat_load_dwordx4 v[144:147], v[130:131] offset:16
	flat_load_dwordx4 v[152:155], v[128:129]
	flat_load_dwordx4 v[148:151], v[128:129] offset:16
	v_add_u32_e32 v128, 0x480, v178
	v_and_b32_e32 v128, 0xfef8, v128
	v_lshlrev_b32_e32 v128, 2, v128
	v_mov_b32_e32 v129, v177
	v_lshl_add_u64 v[130:131], s[40:41], 0, v[128:129]
	v_lshl_add_u64 v[132:133], s[42:43], 0, v[128:129]
	flat_load_dwordx4 v[140:143], v[130:131]
	s_nop 0
	flat_load_dwordx4 v[128:131], v[130:131] offset:16
	s_nop 0
	flat_load_dwordx4 v[136:139], v[132:133]
	s_nop 0
	flat_load_dwordx4 v[132:135], v[132:133] offset:16
	ds_read_b32 v160, v250 offset:256
	s_waitcnt lgkmcnt(0)
	v_pk_mul_f32 v[162:163], v[62:63], v[160:161] op_sel_hi:[1,0]
	v_pk_mul_f32 v[226:227], v[60:61], v[160:161] op_sel_hi:[1,0]
	v_pk_mul_f32 v[216:217], v[162:163], v[162:163]
	v_pk_mul_f32 v[218:219], v[226:227], v[226:227]
	v_pk_mul_f32 v[234:235], v[58:59], v[160:161] op_sel_hi:[1,0]
	v_pk_mov_b32 v[220:221], v[218:219], v[216:217] op_sel:[1,0]
	v_mov_b32_e32 v219, v217
	v_pk_add_f32 v[216:217], v[220:221], v[218:219]
	v_pk_mul_f32 v[232:233], v[56:57], v[160:161] op_sel_hi:[1,0]
	v_pk_add_f32 v[224:225], v[216:217], v[216:217] op_sel_hi:[0,1]
	v_pk_mul_f32 v[216:217], v[234:235], v[234:235]
	v_pk_mul_f32 v[218:219], v[232:233], v[232:233]
	v_pk_mul_f32 v[222:223], v[46:47], v[160:161] op_sel_hi:[1,0]
	v_pk_mov_b32 v[220:221], v[218:219], v[216:217] op_sel:[1,0]
	v_mov_b32_e32 v219, v217
	v_pk_add_f32 v[216:217], v[220:221], v[218:219]
	v_pk_mul_f32 v[218:219], v[54:55], v[160:161] op_sel_hi:[1,0]
	v_pk_add_f32 v[228:229], v[216:217], v[216:217] op_sel_hi:[0,1]
	v_pk_mul_f32 v[216:217], v[52:53], v[160:161] op_sel_hi:[1,0]
	v_mul_f32_e32 v224, v222, v222
	v_mul_f32_e32 v220, v216, v216
	v_pk_fma_f32 v[230:231], v[216:217], v[216:217], v[220:221] op_sel_hi:[1,1,0]
	v_mul_f32_e32 v220, v218, v218
	v_pk_fma_f32 v[236:237], v[218:219], v[218:219], v[220:221] op_sel_hi:[1,1,0]
	v_pk_mul_f32 v[220:221], v[44:45], v[160:161] op_sel_hi:[1,0]
	v_mul_f32_e32 v228, v223, v223
	v_mul_f32_e32 v230, v220, v220
	v_mul_f32_e32 v236, v221, v221
	v_pk_add_f32 v[160:161], v[230:231], v[236:237]
	v_pk_add_f32 v[224:225], v[224:225], v[228:229]
	s_nop 0
	v_pk_add_f32 v[160:161], v[160:161], v[224:225]
	s_nop 0
	v_add_f32_e32 v160, v160, v161
	ds_bpermute_b32 v161, v243, v160
	s_waitcnt lgkmcnt(0)
	v_add_f32_e32 v160, v160, v161
	ds_bpermute_b32 v161, v242, v160
	s_waitcnt lgkmcnt(0)
	v_add_f32_e32 v160, v160, v161
	v_fmamk_f32 v160, v160, 0x3c800000, v241
	v_rsq_f32_e32 v224, v160
	s_nop 0
	v_mov_b32_e32 v225, v224
	v_pk_mul_f32 v[160:161], v[226:227], v[224:225] op_sel_hi:[1,0]
	v_pk_mul_f32 v[162:163], v[162:163], v[224:225] op_sel_hi:[1,0]
	v_pk_mul_f32 v[228:229], v[210:211], v[160:161]
	v_pk_mul_f32 v[226:227], v[212:213], v[162:163]
	ds_bpermute_b32 v160, v243, v228
	ds_bpermute_b32 v161, v243, v229
	ds_bpermute_b32 v236, v243, v226
	ds_bpermute_b32 v237, v243, v227
	v_mov_b32_e32 v230, v224
	v_mov_b32_e32 v231, v224
	s_and_saveexec_b64 s[4:5], vcc
	s_xor_b64 s[4:5], exec, s[4:5]
	s_cbranch_execz .LBB0_199
	v_cmp_eq_u32_e32 vcc, 1, v203
	s_and_saveexec_b64 s[34:35], vcc
	s_cbranch_execz .LBB0_198
	s_waitcnt vmcnt(0)
	v_pk_mul_f32 v[158:159], v[158:159], v[226:227]
	v_pk_mul_f32 v[156:157], v[156:157], v[228:229]
	s_waitcnt lgkmcnt(0)
	v_pk_fma_f32 v[226:227], v[154:155], v[236:237], v[158:159]
	v_pk_fma_f32 v[228:229], v[152:153], v[160:161], v[156:157]

; __device__ __forceinline__ unsigned cvt_pk_bf16(float lo, float hi) { unsigned r; asm volatile("v_cvt_pk_bf16_f32 %0, %1, %2" : "=v"(r) : "v"(lo), "v"(hi)); return r; }
;     __device__ __forceinline__ void operator()(const f32x4 (&acc)[2][2][4][2], const Unit& u, int wr, int wc, int fr, int fq) const {
;     ...
;                 const int row = row0 + ai * HALF + m * 16; const float rs = tb[ai * 64 + m * 16 + fr];
;                 f32x4 v[2][2]; float ss = 0.f;
; #pragma unroll
;                 for (int bj = 0; bj < 2; ++bj)
; #pragma unroll
;                     for (int n = 0; n < 2; ++n) { v[bj][n] = acc[ai][bj][m][n] * rs; const f32x4 t = v[bj][n]; ss += (t[0] * t[0] + t[1] * t[1]) + (t[2] * t[2] + t[3] * t[3]); }
;                 ss += __shfl_xor(ss, 16); ss += __shfl_xor(ss, 32);
;                 const float hr = __builtin_amdgcn_rsqf(ss * (1.0f / 64.0f) + 1e-6f);
; #pragma unroll
;                 for (int bj = 0; bj < 2; ++bj)
; #pragma unroll
;                     for (int n = 0; n < 2; ++n) v[bj][n] = v[bj][n] * hr * gv[bj][n];
; #pragma unroll
;                 for (int n = 0; n < 2; ++n) {
;                     const f32x4 c = rc[m][n], s = rsn[m][n];
;                     f32x4 mine = v[0][n], other;
; #pragma unroll
;                     for (int e = 0; e < 4; ++e) other[e] = __shfl_xor(mine[e], 16);
;                     if (fq == 0) v[0][n] = mine * c - other * s;
;                     else if (fq == 1) v[0][n] = mine * c + other * s;
;                 }
;                 bf16_t* rowp = dst + (size_t)row * 1024 + head * 64 + 8 * fq;
; #pragma unroll
;                 for (int bj = 0; bj < 2; ++bj) { u32x4 w; w.x = cvt_pk_bf16(v[bj][0][0], v[bj][0][1]); w.y = cvt_pk_bf16(v[bj][0][2], v[bj][0][3]);
;                     w.z = cvt_pk_bf16(v[bj][1][0], v[bj][1][1]); w.w = cvt_pk_bf16(v[bj][1][2], v[bj][1][3]); *(u32x4*)(rowp + bj * 32) = w; }
.LBB0_207:
	s_or_b64 exec, exec, s[4:5]
	v_pk_mul_f32 v[144:145], v[218:219], v[230:231]
	v_pk_mul_f32 v[146:147], v[216:217], v[224:225]
	v_pk_mul_f32 v[148:149], v[172:173], v[144:145]
	v_pk_mul_f32 v[144:145], v[222:223], v[230:231]
	v_pk_mul_f32 v[150:151], v[168:169], v[146:147]
	s_waitcnt lgkmcnt(2)
	v_pk_mul_f32 v[152:153], v[170:171], v[144:145]
	v_lshlrev_b64 v[144:145], 11, v[208:209]
	v_pk_mul_f32 v[146:147], v[220:221], v[224:225]
	s_waitcnt lgkmcnt(0)
	v_lshl_add_u64 v[160:161], v[214:215], 0, v[144:145]
	s_mov_b32 s4, 0x40000
	v_pk_mul_f32 v[154:155], v[174:175], v[146:147]
	v_cvt_pk_bf16_f32 v144, v228, v229
	v_cvt_pk_bf16_f32 v145, v226, v227
	v_cvt_pk_bf16_f32 v146, v158, v159
	v_cvt_pk_bf16_f32 v147, v156, v157
	v_add_co_u32_e32 v156, vcc, s4, v160
	v_lshl_add_u64 v[162:163], v[160:161], 0, s[18:19]
	s_nop 0
	v_addc_co_u32_e32 v157, vcc, 0, v161, vcc
	flat_store_dwordx4 v[156:157], v[144:147] sc1
	v_cmp_lt_i32_e32 vcc, 0, v203
	s_nop 0
	v_cvt_pk_bf16_f32 v144, v150, v151
	v_cvt_pk_bf16_f32 v145, v148, v149
	v_cvt_pk_bf16_f32 v146, v154, v155
	v_cvt_pk_bf16_f32 v147, v152, v153
	flat_store_dwordx4 v[162:163], v[144:147] offset:64 sc1
	ds_read_b32 v144, v250 offset:320
	s_waitcnt lgkmcnt(0)
	v_pk_mul_f32 v[158:159], v[48:49], v[144:145] op_sel_hi:[1,0]
	v_pk_mul_f32 v[146:147], v[50:51], v[144:145] op_sel_hi:[1,0]
	v_pk_mul_f32 v[150:151], v[158:159], v[158:159]
	v_pk_mul_f32 v[148:149], v[146:147], v[146:147]
	v_pk_mul_f32 v[218:219], v[42:43], v[144:145] op_sel_hi:[1,0]
	v_pk_mov_b32 v[152:153], v[150:151], v[148:149] op_sel:[1,0]
	v_mov_b32_e32 v151, v149
	v_pk_add_f32 v[148:149], v[152:153], v[150:151]
	v_pk_mul_f32 v[216:217], v[40:41], v[144:145] op_sel_hi:[1,0]
	v_pk_add_f32 v[156:157], v[148:149], v[148:149] op_sel_hi:[0,1]
	v_pk_mul_f32 v[148:149], v[218:219], v[218:219]
	v_pk_mul_f32 v[150:151], v[216:217], v[216:217]
	v_pk_mul_f32 v[154:155], v[30:31], v[144:145] op_sel_hi:[1,0]
	v_pk_mov_b32 v[152:153], v[150:151], v[148:149] op_sel:[1,0]
	v_mov_b32_e32 v151, v149
	v_pk_add_f32 v[148:149], v[152:153], v[150:151]
	v_pk_mul_f32 v[150:151], v[38:39], v[144:145] op_sel_hi:[1,0]
	v_pk_add_f32 v[160:161], v[148:149], v[148:149] op_sel_hi:[0,1]
	v_pk_mul_f32 v[148:149], v[36:37], v[144:145] op_sel_hi:[1,0]
	v_mul_f32_e32 v156, v154, v154
	v_mul_f32_e32 v152, v148, v148
	v_pk_fma_f32 v[162:163], v[148:149], v[148:149], v[152:153] op_sel_hi:[1,1,0]
	v_mul_f32_e32 v152, v150, v150
	v_pk_fma_f32 v[220:221], v[150:151], v[150:151], v[152:153] op_sel_hi:[1,1,0]
	v_pk_mul_f32 v[152:153], v[28:29], v[144:145] op_sel_hi:[1,0]
	v_mul_f32_e32 v160, v155, v155
	v_mul_f32_e32 v162, v152, v152
	v_mul_f32_e32 v220, v153, v153
	v_pk_add_f32 v[144:145], v[162:163], v[220:221]
	v_pk_add_f32 v[156:157], v[156:157], v[160:161]
	s_nop 0
	v_pk_add_f32 v[144:145], v[144:145], v[156:157]
	s_nop 0
	v_add_f32_e32 v144, v144, v145
	ds_bpermute_b32 v145, v243, v144
	s_waitcnt lgkmcnt(0)
	v_add_f32_e32 v144, v144, v145
	ds_bpermute_b32 v145, v242, v144
	s_waitcnt lgkmcnt(0)
	v_add_f32_e32 v144, v144, v145
	v_fmamk_f32 v144, v144, 0x3c800000, v241
	v_rsq_f32_e32 v156, v144
	s_nop 0
	v_mov_b32_e32 v157, v156
	v_pk_mul_f32 v[144:145], v[158:159], v[156:157] op_sel_hi:[1,0]
	v_pk_mul_f32 v[146:147], v[146:147], v[156:157] op_sel_hi:[1,0]
	v_pk_mul_f32 v[160:161], v[210:211], v[144:145]
	v_pk_mul_f32 v[158:159], v[212:213], v[146:147]
	ds_bpermute_b32 v144, v243, v160
	ds_bpermute_b32 v145, v243, v161
	ds_bpermute_b32 v220, v243, v158
	ds_bpermute_b32 v221, v243, v159
	v_mov_b32_e32 v162, v156
	v_mov_b32_e32 v163, v156
	s_and_saveexec_b64 s[4:5], vcc
	s_xor_b64 s[4:5], exec, s[4:5]
	s_cbranch_execz .LBB0_211
	v_cmp_eq_u32_e32 vcc, 1, v203
	s_and_saveexec_b64 s[34:35], vcc
	s_cbranch_execz .LBB0_210
	v_pk_mul_f32 v[142:143], v[142:143], v[158:159]
	v_pk_mul_f32 v[140:141], v[140:141], v[160:161]
	s_waitcnt lgkmcnt(0)
	v_pk_fma_f32 v[158:159], v[138:139], v[220:221], v[142:143]
	v_pk_fma_f32 v[160:161], v[136:137], v[144:145], v[140:141]

; __device__ __forceinline__ unsigned cvt_pk_bf16(float lo, float hi) { unsigned r; asm volatile("v_cvt_pk_bf16_f32 %0, %1, %2" : "=v"(r) : "v"(lo), "v"(hi)); return r; }
;     __device__ __forceinline__ void operator()(const f32x4 (&acc)[2][2][4][2], const Unit& u, int wr, int wc, int fr, int fq) const {
;     ...
;             f32x4 rc[4][2], rsn[4][2];
; #pragma unroll
;             for (int m = 2 * (aim & 1); m < 2 * (aim & 1) + 2; ++m)
; #pragma unroll
;                 for (int n = 0; n < 2; ++n) { const int pos = (row0 + ai * HALF + m * 16) & 8191; rc[m][n] = *(const f32x4*)(ropeC + pos * 8 + 4 * n); rsn[m][n] = *(const f32x4*)(ropeS + pos * 8 + 4 * n); }
;             asm volatile("" ::: "memory");
; #pragma unroll
;             for (int m = 2 * (aim & 1); m < 2 * (aim & 1) + 2; ++m) {
;                 const int row = row0 + ai * HALF + m * 16; const float rs = tb[ai * 64 + m * 16 + fr];
;                 f32x4 v[2][2]; float ss = 0.f;
; #pragma unroll
;                 for (int bj = 0; bj < 2; ++bj)
; #pragma unroll
;                     for (int n = 0; n < 2; ++n) { v[bj][n] = acc[ai][bj][m][n] * rs; const f32x4 t = v[bj][n]; ss += (t[0] * t[0] + t[1] * t[1]) + (t[2] * t[2] + t[3] * t[3]); }
;                 ss += __shfl_xor(ss, 16); ss += __shfl_xor(ss, 32);
;                 const float hr = __builtin_amdgcn_rsqf(ss * (1.0f / 64.0f) + 1e-6f);
; #pragma unroll
;                 for (int bj = 0; bj < 2; ++bj)
; #pragma unroll
;                     for (int n = 0; n < 2; ++n) v[bj][n] = v[bj][n] * hr * gv[bj][n];
; #pragma unroll
;                 for (int n = 0; n < 2; ++n) {
;                     const f32x4 c = rc[m][n], s = rsn[m][n];
;                     f32x4 mine = v[0][n], other;
; #pragma unroll
;                     for (int e = 0; e < 4; ++e) other[e] = __shfl_xor(mine[e], 16);
;                     if (fq == 0) v[0][n] = mine * c - other * s;
;                     else if (fq == 1) v[0][n] = mine * c + other * s;
;                 }
;                 bf16_t* rowp = dst + (size_t)row * 1024 + head * 64 + 8 * fq;
; #pragma unroll
;                 for (int bj = 0; bj < 2; ++bj) { u32x4 w; w.x = cvt_pk_bf16(v[bj][0][0], v[bj][0][1]); w.y = cvt_pk_bf16(v[bj][0][2], v[bj][0][3]);
;                     w.z = cvt_pk_bf16(v[bj][1][0], v[bj][1][1]); w.w = cvt_pk_bf16(v[bj][1][2], v[bj][1][3]); *(u32x4*)(rowp + bj * 32) = w; }
.LBB0_219:
	s_or_b64 exec, exec, s[4:5]
	v_pk_mul_f32 v[128:129], v[150:151], v[162:163]
	v_pk_mul_f32 v[130:131], v[148:149], v[156:157]
	v_pk_mul_f32 v[132:133], v[172:173], v[128:129]
	v_pk_mul_f32 v[128:129], v[154:155], v[162:163]
	s_mov_b64 s[4:5], 0x48000
	v_pk_mul_f32 v[136:137], v[170:171], v[128:129]
	v_lshlrev_b64 v[128:129], 11, v[208:209]
	s_waitcnt lgkmcnt(0)
	v_lshl_add_u64 v[144:145], v[214:215], 0, v[128:129]
	v_pk_mul_f32 v[134:135], v[168:169], v[130:131]
	v_pk_mul_f32 v[130:131], v[152:153], v[156:157]
	v_lshl_add_u64 v[146:147], v[144:145], 0, s[4:5]
	s_mov_b32 s4, 0x48000
	v_pk_mul_f32 v[138:139], v[174:175], v[130:131]
	v_cvt_pk_bf16_f32 v128, v160, v161
	v_cvt_pk_bf16_f32 v129, v158, v159
	v_cvt_pk_bf16_f32 v130, v142, v143
	v_cvt_pk_bf16_f32 v131, v140, v141
	v_add_co_u32_e32 v140, vcc, s4, v144
	s_nop 1
	v_addc_co_u32_e32 v141, vcc, 0, v145, vcc
	flat_store_dwordx4 v[140:141], v[128:131] sc1
	v_cmp_lt_i32_e32 vcc, 0, v203
	s_nop 0
	v_cvt_pk_bf16_f32 v128, v134, v135
	v_cvt_pk_bf16_f32 v129, v132, v133
	v_cvt_pk_bf16_f32 v130, v138, v139
	v_cvt_pk_bf16_f32 v131, v136, v137
	flat_store_dwordx4 v[146:147], v[128:131] offset:64 sc1
	s_nop 1
	v_add_u32_e32 v128, 0x500, v178
	v_and_b32_e32 v128, 0xff78, v128
	v_lshlrev_b32_e32 v128, 2, v128
	v_mov_b32_e32 v129, v177
	v_lshl_add_u64 v[130:131], s[40:41], 0, v[128:129]
	v_lshl_add_u64 v[128:129], s[42:43], 0, v[128:129]
	flat_load_dwordx4 v[156:159], v[130:131]
	flat_load_dwordx4 v[144:147], v[130:131] offset:16
	flat_load_dwordx4 v[152:155], v[128:129]
	flat_load_dwordx4 v[148:151], v[128:129] offset:16
	v_add_u32_e32 v128, 0x580, v178
	v_and_b32_e32 v128, 0xfff8, v128
	v_lshlrev_b32_e32 v128, 2, v128
	v_mov_b32_e32 v129, v177
	v_lshl_add_u64 v[130:131], s[40:41], 0, v[128:129]
	v_lshl_add_u64 v[132:133], s[42:43], 0, v[128:129]
	flat_load_dwordx4 v[140:143], v[130:131]
	s_nop 0
	flat_load_dwordx4 v[128:131], v[130:131] offset:16
	s_nop 0
	flat_load_dwordx4 v[136:139], v[132:133]
	s_nop 0
	flat_load_dwordx4 v[132:135], v[132:133] offset:16
	ds_read_b32 v160, v250 offset:384
	s_waitcnt lgkmcnt(0)
	v_pk_mul_f32 v[162:163], v[34:35], v[160:161] op_sel_hi:[1,0]
	v_pk_mul_f32 v[178:179], v[32:33], v[160:161] op_sel_hi:[1,0]
	v_pk_mul_f32 v[216:217], v[162:163], v[162:163]
	v_pk_mul_f32 v[218:219], v[178:179], v[178:179]
	v_pk_mul_f32 v[234:235], v[26:27], v[160:161] op_sel_hi:[1,0]
	v_pk_mov_b32 v[220:221], v[218:219], v[216:217] op_sel:[1,0]
	v_mov_b32_e32 v219, v217
	v_pk_add_f32 v[216:217], v[220:221], v[218:219]
	v_pk_mul_f32 v[232:233], v[24:25], v[160:161] op_sel_hi:[1,0]
	v_pk_add_f32 v[224:225], v[216:217], v[216:217] op_sel_hi:[0,1]
	v_pk_mul_f32 v[216:217], v[234:235], v[234:235]
	v_pk_mul_f32 v[218:219], v[232:233], v[232:233]
	v_pk_mul_f32 v[222:223], v[14:15], v[160:161] op_sel_hi:[1,0]
	v_pk_mov_b32 v[220:221], v[218:219], v[216:217] op_sel:[1,0]
	v_mov_b32_e32 v219, v217
	v_pk_add_f32 v[216:217], v[220:221], v[218:219]
	v_pk_mul_f32 v[218:219], v[22:23], v[160:161] op_sel_hi:[1,0]
	v_pk_add_f32 v[226:227], v[216:217], v[216:217] op_sel_hi:[0,1]
	v_pk_mul_f32 v[216:217], v[20:21], v[160:161] op_sel_hi:[1,0]
	v_mul_f32_e32 v224, v222, v222
	v_mul_f32_e32 v220, v216, v216
	v_pk_fma_f32 v[228:229], v[216:217], v[216:217], v[220:221] op_sel_hi:[1,1,0]
	v_mul_f32_e32 v220, v218, v218
	v_pk_fma_f32 v[230:231], v[218:219], v[218:219], v[220:221] op_sel_hi:[1,1,0]
	v_pk_mul_f32 v[220:221], v[12:13], v[160:161] op_sel_hi:[1,0]
	v_mul_f32_e32 v226, v223, v223
	v_mul_f32_e32 v228, v220, v220
	v_mul_f32_e32 v230, v221, v221
	v_pk_add_f32 v[160:161], v[228:229], v[230:231]
	v_pk_add_f32 v[224:225], v[224:225], v[226:227]
	s_nop 0
	v_pk_add_f32 v[160:161], v[160:161], v[224:225]
	s_nop 0
	v_add_f32_e32 v160, v160, v161
	ds_bpermute_b32 v161, v243, v160
	s_waitcnt lgkmcnt(0)
	v_add_f32_e32 v160, v160, v161
	ds_bpermute_b32 v161, v242, v160
	s_waitcnt lgkmcnt(0)
	v_add_f32_e32 v160, v160, v161
	v_fmamk_f32 v160, v160, 0x3c800000, v241
	v_rsq_f32_e32 v224, v160
	s_nop 0
	v_mov_b32_e32 v225, v224
	v_pk_mul_f32 v[160:161], v[178:179], v[224:225] op_sel_hi:[1,0]
	v_pk_mul_f32 v[162:163], v[162:163], v[224:225] op_sel_hi:[1,0]
	v_pk_mul_f32 v[228:229], v[210:211], v[160:161]
	v_pk_mul_f32 v[226:227], v[212:213], v[162:163]
	ds_bpermute_b32 v160, v243, v228
	ds_bpermute_b32 v161, v243, v229
	ds_bpermute_b32 v236, v243, v226
	ds_bpermute_b32 v237, v243, v227
	v_mov_b32_e32 v230, v224
	v_mov_b32_e32 v231, v224
	s_and_saveexec_b64 s[4:5], vcc
	s_xor_b64 s[4:5], exec, s[4:5]
	s_cbranch_execz .LBB0_223
	v_cmp_eq_u32_e32 vcc, 1, v203
	s_and_saveexec_b64 s[34:35], vcc
	s_cbranch_execz .LBB0_222
	s_waitcnt vmcnt(0)
	v_pk_mul_f32 v[158:159], v[158:159], v[226:227]
	v_pk_mul_f32 v[156:157], v[156:157], v[228:229]
	s_waitcnt lgkmcnt(0)
	v_pk_fma_f32 v[226:227], v[154:155], v[236:237], v[158:159]
	v_pk_fma_f32 v[228:229], v[152:153], v[160:161], v[156:157]

; __device__ __forceinline__ unsigned cvt_pk_bf16(float lo, float hi) { unsigned r; asm volatile("v_cvt_pk_bf16_f32 %0, %1, %2" : "=v"(r) : "v"(lo), "v"(hi)); return r; }
;     __device__ __forceinline__ void operator()(const f32x4 (&acc)[2][2][4][2], const Unit& u, int wr, int wc, int fr, int fq) const {
;     ...
;                 const int row = row0 + ai * HALF + m * 16; const float rs = tb[ai * 64 + m * 16 + fr];
;                 f32x4 v[2][2]; float ss = 0.f;
; #pragma unroll
;                 for (int bj = 0; bj < 2; ++bj)
; #pragma unroll
;                     for (int n = 0; n < 2; ++n) { v[bj][n] = acc[ai][bj][m][n] * rs; const f32x4 t = v[bj][n]; ss += (t[0] * t[0] + t[1] * t[1]) + (t[2] * t[2] + t[3] * t[3]); }
;                 ss += __shfl_xor(ss, 16); ss += __shfl_xor(ss, 32);
;                 const float hr = __builtin_amdgcn_rsqf(ss * (1.0f / 64.0f) + 1e-6f);
; #pragma unroll
;                 for (int bj = 0; bj < 2; ++bj)
; #pragma unroll
;                     for (int n = 0; n < 2; ++n) v[bj][n] = v[bj][n] * hr * gv[bj][n];
; #pragma unroll
;                 for (int n = 0; n < 2; ++n) {
;                     const f32x4 c = rc[m][n], s = rsn[m][n];
;                     f32x4 mine = v[0][n], other;
; #pragma unroll
;                     for (int e = 0; e < 4; ++e) other[e] = __shfl_xor(mine[e], 16);
;                     if (fq == 0) v[0][n] = mine * c - other * s;
;                     else if (fq == 1) v[0][n] = mine * c + other * s;
;                 }
;                 bf16_t* rowp = dst + (size_t)row * 1024 + head * 64 + 8 * fq;
; #pragma unroll
;                 for (int bj = 0; bj < 2; ++bj) { u32x4 w; w.x = cvt_pk_bf16(v[bj][0][0], v[bj][0][1]); w.y = cvt_pk_bf16(v[bj][0][2], v[bj][0][3]);
;                     w.z = cvt_pk_bf16(v[bj][1][0], v[bj][1][1]); w.w = cvt_pk_bf16(v[bj][1][2], v[bj][1][3]); *(u32x4*)(rowp + bj * 32) = w; }
.LBB0_231:
	s_or_b64 exec, exec, s[4:5]
	v_pk_mul_f32 v[144:145], v[218:219], v[230:231]
	v_pk_mul_f32 v[146:147], v[216:217], v[224:225]
	v_pk_mul_f32 v[148:149], v[172:173], v[144:145]
	v_pk_mul_f32 v[144:145], v[222:223], v[230:231]
	s_mov_b64 s[4:5], 0x50000
	s_waitcnt lgkmcnt(2)
	v_pk_mul_f32 v[152:153], v[170:171], v[144:145]
	v_lshlrev_b64 v[144:145], 11, v[208:209]
	s_waitcnt lgkmcnt(0)
	v_lshl_add_u64 v[160:161], v[214:215], 0, v[144:145]
	v_pk_mul_f32 v[150:151], v[168:169], v[146:147]
	v_pk_mul_f32 v[146:147], v[220:221], v[224:225]
	v_lshl_add_u64 v[162:163], v[160:161], 0, s[4:5]
	s_mov_b32 s4, 0x50000
	v_pk_mul_f32 v[154:155], v[174:175], v[146:147]
	v_cvt_pk_bf16_f32 v144, v228, v229
	v_cvt_pk_bf16_f32 v145, v226, v227
	v_cvt_pk_bf16_f32 v146, v158, v159
	v_cvt_pk_bf16_f32 v147, v156, v157
	v_add_co_u32_e32 v156, vcc, s4, v160
	s_nop 1
	v_addc_co_u32_e32 v157, vcc, 0, v161, vcc
	flat_store_dwordx4 v[156:157], v[144:147] sc1
	v_cmp_lt_i32_e32 vcc, 0, v203
	s_nop 0
	v_cvt_pk_bf16_f32 v144, v150, v151
	v_cvt_pk_bf16_f32 v145, v148, v149
	v_cvt_pk_bf16_f32 v146, v154, v155
	v_cvt_pk_bf16_f32 v147, v152, v153
	flat_store_dwordx4 v[162:163], v[144:147] offset:64 sc1
	ds_read_b32 v144, v250 offset:448
	s_waitcnt lgkmcnt(0)
	v_pk_mul_f32 v[158:159], v[16:17], v[144:145] op_sel_hi:[1,0]
	v_pk_mul_f32 v[146:147], v[18:19], v[144:145] op_sel_hi:[1,0]
	v_pk_mul_f32 v[150:151], v[158:159], v[158:159]
	v_pk_mul_f32 v[148:149], v[146:147], v[146:147]
	v_pk_mul_f32 v[218:219], v[10:11], v[144:145] op_sel_hi:[1,0]
	v_pk_mov_b32 v[152:153], v[150:151], v[148:149] op_sel:[1,0]
	v_mov_b32_e32 v151, v149
	v_pk_add_f32 v[148:149], v[152:153], v[150:151]
	v_pk_mul_f32 v[216:217], v[8:9], v[144:145] op_sel_hi:[1,0]
	v_pk_add_f32 v[156:157], v[148:149], v[148:149] op_sel_hi:[0,1]
	v_pk_mul_f32 v[148:149], v[218:219], v[218:219]
	v_pk_mul_f32 v[150:151], v[216:217], v[216:217]
	v_pk_mul_f32 v[154:155], v[2:3], v[144:145] op_sel_hi:[1,0]
	v_pk_mov_b32 v[152:153], v[150:151], v[148:149] op_sel:[1,0]
	v_mov_b32_e32 v151, v149
	v_pk_add_f32 v[148:149], v[152:153], v[150:151]
	v_pk_mul_f32 v[150:151], v[6:7], v[144:145] op_sel_hi:[1,0]
	v_pk_add_f32 v[160:161], v[148:149], v[148:149] op_sel_hi:[0,1]
	v_pk_mul_f32 v[148:149], v[4:5], v[144:145] op_sel_hi:[1,0]
	v_mul_f32_e32 v156, v154, v154
	v_mul_f32_e32 v152, v148, v148
	v_pk_fma_f32 v[162:163], v[148:149], v[148:149], v[152:153] op_sel_hi:[1,1,0]
	v_mul_f32_e32 v152, v150, v150
	v_pk_fma_f32 v[178:179], v[150:151], v[150:151], v[152:153] op_sel_hi:[1,1,0]
	v_pk_mul_f32 v[152:153], v[0:1], v[144:145] op_sel_hi:[1,0]
	v_mul_f32_e32 v160, v155, v155
	v_mul_f32_e32 v162, v152, v152
	v_mul_f32_e32 v178, v153, v153
	v_pk_add_f32 v[144:145], v[162:163], v[178:179]
	v_pk_add_f32 v[156:157], v[156:157], v[160:161]
	s_nop 0
	v_pk_add_f32 v[144:145], v[144:145], v[156:157]
	s_nop 0
	v_add_f32_e32 v144, v144, v145
	ds_bpermute_b32 v145, v243, v144
	s_waitcnt lgkmcnt(0)
	v_add_f32_e32 v144, v144, v145
	ds_bpermute_b32 v145, v242, v144
	s_waitcnt lgkmcnt(0)
	v_add_f32_e32 v144, v144, v145
	v_fmamk_f32 v144, v144, 0x3c800000, v241
	v_rsq_f32_e32 v156, v144
	s_nop 0
	v_mov_b32_e32 v157, v156
	v_pk_mul_f32 v[144:145], v[158:159], v[156:157] op_sel_hi:[1,0]
	v_pk_mul_f32 v[146:147], v[146:147], v[156:157] op_sel_hi:[1,0]
	v_pk_mul_f32 v[160:161], v[210:211], v[144:145]
	v_pk_mul_f32 v[158:159], v[212:213], v[146:147]
	ds_bpermute_b32 v144, v243, v160
	ds_bpermute_b32 v145, v243, v161
	ds_bpermute_b32 v210, v243, v158
	ds_bpermute_b32 v211, v243, v159
	v_mov_b32_e32 v162, v156
	v_mov_b32_e32 v163, v156
	s_and_saveexec_b64 s[4:5], vcc
	s_xor_b64 s[4:5], exec, s[4:5]
	s_cbranch_execz .LBB0_235
	v_cmp_eq_u32_e32 vcc, 1, v203
	s_and_saveexec_b64 s[34:35], vcc
	s_cbranch_execz .LBB0_234
	v_pk_mul_f32 v[142:143], v[142:143], v[158:159]
	v_pk_mul_f32 v[140:141], v[140:141], v[160:161]
	s_waitcnt lgkmcnt(0)
	v_pk_fma_f32 v[158:159], v[138:139], v[210:211], v[142:143]
	v_pk_fma_f32 v[160:161], v[136:137], v[144:145], v[140:141]

; __device__ __forceinline__ unsigned cvt_pk_bf16(float lo, float hi) { unsigned r; asm volatile("v_cvt_pk_bf16_f32 %0, %1, %2" : "=v"(r) : "v"(lo), "v"(hi)); return r; }
;     __device__ __forceinline__ void operator()(const f32x4 (&acc)[2][2][4][2], const Unit& u, int wr, int wc, int fr, int fq) const {
;     ...
;                 bf16_t* rowp = dst + (size_t)row * 1024 + head * 64 + 8 * fq;
; #pragma unroll
;                 for (int bj = 0; bj < 2; ++bj) { u32x4 w; w.x = cvt_pk_bf16(v[bj][0][0], v[bj][0][1]); w.y = cvt_pk_bf16(v[bj][0][2], v[bj][0][3]);
;                     w.z = cvt_pk_bf16(v[bj][1][0], v[bj][1][1]); w.w = cvt_pk_bf16(v[bj][1][2], v[bj][1][3]); *(u32x4*)(rowp + bj * 32) = w; }
.LBB0_243:
	s_or_b64 exec, exec, s[4:5]
	v_pk_mul_f32 v[128:129], v[150:151], v[162:163]
	v_pk_mul_f32 v[130:131], v[148:149], v[156:157]
	v_pk_mul_f32 v[132:133], v[172:173], v[128:129]
	v_pk_mul_f32 v[128:129], v[154:155], v[162:163]
	s_mov_b64 s[4:5], 0x58000
	v_pk_mul_f32 v[136:137], v[170:171], v[128:129]
	v_lshlrev_b64 v[128:129], 11, v[208:209]
	s_waitcnt lgkmcnt(0)
	v_lshl_add_u64 v[144:145], v[214:215], 0, v[128:129]
	v_pk_mul_f32 v[134:135], v[168:169], v[130:131]
	v_pk_mul_f32 v[130:131], v[152:153], v[156:157]
	v_lshl_add_u64 v[146:147], v[144:145], 0, s[4:5]
	s_mov_b32 s4, 0x58000
	v_pk_mul_f32 v[138:139], v[174:175], v[130:131]
	v_cvt_pk_bf16_f32 v128, v160, v161
	v_cvt_pk_bf16_f32 v129, v158, v159
	v_cvt_pk_bf16_f32 v130, v142, v143
	v_cvt_pk_bf16_f32 v131, v140, v141
	v_add_co_u32_e32 v140, vcc, s4, v144
	s_nop 1
	v_addc_co_u32_e32 v141, vcc, 0, v145, vcc
	flat_store_dwordx4 v[140:141], v[128:131] sc1
	s_nop 1
	v_cvt_pk_bf16_f32 v128, v134, v135
	v_cvt_pk_bf16_f32 v129, v132, v133
	v_cvt_pk_bf16_f32 v130, v138, v139
	v_cvt_pk_bf16_f32 v131, v136, v137
	flat_store_dwordx4 v[146:147], v[128:131] offset:64 sc1

; __device__ __forceinline__ unsigned cvt_pk_bf16(float lo, float hi) { unsigned r; asm volatile("v_cvt_pk_bf16_f32 %0, %1, %2" : "=v"(r) : "v"(lo), "v"(hi)); return r; }
;     __device__ __forceinline__ void operator()(const f32x4 (&acc)[2][2][4][2], const Unit& u, int wr, int wc, int fr, int fq) const {
;     ...
;         if (u.pn >= 8) {
; #pragma unroll
;             for (int ai = 0; ai < 2; ++ai)
; #pragma unroll
;                 for (int m = 0; m < 4; ++m) {
;                     const int row = row0 + ai * HALF + m * 16; const float rs = tb[ai * 64 + m * 16 + fr];
;                     bf16_t* rowp = V + (size_t)row * 1024 + (u.pn - 8) * BM + wc * 32 + 8 * fq;
; #pragma unroll
;                     for (int bj = 0; bj < 2; ++bj) { const f32x4 v0 = acc[ai][bj][m][0] * rs, v1 = acc[ai][bj][m][1] * rs; u32x4 w;
;                         w.x = cvt_pk_bf16(v0[0], v0[1]); w.y = cvt_pk_bf16(v0[2], v0[3]); w.z = cvt_pk_bf16(v1[0], v1[1]); w.w = cvt_pk_bf16(v1[2], v1[3]);
;                         *(u32x4*)(rowp + bj * HALF) = w; }
;                 }
;             return;
.LBB0_245:
	s_and_b64 vcc, exec, s[4:5]
	s_cbranch_vccz .LBB0_244
	s_lshl_b32 s4, s29, 8
	s_addk_i32 s4, 0xf800
	ds_read_b32 v130, v250
	v_ashrrev_i32_e32 v209, 31, v208
	s_ashr_i32 s5, s4, 31
	v_lshlrev_b64 v[128:129], 11, v[208:209]
	v_lshl_add_u64 v[128:129], s[26:27], 0, v[128:129]
	s_lshl_b64 s[4:5], s[4:5], 1
	v_readlane_b32 s14, v254, 24
	v_lshl_add_u64 v[128:129], v[128:129], 0, s[4:5]
	v_readlane_b32 s15, v254, 25
	v_lshlrev_b32_e32 v132, 1, v202
	v_mov_b32_e32 v133, v177
	v_lshl_add_u64 v[128:129], v[128:129], 0, s[14:15]
	v_lshl_add_u64 v[128:129], v[128:129], 0, v[132:133]
	s_waitcnt lgkmcnt(0)
	v_pk_mul_f32 v[126:127], v[126:127], v[130:131] op_sel_hi:[1,0]
	v_pk_mul_f32 v[124:125], v[124:125], v[130:131] op_sel_hi:[1,0]
	v_pk_mul_f32 v[134:135], v[122:123], v[130:131] op_sel_hi:[1,0]
	v_pk_mul_f32 v[122:123], v[120:121], v[130:131] op_sel_hi:[1,0]
	v_cvt_pk_bf16_f32 v120, v124, v125
	v_cvt_pk_bf16_f32 v121, v126, v127
	v_pk_mul_f32 v[116:117], v[116:117], v[130:131] op_sel_hi:[1,0]
	v_cvt_pk_bf16_f32 v122, v122, v123
	v_cvt_pk_bf16_f32 v123, v134, v135
	flat_store_dwordx4 v[128:129], v[120:123] sc1
	v_pk_mul_f32 v[118:119], v[118:119], v[130:131] op_sel_hi:[1,0]
	s_nop 0
	v_pk_mul_f32 v[120:121], v[114:115], v[130:131] op_sel_hi:[1,0]
	v_pk_mul_f32 v[114:115], v[112:113], v[130:131] op_sel_hi:[1,0]
	v_cvt_pk_bf16_f32 v112, v116, v117
	v_cvt_pk_bf16_f32 v113, v118, v119
	s_nop 0
	v_cvt_pk_bf16_f32 v114, v114, v115
	v_cvt_pk_bf16_f32 v115, v120, v121
	flat_store_dwordx4 v[128:129], v[112:115] offset:256 sc1
	ds_read_b32 v114, v250 offset:64
	s_waitcnt lgkmcnt(0)
	v_pk_mul_f32 v[110:111], v[110:111], v[114:115] op_sel_hi:[1,0]
	v_or_b32_e32 v112, 16, v208
	v_ashrrev_i32_e32 v113, 31, v112
	v_lshlrev_b64 v[112:113], 11, v[112:113]
	v_lshl_add_u64 v[112:113], s[26:27], 0, v[112:113]
	v_lshl_add_u64 v[112:113], v[112:113], 0, s[4:5]
	v_lshl_add_u64 v[112:113], v[112:113], 0, s[14:15]
	v_lshl_add_u64 v[112:113], v[112:113], 0, v[132:133]
	v_pk_mul_f32 v[108:109], v[108:109], v[114:115] op_sel_hi:[1,0]
	v_pk_mul_f32 v[116:117], v[106:107], v[114:115] op_sel_hi:[1,0]
	v_pk_mul_f32 v[106:107], v[104:105], v[114:115] op_sel_hi:[1,0]
	v_cvt_pk_bf16_f32 v104, v108, v109
	v_cvt_pk_bf16_f32 v105, v110, v111
	v_pk_mul_f32 v[100:101], v[100:101], v[114:115] op_sel_hi:[1,0]
	v_cvt_pk_bf16_f32 v106, v106, v107
	v_cvt_pk_bf16_f32 v107, v116, v117
	flat_store_dwordx4 v[112:113], v[104:107] sc1
	v_pk_mul_f32 v[102:103], v[102:103], v[114:115] op_sel_hi:[1,0]
	s_nop 0
	v_pk_mul_f32 v[104:105], v[98:99], v[114:115] op_sel_hi:[1,0]
	v_pk_mul_f32 v[98:99], v[96:97], v[114:115] op_sel_hi:[1,0]
	v_cvt_pk_bf16_f32 v96, v100, v101
	v_cvt_pk_bf16_f32 v97, v102, v103
	s_nop 0
	v_cvt_pk_bf16_f32 v98, v98, v99
	v_cvt_pk_bf16_f32 v99, v104, v105
	flat_store_dwordx4 v[112:113], v[96:99] offset:256 sc1
	ds_read_b32 v98, v250 offset:128
	s_waitcnt lgkmcnt(0)
	v_pk_mul_f32 v[94:95], v[94:95], v[98:99] op_sel_hi:[1,0]
	v_or_b32_e32 v96, 32, v208
	v_ashrrev_i32_e32 v97, 31, v96
	v_lshlrev_b64 v[96:97], 11, v[96:97]
	v_lshl_add_u64 v[96:97], s[26:27], 0, v[96:97]
	v_lshl_add_u64 v[96:97], v[96:97], 0, s[4:5]
	v_lshl_add_u64 v[96:97], v[96:97], 0, s[14:15]
	v_lshl_add_u64 v[96:97], v[96:97], 0, v[132:133]
	v_pk_mul_f32 v[92:93], v[92:93], v[98:99] op_sel_hi:[1,0]
	v_pk_mul_f32 v[100:101], v[90:91], v[98:99] op_sel_hi:[1,0]
	v_pk_mul_f32 v[90:91], v[88:89], v[98:99] op_sel_hi:[1,0]
	v_cvt_pk_bf16_f32 v88, v92, v93
	v_cvt_pk_bf16_f32 v89, v94, v95
	v_pk_mul_f32 v[84:85], v[84:85], v[98:99] op_sel_hi:[1,0]
	v_cvt_pk_bf16_f32 v90, v90, v91
	v_cvt_pk_bf16_f32 v91, v100, v101
	flat_store_dwordx4 v[96:97], v[88:91] sc1
	v_pk_mul_f32 v[86:87], v[86:87], v[98:99] op_sel_hi:[1,0]
	s_nop 0
	v_pk_mul_f32 v[88:89], v[82:83], v[98:99] op_sel_hi:[1,0]
	v_pk_mul_f32 v[82:83], v[80:81], v[98:99] op_sel_hi:[1,0]
	v_cvt_pk_bf16_f32 v80, v84, v85
	v_cvt_pk_bf16_f32 v81, v86, v87
	s_nop 0
	v_cvt_pk_bf16_f32 v82, v82, v83
	v_cvt_pk_bf16_f32 v83, v88, v89
	flat_store_dwordx4 v[96:97], v[80:83] offset:256 sc1
	ds_read_b32 v82, v250 offset:192
	s_waitcnt lgkmcnt(0)
	v_pk_mul_f32 v[78:79], v[78:79], v[82:83] op_sel_hi:[1,0]
	v_or_b32_e32 v80, 48, v208
	v_ashrrev_i32_e32 v81, 31, v80
	v_lshlrev_b64 v[80:81], 11, v[80:81]
	v_lshl_add_u64 v[80:81], s[26:27], 0, v[80:81]
	v_lshl_add_u64 v[80:81], v[80:81], 0, s[4:5]
	v_lshl_add_u64 v[80:81], v[80:81], 0, s[14:15]
	v_lshl_add_u64 v[80:81], v[80:81], 0, v[132:133]
	v_pk_mul_f32 v[76:77], v[76:77], v[82:83] op_sel_hi:[1,0]
	v_pk_mul_f32 v[84:85], v[74:75], v[82:83] op_sel_hi:[1,0]
	v_pk_mul_f32 v[74:75], v[72:73], v[82:83] op_sel_hi:[1,0]
	v_cvt_pk_bf16_f32 v72, v76, v77
	v_cvt_pk_bf16_f32 v73, v78, v79
	v_pk_mul_f32 v[70:71], v[70:71], v[82:83] op_sel_hi:[1,0]
	v_cvt_pk_bf16_f32 v74, v74, v75
	v_cvt_pk_bf16_f32 v75, v84, v85
	flat_store_dwordx4 v[80:81], v[72:75] sc1
	v_pk_mul_f32 v[68:69], v[68:69], v[82:83] op_sel_hi:[1,0]
	s_mov_b32 s4, 0x40000
	v_pk_mul_f32 v[72:73], v[66:67], v[82:83] op_sel_hi:[1,0]
	v_pk_mul_f32 v[66:67], v[64:65], v[82:83] op_sel_hi:[1,0]
	v_cvt_pk_bf16_f32 v64, v68, v69
	v_cvt_pk_bf16_f32 v65, v70, v71
	s_nop 0
	v_cvt_pk_bf16_f32 v66, v66, v67
	v_cvt_pk_bf16_f32 v67, v72, v73
	flat_store_dwordx4 v[80:81], v[64:67] offset:256 sc1
	ds_read_b32 v64, v250 offset:256
	s_waitcnt lgkmcnt(0)
; __device__ __forceinline__ unsigned cvt_pk_bf16(float lo, float hi) { unsigned r; asm volatile("v_cvt_pk_bf16_f32 %0, %1, %2" : "=v"(r) : "v"(lo), "v"(hi)); return r; }
;     __device__ __forceinline__ void operator()(const f32x4 (&acc)[2][2][4][2], const Unit& u, int wr, int wc, int fr, int fq) const {
;     ...
;         if (u.pn >= 8) {
; #pragma unroll
;             for (int ai = 0; ai < 2; ++ai)
; #pragma unroll
;                 for (int m = 0; m < 4; ++m) {
;                     const int row = row0 + ai * HALF + m * 16; const float rs = tb[ai * 64 + m * 16 + fr];
;                     bf16_t* rowp = V + (size_t)row * 1024 + (u.pn - 8) * BM + wc * 32 + 8 * fq;
; #pragma unroll
;                     for (int bj = 0; bj < 2; ++bj) { const f32x4 v0 = acc[ai][bj][m][0] * rs, v1 = acc[ai][bj][m][1] * rs; u32x4 w;
;                         w.x = cvt_pk_bf16(v0[0], v0[1]); w.y = cvt_pk_bf16(v0[2], v0[3]); w.z = cvt_pk_bf16(v1[0], v1[1]); w.w = cvt_pk_bf16(v1[2], v1[3]);
;                         *(u32x4*)(rowp + bj * HALF) = w; }
;                 }
;             return;
	v_pk_mul_f32 v[60:61], v[60:61], v[64:65] op_sel_hi:[1,0]
	v_pk_mul_f32 v[68:69], v[58:59], v[64:65] op_sel_hi:[1,0]
	v_pk_mul_f32 v[58:59], v[56:57], v[64:65] op_sel_hi:[1,0]
	v_cvt_pk_bf16_f32 v56, v60, v61
	v_add_co_u32_e32 v60, vcc, s4, v128
	v_pk_mul_f32 v[62:63], v[62:63], v[64:65] op_sel_hi:[1,0]
	s_nop 0
	v_addc_co_u32_e32 v61, vcc, 0, v129, vcc
	v_cvt_pk_bf16_f32 v57, v62, v63
	v_lshl_add_u64 v[66:67], v[128:129], 0, s[18:19]
	v_cvt_pk_bf16_f32 v58, v58, v59
	v_cvt_pk_bf16_f32 v59, v68, v69
	flat_store_dwordx4 v[60:61], v[56:59] sc1
	v_pk_mul_f32 v[54:55], v[54:55], v[64:65] op_sel_hi:[1,0]
	v_pk_mul_f32 v[52:53], v[52:53], v[64:65] op_sel_hi:[1,0]
	v_pk_mul_f32 v[56:57], v[46:47], v[64:65] op_sel_hi:[1,0]
	v_pk_mul_f32 v[46:47], v[44:45], v[64:65] op_sel_hi:[1,0]
	v_cvt_pk_bf16_f32 v44, v52, v53
	v_cvt_pk_bf16_f32 v45, v54, v55
	s_mov_b64 s[4:5], 0x48000
	v_cvt_pk_bf16_f32 v46, v46, v47
	v_cvt_pk_bf16_f32 v47, v56, v57
	flat_store_dwordx4 v[66:67], v[44:47] offset:256 sc1
	ds_read_b32 v44, v250 offset:320
	s_waitcnt lgkmcnt(0)
	v_pk_mul_f32 v[48:49], v[48:49], v[44:45] op_sel_hi:[1,0]
	v_lshl_add_u64 v[46:47], v[128:129], 0, s[4:5]
	s_mov_b32 s4, 0x48000
	v_pk_mul_f32 v[52:53], v[42:43], v[44:45] op_sel_hi:[1,0]
	v_pk_mul_f32 v[42:43], v[40:41], v[44:45] op_sel_hi:[1,0]
	v_cvt_pk_bf16_f32 v40, v48, v49
	v_add_co_u32_e32 v48, vcc, s4, v128
	v_pk_mul_f32 v[50:51], v[50:51], v[44:45] op_sel_hi:[1,0]
	s_nop 0
	v_addc_co_u32_e32 v49, vcc, 0, v129, vcc
	v_cvt_pk_bf16_f32 v41, v50, v51
	v_cvt_pk_bf16_f32 v42, v42, v43
	v_cvt_pk_bf16_f32 v43, v52, v53
	flat_store_dwordx4 v[48:49], v[40:43] sc1
	v_pk_mul_f32 v[38:39], v[38:39], v[44:45] op_sel_hi:[1,0]
	v_pk_mul_f32 v[36:37], v[36:37], v[44:45] op_sel_hi:[1,0]
	v_pk_mul_f32 v[40:41], v[30:31], v[44:45] op_sel_hi:[1,0]
	v_pk_mul_f32 v[30:31], v[28:29], v[44:45] op_sel_hi:[1,0]
	v_cvt_pk_bf16_f32 v28, v36, v37
	v_cvt_pk_bf16_f32 v29, v38, v39
	s_mov_b64 s[4:5], 0x50000
	v_cvt_pk_bf16_f32 v30, v30, v31
	v_cvt_pk_bf16_f32 v31, v40, v41
	flat_store_dwordx4 v[46:47], v[28:31] offset:256 sc1
	ds_read_b32 v28, v250 offset:384
	s_waitcnt lgkmcnt(0)
	v_pk_mul_f32 v[32:33], v[32:33], v[28:29] op_sel_hi:[1,0]
	v_lshl_add_u64 v[30:31], v[128:129], 0, s[4:5]
	s_mov_b32 s4, 0x50000
	v_pk_mul_f32 v[36:37], v[26:27], v[28:29] op_sel_hi:[1,0]
	v_pk_mul_f32 v[26:27], v[24:25], v[28:29] op_sel_hi:[1,0]
	v_cvt_pk_bf16_f32 v24, v32, v33
	v_add_co_u32_e32 v32, vcc, s4, v128
	v_pk_mul_f32 v[34:35], v[34:35], v[28:29] op_sel_hi:[1,0]
	s_nop 0
	v_addc_co_u32_e32 v33, vcc, 0, v129, vcc
	v_cvt_pk_bf16_f32 v25, v34, v35
	v_cvt_pk_bf16_f32 v26, v26, v27
	v_cvt_pk_bf16_f32 v27, v36, v37
	flat_store_dwordx4 v[32:33], v[24:27] sc1
	v_pk_mul_f32 v[22:23], v[22:23], v[28:29] op_sel_hi:[1,0]
	v_pk_mul_f32 v[20:21], v[20:21], v[28:29] op_sel_hi:[1,0]
	v_pk_mul_f32 v[24:25], v[14:15], v[28:29] op_sel_hi:[1,0]
	v_pk_mul_f32 v[14:15], v[12:13], v[28:29] op_sel_hi:[1,0]
	v_cvt_pk_bf16_f32 v12, v20, v21
	v_cvt_pk_bf16_f32 v13, v22, v23
	s_mov_b64 s[4:5], 0x58000
	v_cvt_pk_bf16_f32 v14, v14, v15
	v_cvt_pk_bf16_f32 v15, v24, v25
	flat_store_dwordx4 v[30:31], v[12:15] offset:256 sc1
	ds_read_b32 v12, v250 offset:448
	s_waitcnt lgkmcnt(0)
	v_pk_mul_f32 v[16:17], v[16:17], v[12:13] op_sel_hi:[1,0]
	v_lshl_add_u64 v[14:15], v[128:129], 0, s[4:5]
	s_mov_b32 s4, 0x58000
	v_pk_mul_f32 v[20:21], v[10:11], v[12:13] op_sel_hi:[1,0]
	v_pk_mul_f32 v[10:11], v[8:9], v[12:13] op_sel_hi:[1,0]
	v_cvt_pk_bf16_f32 v8, v16, v17
	v_add_co_u32_e32 v16, vcc, s4, v128
	v_pk_mul_f32 v[18:19], v[18:19], v[12:13] op_sel_hi:[1,0]
	s_nop 0
	v_addc_co_u32_e32 v17, vcc, 0, v129, vcc
	v_cvt_pk_bf16_f32 v9, v18, v19
	v_cvt_pk_bf16_f32 v10, v10, v11
	v_cvt_pk_bf16_f32 v11, v20, v21
	flat_store_dwordx4 v[16:17], v[8:11] sc1
	v_pk_mul_f32 v[6:7], v[6:7], v[12:13] op_sel_hi:[1,0]
	v_pk_mul_f32 v[4:5], v[4:5], v[12:13] op_sel_hi:[1,0]
	v_pk_mul_f32 v[8:9], v[2:3], v[12:13] op_sel_hi:[1,0]
	v_pk_mul_f32 v[2:3], v[0:1], v[12:13] op_sel_hi:[1,0]
	v_cvt_pk_bf16_f32 v0, v4, v5
	v_cvt_pk_bf16_f32 v1, v6, v7
	s_nop 0
	v_cvt_pk_bf16_f32 v2, v2, v3
	v_cvt_pk_bf16_f32 v3, v8, v9
	flat_store_dwordx4 v[14:15], v[0:3] offset:256 sc1
	s_andn2_b64 vcc, exec, s[0:1]
	s_mov_b64 s[0:1], -1
	s_cbranch_vccnz .LBB0_139

; __device__ __forceinline__ unsigned cvt_pk_bf16(float lo, float hi) { unsigned r; asm volatile("v_cvt_pk_bf16_f32 %0, %1, %2" : "=v"(r) : "v"(lo), "v"(hi)); return r; }
; __device__ __forceinline__ float row_rstd16(const float* rowsq, int row) {
;     const f32x4* p = (const f32x4*)(rowsq + (size_t)row * 16);
;     const f32x4 a = p[0], b = p[1], c = p[2], d = p[3];
;     const float s = ((a[0] + a[1]) + (a[2] + a[3])) + ((b[0] + b[1]) + (b[2] + b[3])) + ((c[0] + c[1]) + (c[2] + c[3])) + ((d[0] + d[1]) + (d[2] + d[3]));
;     return __builtin_amdgcn_rsqf(s * (1.0f / 1024.0f) + 1e-6f);
; }
;     __device__ __forceinline__ void operator()(const f32x4 (&acc)[2][2][4][2], const Unit& u, int wr, int wc, int fr, int fq) const {
;     ...
;         for (int ai = 0; ai < 2; ++ai) tb[ai * 64 + fq * 16 + fr] = row_rstd16(rowsq, u.pm * BM + ai * HALF + wr * 64 + fq * 16 + fr);
; #pragma unroll
;         for (int ai = 0; ai < 2; ++ai)
; #pragma unroll
;             for (int m = 0; m < 4; ++m) {
;                 const int row = row0 + ai * HALF + m * 16; const float rs = tb[ai * 64 + m * 16 + fr];
;                 if (u.pn < 4) {
;                     bf16_t* rowp = UV + (size_t)row * 1024 + u.pn * BM + wc * 32 + 8 * fq;
; #pragma unroll
;                     for (int bj = 0; bj < 2; ++bj) { const f32x4 v0 = acc[ai][bj][m][0] * rs, v1 = acc[ai][bj][m][1] * rs; u32x4 w;
;                         w.x = cvt_pk_bf16(gelu_tanh(v0[0]), gelu_tanh(v0[1])); w.y = cvt_pk_bf16(gelu_tanh(v0[2]), gelu_tanh(v0[3]));
;                         w.z = cvt_pk_bf16(gelu_tanh(v1[0]), gelu_tanh(v1[1])); w.w = cvt_pk_bf16(gelu_tanh(v1[2]), gelu_tanh(v1[3]));
;                         *(u32x4*)(rowp + bj * HALF) = w; }
;                 } else {
;                     bf16_t* rowp = Gb + (size_t)row * 512 + (u.pn - 4) * 128 + wc * 32 + 8 * fq;
;                     const f32x4 a0 = acc[ai][0][m][0] * rs, a1 = acc[ai][0][m][1] * rs, g0 = acc[ai][1][m][0] * rs, g1 = acc[ai][1][m][1] * rs; u32x4 w;
;                     w.x = cvt_pk_bf16(a0[0] * sigmoidf_(g0[0]), a0[1] * sigmoidf_(g0[1])); w.y = cvt_pk_bf16(a0[2] * sigmoidf_(g0[2]), a0[3] * sigmoidf_(g0[3]));
;                     w.z = cvt_pk_bf16(a1[0] * sigmoidf_(g1[0]), a1[1] * sigmoidf_(g1[1])); w.w = cvt_pk_bf16(a1[2] * sigmoidf_(g1[2]), a1[3] * sigmoidf_(g1[3]));
;                     *(u32x4*)rowp = w;
.LBB0_268:
	s_lshl_b32 s3, s3, 8
	v_add_u32_e32 v146, s3, v150
	v_ashrrev_i32_e32 v147, 31, v146
	v_lshlrev_b64 v[142:143], 6, v[146:147]
	v_lshl_add_u64 v[162:163], s[8:9], 0, v[142:143]
	flat_load_dwordx4 v[142:145], v[162:163]
	flat_load_dwordx4 v[154:157], v[162:163] offset:16
	flat_load_dwordx4 v[158:161], v[162:163] offset:32
	s_nop 0
	flat_load_dwordx4 v[162:165], v[162:163] offset:48
	v_add_u32_e32 v194, 0x80, v146
	v_ashrrev_i32_e32 v195, 31, v194
	v_lshlrev_b64 v[194:195], 6, v[194:195]
	v_lshl_add_u64 v[194:195], s[8:9], 0, v[194:195]
	flat_load_dwordx4 v[196:199], v[194:195]
	flat_load_dwordx4 v[200:203], v[194:195] offset:16
	flat_load_dwordx4 v[204:207], v[194:195] offset:32
	flat_load_dwordx4 v[208:211], v[194:195] offset:48
	v_add_u32_e32 v146, 0x80, v146
	s_cmp_gt_i32 s10, 3
	s_cselect_b64 s[16:17], -1, 0
	v_readlane_b32 s14, v254, 24
	s_mov_b64 s[0:1], -1
	s_and_b64 vcc, exec, s[16:17]
	v_readlane_b32 s15, v254, 25
	s_waitcnt vmcnt(0) lgkmcnt(0)
	v_add_f32_e32 v142, v142, v143
	v_add_f32_e32 v143, v144, v145
	v_add_f32_e32 v144, v154, v155
	v_add_f32_e32 v145, v156, v157
	v_add_f32_e32 v147, v158, v159
	v_add_f32_e32 v148, v160, v161
	v_add_f32_e32 v142, v142, v143
	v_add_f32_e32 v143, v144, v145
	v_add_f32_e32 v154, v162, v163
	v_add_f32_e32 v155, v164, v165
	v_add_f32_e32 v144, v147, v148
	v_add_f32_e32 v142, v142, v143
	v_add_f32_e32 v145, v154, v155
	v_add_f32_e32 v142, v142, v144
	v_add_f32_e32 v142, v142, v145
	v_fmamk_f32 v142, v142, 0x3a800000, v241
	v_rsq_f32_e32 v144, v142
	v_ashrrev_i32_e32 v147, 31, v146
	ds_write_b32 v152, v144
	v_add_u32_e32 v144, s3, v137
	v_lshlrev_b32_e32 v142, 1, v136
	s_waitcnt vmcnt(0) lgkmcnt(0)
	v_add_f32_e32 v143, v196, v197
	v_add_f32_e32 v145, v198, v199
	v_add_f32_e32 v146, v200, v201
	v_add_f32_e32 v147, v202, v203
	v_add_f32_e32 v148, v204, v205
	v_add_f32_e32 v154, v206, v207
	v_add_f32_e32 v143, v143, v145
	v_add_f32_e32 v145, v146, v147
	v_add_f32_e32 v155, v208, v209
	v_add_f32_e32 v156, v210, v211
	v_add_f32_e32 v146, v148, v154
	v_add_f32_e32 v143, v143, v145
	v_add_f32_e32 v147, v155, v156
	v_add_f32_e32 v143, v143, v146
	v_add_f32_e32 v143, v143, v147
	v_fmamk_f32 v143, v143, 0x3a800000, v241
	ds_read_b32 v148, v151
	v_rsq_f32_e32 v143, v143
	v_ashrrev_i32_e32 v145, 31, v144
	ds_write_b32 v152, v143 offset:256
	s_cbranch_vccz .LBB0_270
	v_lshlrev_b64 v[146:147], 10, v[144:145]
	v_lshl_add_u64 v[146:147], s[42:43], 0, v[146:147]
	s_lshl_b32 s14, s10, 8
	v_lshl_add_u64 v[146:147], v[146:147], 0, s[14:15]
	s_lshl_b32 s14, s58, 1
	v_lshl_add_u64 v[146:147], v[146:147], 0, s[14:15]
	v_mov_b32_e32 v143, v177
	s_waitcnt lgkmcnt(1)
	v_pk_mul_f32 v[164:165], v[116:117], v[148:149] op_sel_hi:[1,0]
	v_lshl_add_u64 v[146:147], v[146:147], 0, v[142:143]
	v_mul_f32_e32 v143, 0xbfb8aa3b, v164
	v_mul_f32_e32 v164, 0xbfb8aa3b, v165
	v_exp_f32_e32 v143, v143
	v_exp_f32_e32 v168, v164
	v_pk_mul_f32 v[162:163], v[118:119], v[148:149] op_sel_hi:[1,0]
	v_pk_mul_f32 v[154:155], v[124:125], v[148:149] op_sel_hi:[1,0]
	v_add_f32_e32 v143, 1.0, v143
	v_add_f32_e32 v168, 1.0, v168
	v_rcp_f32_e32 v143, v143
	v_rcp_f32_e32 v168, v168
	v_mul_f32_e32 v162, 0xbfb8aa3b, v162
	v_exp_f32_e32 v162, v162
	v_pk_mul_f32 v[164:165], v[112:113], v[148:149] op_sel_hi:[1,0]
	v_mul_f32_e32 v143, v154, v143
	v_mul_f32_e32 v154, v155, v168
	v_mul_f32_e32 v155, 0xbfb8aa3b, v163
	v_cvt_pk_bf16_f32 v154, v143, v154
	v_add_f32_e32 v143, 1.0, v162
	v_exp_f32_e32 v155, v155
	v_mul_f32_e32 v162, 0xbfb8aa3b, v164
	v_rcp_f32_e32 v143, v143
	v_exp_f32_e32 v162, v162
	v_pk_mul_f32 v[156:157], v[126:127], v[148:149] op_sel_hi:[1,0]
	v_add_f32_e32 v155, 1.0, v155
	v_mul_f32_e32 v143, v156, v143
	v_rcp_f32_e32 v155, v155
	v_add_f32_e32 v156, 1.0, v162
	v_rcp_f32_e32 v156, v156
	v_pk_mul_f32 v[160:161], v[120:121], v[148:149] op_sel_hi:[1,0]
	v_pk_mul_f32 v[166:167], v[114:115], v[148:149] op_sel_hi:[1,0]
	v_mul_f32_e32 v162, 0xbfb8aa3b, v165
	v_mul_f32_e32 v155, v157, v155
	v_exp_f32_e32 v162, v162
	v_cvt_pk_bf16_f32 v155, v143, v155
	v_mul_f32_e32 v143, v160, v156
	v_mul_f32_e32 v157, 0xbfb8aa3b, v166
	v_mul_f32_e32 v160, 0xbfb8aa3b, v167
	v_exp_f32_e32 v157, v157
	v_exp_f32_e32 v160, v160
	v_add_f32_e32 v156, 1.0, v162
	v_rcp_f32_e32 v156, v156
	v_add_f32_e32 v157, 1.0, v157
	v_add_f32_e32 v160, 1.0, v160
	v_rcp_f32_e32 v157, v157
	v_rcp_f32_e32 v160, v160
	v_pk_mul_f32 v[158:159], v[122:123], v[148:149] op_sel_hi:[1,0]
	v_mul_f32_e32 v156, v161, v156
	v_add_co_u32_e32 v146, vcc, 0xfffffc00, v146
	v_cvt_pk_bf16_f32 v156, v143, v156
	v_mul_f32_e32 v143, v158, v157
	v_mul_f32_e32 v157, v159, v160
	v_addc_co_u32_e32 v147, vcc, -1, v147, vcc
	v_cvt_pk_bf16_f32 v157, v143, v157
	flat_store_dwordx4 v[146:147], v[154:157] sc1
	s_mov_b64 s[0:1], 0
; __device__ __forceinline__ unsigned cvt_pk_bf16(float lo, float hi) { unsigned r; asm volatile("v_cvt_pk_bf16_f32 %0, %1, %2" : "=v"(r) : "v"(lo), "v"(hi)); return r; }
; __device__ __forceinline__ float gelu_tanh(float x) {
;     const float t = 0.7978845608028654f * (x + 0.044715f * x * x * x);
;     const float e = __builtin_amdgcn_exp2f(-2.0f * 1.4426950408889634f * t);
;     return x * __builtin_amdgcn_rcpf(1.0f + e);
; }
;     __device__ __forceinline__ void operator()(const f32x4 (&acc)[2][2][4][2], const Unit& u, int wr, int wc, int fr, int fq) const {
;     ...
;                 const int row = row0 + ai * HALF + m * 16; const float rs = tb[ai * 64 + m * 16 + fr];
;                 if (u.pn < 4) {
;                     bf16_t* rowp = UV + (size_t)row * 1024 + u.pn * BM + wc * 32 + 8 * fq;
; #pragma unroll
;                     for (int bj = 0; bj < 2; ++bj) { const f32x4 v0 = acc[ai][bj][m][0] * rs, v1 = acc[ai][bj][m][1] * rs; u32x4 w;
;                         w.x = cvt_pk_bf16(gelu_tanh(v0[0]), gelu_tanh(v0[1])); w.y = cvt_pk_bf16(gelu_tanh(v0[2]), gelu_tanh(v0[3]));
;                         w.z = cvt_pk_bf16(gelu_tanh(v1[0]), gelu_tanh(v1[1])); w.w = cvt_pk_bf16(gelu_tanh(v1[2]), gelu_tanh(v1[3]));
;                         *(u32x4*)(rowp + bj * HALF) = w; }
.LBB0_270:
	s_andn2_b64 vcc, exec, s[0:1]
	s_cbranch_vccnz .LBB0_272
	s_waitcnt lgkmcnt(0)
	v_pk_mul_f32 v[124:125], v[124:125], v[148:149] op_sel_hi:[1,0]
	v_pk_mul_f32 v[154:155], v[122:123], v[148:149] op_sel_hi:[1,0]
	v_pk_mul_f32 v[122:123], v[120:121], v[148:149] op_sel_hi:[1,0]
	v_mul_f32_e32 v120, 0x3d372713, v124
	v_mul_f32_e32 v121, 0x3d372713, v125
	v_mul_f32_e32 v120, v124, v120
	v_mul_f32_e32 v121, v125, v121
	v_fma_f32 v120, v124, v120, v124
	v_fma_f32 v121, v125, v121, v125
	v_mul_f32_e32 v120, 0x3f4c422a, v120
	v_mul_f32_e32 v121, 0x3f4c422a, v121
	v_mul_f32_e32 v120, 0xc038aa3b, v120
	v_mul_f32_e32 v121, 0xc038aa3b, v121
	v_exp_f32_e32 v120, v120
	v_exp_f32_e32 v121, v121
	v_pk_mul_f32 v[126:127], v[126:127], v[148:149] op_sel_hi:[1,0]
	v_lshlrev_b64 v[146:147], 11, v[144:145]
	v_add_f32_e32 v120, 1.0, v120
	v_add_f32_e32 v121, 1.0, v121
	v_rcp_f32_e32 v120, v120
	v_rcp_f32_e32 v121, v121
	s_lshl_b32 s0, s10, 8
	v_lshl_add_u64 v[146:147], s[40:41], 0, v[146:147]
	v_mul_f32_e32 v120, v124, v120
	v_mul_f32_e32 v121, v125, v121
	v_cvt_pk_bf16_f32 v120, v120, v121
	v_mul_f32_e32 v121, 0x3d372713, v126
	v_mul_f32_e32 v124, 0x3d372713, v127
	v_mul_f32_e32 v121, v126, v121
	v_mul_f32_e32 v124, v127, v124
	v_fma_f32 v121, v126, v121, v126
	v_fma_f32 v124, v127, v124, v127
	v_mul_f32_e32 v121, 0x3f4c422a, v121
	v_mul_f32_e32 v124, 0x3f4c422a, v124
	v_mul_f32_e32 v121, 0xc038aa3b, v121
	v_mul_f32_e32 v124, 0xc038aa3b, v124
	v_exp_f32_e32 v121, v121
	v_exp_f32_e32 v124, v124
	s_ashr_i32 s1, s0, 31
	v_lshl_add_u64 v[146:147], s[0:1], 1, v[146:147]
	v_add_f32_e32 v121, 1.0, v121
	v_add_f32_e32 v124, 1.0, v124
	v_rcp_f32_e32 v121, v121
	v_rcp_f32_e32 v124, v124
	s_lshl_b32 s14, s58, 1
	v_lshl_add_u64 v[146:147], v[146:147], 0, s[14:15]
	v_mul_f32_e32 v121, v126, v121
	v_mul_f32_e32 v124, v127, v124
	v_cvt_pk_bf16_f32 v121, v121, v124
	v_mul_f32_e32 v124, 0x3d372713, v122
	v_mul_f32_e32 v124, v122, v124
	v_fma_f32 v124, v122, v124, v122
	v_mul_f32_e32 v124, 0x3f4c422a, v124
	v_mul_f32_e32 v124, 0xc038aa3b, v124
	v_exp_f32_e32 v124, v124
	v_mov_b32_e32 v143, v177
	v_lshl_add_u64 v[146:147], v[146:147], 0, v[142:143]
	v_pk_mul_f32 v[116:117], v[116:117], v[148:149] op_sel_hi:[1,0]
	v_add_f32_e32 v124, 1.0, v124
	v_rcp_f32_e32 v124, v124
	v_pk_mul_f32 v[118:119], v[118:119], v[148:149] op_sel_hi:[1,0]
	v_mul_f32_e32 v122, v122, v124
	v_mul_f32_e32 v124, 0x3d372713, v123
	v_mul_f32_e32 v124, v123, v124
	v_fma_f32 v124, v123, v124, v123
	v_mul_f32_e32 v124, 0x3f4c422a, v124
	v_mul_f32_e32 v124, 0xc038aa3b, v124
	v_exp_f32_e32 v124, v124
	s_nop 0
	v_add_f32_e32 v124, 1.0, v124
	v_rcp_f32_e32 v124, v124
	s_nop 0
	v_mul_f32_e32 v123, v123, v124
	v_cvt_pk_bf16_f32 v122, v122, v123
	v_mul_f32_e32 v123, 0x3d372713, v154
	v_mul_f32_e32 v123, v154, v123
	v_mul_f32_e32 v124, 0x3d372713, v155
	v_fma_f32 v123, v154, v123, v154
	v_mul_f32_e32 v124, v155, v124
	v_mul_f32_e32 v123, 0x3f4c422a, v123
	v_fma_f32 v124, v155, v124, v155
	v_mul_f32_e32 v123, 0xc038aa3b, v123
	v_mul_f32_e32 v124, 0x3f4c422a, v124
	v_exp_f32_e32 v123, v123
	v_mul_f32_e32 v124, 0xc038aa3b, v124
	v_exp_f32_e32 v124, v124
	v_add_f32_e32 v123, 1.0, v123
	v_rcp_f32_e32 v123, v123
	v_add_f32_e32 v124, 1.0, v124
	v_rcp_f32_e32 v124, v124
	v_mul_f32_e32 v123, v154, v123
	v_mul_f32_e32 v124, v155, v124
	v_cvt_pk_bf16_f32 v123, v123, v124
	flat_store_dwordx4 v[146:147], v[120:123] sc1
	s_nop 1
	v_pk_mul_f32 v[120:121], v[114:115], v[148:149] op_sel_hi:[1,0]
	v_pk_mul_f32 v[114:115], v[112:113], v[148:149] op_sel_hi:[1,0]
	v_mul_f32_e32 v112, 0x3d372713, v116
	v_mul_f32_e32 v113, 0x3d372713, v117
	v_mul_f32_e32 v112, v116, v112
	v_mul_f32_e32 v113, v117, v113
	v_fma_f32 v112, v116, v112, v116
	v_fma_f32 v113, v117, v113, v117
	v_mul_f32_e32 v112, 0x3f4c422a, v112
	v_mul_f32_e32 v113, 0x3f4c422a, v113
	v_mul_f32_e32 v112, 0xc038aa3b, v112
	v_mul_f32_e32 v113, 0xc038aa3b, v113
	v_exp_f32_e32 v112, v112
	v_exp_f32_e32 v113, v113
	v_add_f32_e32 v112, 1.0, v112
	v_add_f32_e32 v113, 1.0, v113
	v_rcp_f32_e32 v112, v112
	v_rcp_f32_e32 v113, v113
	v_mul_f32_e32 v112, v116, v112
	v_mul_f32_e32 v113, v117, v113
	v_cvt_pk_bf16_f32 v112, v112, v113
	v_mul_f32_e32 v113, 0x3d372713, v118
	v_mul_f32_e32 v116, 0x3d372713, v119
	v_mul_f32_e32 v113, v118, v113
	v_mul_f32_e32 v116, v119, v116
	v_fma_f32 v113, v118, v113, v118
	v_fma_f32 v116, v119, v116, v119
	v_mul_f32_e32 v113, 0x3f4c422a, v113
	v_mul_f32_e32 v116, 0x3f4c422a, v116
	v_mul_f32_e32 v113, 0xc038aa3b, v113
	v_mul_f32_e32 v116, 0xc038aa3b, v116
	v_exp_f32_e32 v113, v113
	v_exp_f32_e32 v116, v116
	v_add_f32_e32 v113, 1.0, v113
	v_add_f32_e32 v116, 1.0, v116
	v_rcp_f32_e32 v113, v113
	v_rcp_f32_e32 v116, v116
	v_mul_f32_e32 v113, v118, v113
	v_mul_f32_e32 v116, v119, v116
	v_cvt_pk_bf16_f32 v113, v113, v116
	v_mul_f32_e32 v116, 0x3d372713, v114
	v_mul_f32_e32 v116, v114, v116
	v_fma_f32 v116, v114, v116, v114
	v_mul_f32_e32 v116, 0x3f4c422a, v116
	v_mul_f32_e32 v116, 0xc038aa3b, v116
	v_exp_f32_e32 v116, v116
	s_nop 0
	v_add_f32_e32 v116, 1.0, v116
	v_rcp_f32_e32 v116, v116
	s_nop 0
	v_mul_f32_e32 v114, v114, v116
	v_mul_f32_e32 v116, 0x3d372713, v115
	v_mul_f32_e32 v116, v115, v116
	v_fma_f32 v116, v115, v116, v115
	v_mul_f32_e32 v116, 0x3f4c422a, v116
	v_mul_f32_e32 v116, 0xc038aa3b, v116
	v_exp_f32_e32 v116, v116
	s_nop 0
	v_add_f32_e32 v116, 1.0, v116
	v_rcp_f32_e32 v116, v116
	s_nop 0
	v_mul_f32_e32 v115, v115, v116
	v_cvt_pk_bf16_f32 v114, v114, v115
	v_mul_f32_e32 v115, 0x3d372713, v120
	v_mul_f32_e32 v115, v120, v115
	v_mul_f32_e32 v116, 0x3d372713, v121
	v_fma_f32 v115, v120, v115, v120
	v_mul_f32_e32 v116, v121, v116
	v_mul_f32_e32 v115, 0x3f4c422a, v115
	v_fma_f32 v116, v121, v116, v121
	v_mul_f32_e32 v115, 0xc038aa3b, v115
	v_mul_f32_e32 v116, 0x3f4c422a, v116
	v_exp_f32_e32 v115, v115
	v_mul_f32_e32 v116, 0xc038aa3b, v116
	v_exp_f32_e32 v116, v116
	v_add_f32_e32 v115, 1.0, v115
	v_rcp_f32_e32 v115, v115
	v_add_f32_e32 v116, 1.0, v116
	v_rcp_f32_e32 v116, v116
	v_mul_f32_e32 v115, v120, v115
	v_mul_f32_e32 v116, v121, v116
	v_cvt_pk_bf16_f32 v115, v115, v116
	flat_store_dwordx4 v[146:147], v[112:115] offset:256 sc1
; __device__ __forceinline__ unsigned cvt_pk_bf16(float lo, float hi) { unsigned r; asm volatile("v_cvt_pk_bf16_f32 %0, %1, %2" : "=v"(r) : "v"(lo), "v"(hi)); return r; }
; __device__ __forceinline__ float sigmoidf_(float x) { return __builtin_amdgcn_rcpf(1.0f + __builtin_amdgcn_exp2f(-1.4426950408889634f * x)); }
;     __device__ __forceinline__ void operator()(const f32x4 (&acc)[2][2][4][2], const Unit& u, int wr, int wc, int fr, int fq) const {
;     ...
;                 const int row = row0 + ai * HALF + m * 16; const float rs = tb[ai * 64 + m * 16 + fr];
;                 if (u.pn < 4) {
;                     bf16_t* rowp = UV + (size_t)row * 1024 + u.pn * BM + wc * 32 + 8 * fq;
; #pragma unroll
;                     for (int bj = 0; bj < 2; ++bj) { const f32x4 v0 = acc[ai][bj][m][0] * rs, v1 = acc[ai][bj][m][1] * rs; u32x4 w;
;                         w.x = cvt_pk_bf16(gelu_tanh(v0[0]), gelu_tanh(v0[1])); w.y = cvt_pk_bf16(gelu_tanh(v0[2]), gelu_tanh(v0[3]));
;                         w.z = cvt_pk_bf16(gelu_tanh(v1[0]), gelu_tanh(v1[1])); w.w = cvt_pk_bf16(gelu_tanh(v1[2]), gelu_tanh(v1[3]));
;                         *(u32x4*)(rowp + bj * HALF) = w; }
;                 } else {
;                     bf16_t* rowp = Gb + (size_t)row * 512 + (u.pn - 4) * 128 + wc * 32 + 8 * fq;
;                     const f32x4 a0 = acc[ai][0][m][0] * rs, a1 = acc[ai][0][m][1] * rs, g0 = acc[ai][1][m][0] * rs, g1 = acc[ai][1][m][1] * rs; u32x4 w;
;                     w.x = cvt_pk_bf16(a0[0] * sigmoidf_(g0[0]), a0[1] * sigmoidf_(g0[1])); w.y = cvt_pk_bf16(a0[2] * sigmoidf_(g0[2]), a0[3] * sigmoidf_(g0[3]));
;                     w.z = cvt_pk_bf16(a1[0] * sigmoidf_(g1[0]), a1[1] * sigmoidf_(g1[1])); w.w = cvt_pk_bf16(a1[2] * sigmoidf_(g1[2]), a1[3] * sigmoidf_(g1[3]));
;                     *(u32x4*)rowp = w;
.LBB0_272:
	ds_read_b32 v114, v151 offset:64
	s_nop 0
	v_or_b32_e32 v112, 16, v144
	v_cndmask_b32_e64 v115, 0, 1, s[16:17]
	v_readlane_b32 s18, v254, 53
	v_ashrrev_i32_e32 v113, 31, v112
	v_cmp_ne_u32_e64 s[0:1], 1, v115
	s_andn2_b64 vcc, exec, s[16:17]
	s_mov_b64 s[16:17], -1
	v_readlane_b32 s19, v254, 54
	s_cbranch_vccnz .LBB0_274
	v_lshlrev_b64 v[116:117], 10, v[112:113]
	v_lshl_add_u64 v[116:117], s[42:43], 0, v[116:117]
	s_lshl_b32 s14, s10, 8
	v_lshl_add_u64 v[116:117], v[116:117], 0, s[14:15]
	s_lshl_b32 s14, s58, 1
	v_lshl_add_u64 v[116:117], v[116:117], 0, s[14:15]
	v_mov_b32_e32 v143, v177
	s_waitcnt lgkmcnt(0)
	v_pk_mul_f32 v[146:147], v[100:101], v[114:115] op_sel_hi:[1,0]
	v_lshl_add_u64 v[120:121], v[116:117], 0, v[142:143]
	v_pk_mul_f32 v[118:119], v[110:111], v[114:115] op_sel_hi:[1,0]
	v_pk_mul_f32 v[116:117], v[108:109], v[114:115] op_sel_hi:[1,0]
	v_pk_mul_f32 v[122:123], v[106:107], v[114:115] op_sel_hi:[1,0]
	v_pk_mul_f32 v[124:125], v[104:105], v[114:115] op_sel_hi:[1,0]
	v_pk_mul_f32 v[126:127], v[102:103], v[114:115] op_sel_hi:[1,0]
	v_pk_mul_f32 v[154:155], v[98:99], v[114:115] op_sel_hi:[1,0]
	v_mul_f32_e32 v115, 0xbfb8aa3b, v146
	v_mul_f32_e32 v143, 0xbfb8aa3b, v147
	v_exp_f32_e32 v115, v115
	v_exp_f32_e32 v143, v143
	v_mul_f32_e32 v126, 0xbfb8aa3b, v126
	v_exp_f32_e32 v126, v126
	v_pk_mul_f32 v[146:147], v[96:97], v[114:115] op_sel_hi:[1,0]
	v_add_f32_e32 v115, 1.0, v115
	v_add_f32_e32 v143, 1.0, v143
	v_rcp_f32_e32 v115, v115
	v_rcp_f32_e32 v143, v143
	v_add_co_u32_e32 v120, vcc, 0xfffffc00, v120
	v_mul_f32_e32 v115, v116, v115
	v_mul_f32_e32 v116, v117, v143
	v_mul_f32_e32 v117, 0xbfb8aa3b, v127
	v_cvt_pk_bf16_f32 v116, v115, v116
	v_add_f32_e32 v115, 1.0, v126
	v_exp_f32_e32 v117, v117
	v_mul_f32_e32 v126, 0xbfb8aa3b, v146
	v_rcp_f32_e32 v115, v115
	v_exp_f32_e32 v126, v126
	v_add_f32_e32 v117, 1.0, v117
	v_rcp_f32_e32 v117, v117
	v_mul_f32_e32 v115, v118, v115
	v_add_f32_e32 v118, 1.0, v126
	v_rcp_f32_e32 v118, v118
	v_mul_f32_e32 v126, 0xbfb8aa3b, v147
	v_mul_f32_e32 v117, v119, v117
	v_exp_f32_e32 v126, v126
	v_cvt_pk_bf16_f32 v117, v115, v117
	v_mul_f32_e32 v115, v124, v118
	v_mul_f32_e32 v119, 0xbfb8aa3b, v154
	v_mul_f32_e32 v124, 0xbfb8aa3b, v155
	v_exp_f32_e32 v119, v119
	v_exp_f32_e32 v124, v124
	v_add_f32_e32 v118, 1.0, v126
	v_rcp_f32_e32 v118, v118
	v_add_f32_e32 v119, 1.0, v119
	v_add_f32_e32 v124, 1.0, v124
	v_rcp_f32_e32 v119, v119
	v_rcp_f32_e32 v124, v124
	v_mul_f32_e32 v118, v125, v118
	v_cvt_pk_bf16_f32 v118, v115, v118
	v_mul_f32_e32 v115, v122, v119
	v_mul_f32_e32 v119, v123, v124
	v_addc_co_u32_e32 v121, vcc, -1, v121, vcc
	s_mov_b64 s[16:17], 0
	v_cvt_pk_bf16_f32 v119, v115, v119
	flat_store_dwordx4 v[120:121], v[116:119] sc1
.LBB0_274:
	s_andn2_b64 vcc, exec, s[16:17]
	s_cbranch_vccnz .LBB0_276
	s_waitcnt lgkmcnt(0)
	v_pk_mul_f32 v[108:109], v[108:109], v[114:115] op_sel_hi:[1,0]
	v_pk_mul_f32 v[116:117], v[106:107], v[114:115] op_sel_hi:[1,0]
	v_pk_mul_f32 v[106:107], v[104:105], v[114:115] op_sel_hi:[1,0]
	v_mul_f32_e32 v104, 0x3d372713, v108
	v_mul_f32_e32 v105, 0x3d372713, v109
	v_mul_f32_e32 v104, v108, v104
	v_mul_f32_e32 v105, v109, v105
	v_fma_f32 v104, v108, v104, v108
	v_fma_f32 v105, v109, v105, v109
	v_mul_f32_e32 v104, 0x3f4c422a, v104
	v_mul_f32_e32 v105, 0x3f4c422a, v105
	v_mul_f32_e32 v104, 0xc038aa3b, v104
	v_mul_f32_e32 v105, 0xc038aa3b, v105
	v_exp_f32_e32 v104, v104
	v_exp_f32_e32 v105, v105
	v_pk_mul_f32 v[110:111], v[110:111], v[114:115] op_sel_hi:[1,0]
	v_lshlrev_b64 v[112:113], 11, v[112:113]
	v_add_f32_e32 v104, 1.0, v104
	v_add_f32_e32 v105, 1.0, v105
	v_rcp_f32_e32 v104, v104
	v_rcp_f32_e32 v105, v105
	s_lshl_b32 s16, s10, 8
	v_lshl_add_u64 v[112:113], s[40:41], 0, v[112:113]
	v_mul_f32_e32 v104, v108, v104
	v_mul_f32_e32 v105, v109, v105
	v_cvt_pk_bf16_f32 v104, v104, v105
	v_mul_f32_e32 v105, 0x3d372713, v110
	v_mul_f32_e32 v108, 0x3d372713, v111
	v_mul_f32_e32 v105, v110, v105
	v_mul_f32_e32 v108, v111, v108
	v_fma_f32 v105, v110, v105, v110
	v_fma_f32 v108, v111, v108, v111
	v_mul_f32_e32 v105, 0x3f4c422a, v105
	v_mul_f32_e32 v108, 0x3f4c422a, v108
	v_mul_f32_e32 v105, 0xc038aa3b, v105
	v_mul_f32_e32 v108, 0xc038aa3b, v108
	v_exp_f32_e32 v105, v105
	v_exp_f32_e32 v108, v108
	s_ashr_i32 s17, s16, 31
	v_lshl_add_u64 v[112:113], s[16:17], 1, v[112:113]
	v_add_f32_e32 v105, 1.0, v105
	v_add_f32_e32 v108, 1.0, v108
	v_rcp_f32_e32 v105, v105
	v_rcp_f32_e32 v108, v108
	s_lshl_b32 s14, s58, 1
	v_lshl_add_u64 v[112:113], v[112:113], 0, s[14:15]
	v_mul_f32_e32 v105, v110, v105
	v_mul_f32_e32 v108, v111, v108
	v_cvt_pk_bf16_f32 v105, v105, v108
	v_mul_f32_e32 v108, 0x3d372713, v106
	v_mul_f32_e32 v108, v106, v108
	v_fma_f32 v108, v106, v108, v106
	v_mul_f32_e32 v108, 0x3f4c422a, v108
	v_mul_f32_e32 v108, 0xc038aa3b, v108
	v_exp_f32_e32 v108, v108
	v_mov_b32_e32 v143, v177
	v_lshl_add_u64 v[112:113], v[112:113], 0, v[142:143]
	v_pk_mul_f32 v[100:101], v[100:101], v[114:115] op_sel_hi:[1,0]
	v_add_f32_e32 v108, 1.0, v108
	v_rcp_f32_e32 v108, v108
	v_pk_mul_f32 v[102:103], v[102:103], v[114:115] op_sel_hi:[1,0]
	v_mul_f32_e32 v106, v106, v108
	v_mul_f32_e32 v108, 0x3d372713, v107
	v_mul_f32_e32 v108, v107, v108
	v_fma_f32 v108, v107, v108, v107
	v_mul_f32_e32 v108, 0x3f4c422a, v108
	v_mul_f32_e32 v108, 0xc038aa3b, v108
	v_exp_f32_e32 v108, v108
	s_nop 0
	v_add_f32_e32 v108, 1.0, v108
	v_rcp_f32_e32 v108, v108
	s_nop 0
	v_mul_f32_e32 v107, v107, v108
	v_cvt_pk_bf16_f32 v106, v106, v107
	v_mul_f32_e32 v107, 0x3d372713, v116
	v_mul_f32_e32 v107, v116, v107
	v_mul_f32_e32 v108, 0x3d372713, v117
	v_fma_f32 v107, v116, v107, v116
	v_mul_f32_e32 v108, v117, v108
; __device__ __forceinline__ unsigned cvt_pk_bf16(float lo, float hi) { unsigned r; asm volatile("v_cvt_pk_bf16_f32 %0, %1, %2" : "=v"(r) : "v"(lo), "v"(hi)); return r; }
; __device__ __forceinline__ float sigmoidf_(float x) { return __builtin_amdgcn_rcpf(1.0f + __builtin_amdgcn_exp2f(-1.4426950408889634f * x)); }
;     __device__ __forceinline__ void operator()(const f32x4 (&acc)[2][2][4][2], const Unit& u, int wr, int wc, int fr, int fq) const {
;     ...
;                 const int row = row0 + ai * HALF + m * 16; const float rs = tb[ai * 64 + m * 16 + fr];
;                 if (u.pn < 4) {
;                     bf16_t* rowp = UV + (size_t)row * 1024 + u.pn * BM + wc * 32 + 8 * fq;
; #pragma unroll
;                     for (int bj = 0; bj < 2; ++bj) { const f32x4 v0 = acc[ai][bj][m][0] * rs, v1 = acc[ai][bj][m][1] * rs; u32x4 w;
;                         w.x = cvt_pk_bf16(gelu_tanh(v0[0]), gelu_tanh(v0[1])); w.y = cvt_pk_bf16(gelu_tanh(v0[2]), gelu_tanh(v0[3]));
;                         w.z = cvt_pk_bf16(gelu_tanh(v1[0]), gelu_tanh(v1[1])); w.w = cvt_pk_bf16(gelu_tanh(v1[2]), gelu_tanh(v1[3]));
;                         *(u32x4*)(rowp + bj * HALF) = w; }
;                 } else {
;                     bf16_t* rowp = Gb + (size_t)row * 512 + (u.pn - 4) * 128 + wc * 32 + 8 * fq;
;                     const f32x4 a0 = acc[ai][0][m][0] * rs, a1 = acc[ai][0][m][1] * rs, g0 = acc[ai][1][m][0] * rs, g1 = acc[ai][1][m][1] * rs; u32x4 w;
;                     w.x = cvt_pk_bf16(a0[0] * sigmoidf_(g0[0]), a0[1] * sigmoidf_(g0[1])); w.y = cvt_pk_bf16(a0[2] * sigmoidf_(g0[2]), a0[3] * sigmoidf_(g0[3]));
;                     w.z = cvt_pk_bf16(a1[0] * sigmoidf_(g1[0]), a1[1] * sigmoidf_(g1[1])); w.w = cvt_pk_bf16(a1[2] * sigmoidf_(g1[2]), a1[3] * sigmoidf_(g1[3]));
;                     *(u32x4*)rowp = w;
	v_mul_f32_e32 v107, 0x3f4c422a, v107
	v_fma_f32 v108, v117, v108, v117
	v_mul_f32_e32 v107, 0xc038aa3b, v107
	v_mul_f32_e32 v108, 0x3f4c422a, v108
	v_exp_f32_e32 v107, v107
	v_mul_f32_e32 v108, 0xc038aa3b, v108
	v_exp_f32_e32 v108, v108
	v_add_f32_e32 v107, 1.0, v107
	v_rcp_f32_e32 v107, v107
	v_add_f32_e32 v108, 1.0, v108
	v_rcp_f32_e32 v108, v108
	v_mul_f32_e32 v107, v116, v107
	v_mul_f32_e32 v108, v117, v108
	v_cvt_pk_bf16_f32 v107, v107, v108
	flat_store_dwordx4 v[112:113], v[104:107] sc1
	s_nop 1
	v_pk_mul_f32 v[104:105], v[98:99], v[114:115] op_sel_hi:[1,0]
	v_pk_mul_f32 v[98:99], v[96:97], v[114:115] op_sel_hi:[1,0]
	v_mul_f32_e32 v96, 0x3d372713, v100
	v_mul_f32_e32 v97, 0x3d372713, v101
	v_mul_f32_e32 v96, v100, v96
	v_mul_f32_e32 v97, v101, v97
	v_fma_f32 v96, v100, v96, v100
	v_fma_f32 v97, v101, v97, v101
	v_mul_f32_e32 v96, 0x3f4c422a, v96
	v_mul_f32_e32 v97, 0x3f4c422a, v97
	v_mul_f32_e32 v96, 0xc038aa3b, v96
	v_mul_f32_e32 v97, 0xc038aa3b, v97
	v_exp_f32_e32 v96, v96
	v_exp_f32_e32 v97, v97
	v_add_f32_e32 v96, 1.0, v96
	v_add_f32_e32 v97, 1.0, v97
	v_rcp_f32_e32 v96, v96
	v_rcp_f32_e32 v97, v97
	v_mul_f32_e32 v96, v100, v96
	v_mul_f32_e32 v97, v101, v97
	v_cvt_pk_bf16_f32 v96, v96, v97
	v_mul_f32_e32 v97, 0x3d372713, v102
	v_mul_f32_e32 v100, 0x3d372713, v103
	v_mul_f32_e32 v97, v102, v97
	v_mul_f32_e32 v100, v103, v100
	v_fma_f32 v97, v102, v97, v102
	v_fma_f32 v100, v103, v100, v103
	v_mul_f32_e32 v97, 0x3f4c422a, v97
	v_mul_f32_e32 v100, 0x3f4c422a, v100
	v_mul_f32_e32 v97, 0xc038aa3b, v97
	v_mul_f32_e32 v100, 0xc038aa3b, v100
	v_exp_f32_e32 v97, v97
	v_exp_f32_e32 v100, v100
	v_add_f32_e32 v97, 1.0, v97
	v_add_f32_e32 v100, 1.0, v100
	v_rcp_f32_e32 v97, v97
	v_rcp_f32_e32 v100, v100
	v_mul_f32_e32 v97, v102, v97
	v_mul_f32_e32 v100, v103, v100
	v_cvt_pk_bf16_f32 v97, v97, v100
	v_mul_f32_e32 v100, 0x3d372713, v98
	v_mul_f32_e32 v100, v98, v100
	v_fma_f32 v100, v98, v100, v98
	v_mul_f32_e32 v100, 0x3f4c422a, v100
	v_mul_f32_e32 v100, 0xc038aa3b, v100
	v_exp_f32_e32 v100, v100
	s_nop 0
	v_add_f32_e32 v100, 1.0, v100
	v_rcp_f32_e32 v100, v100
	s_nop 0
	v_mul_f32_e32 v98, v98, v100
	v_mul_f32_e32 v100, 0x3d372713, v99
	v_mul_f32_e32 v100, v99, v100
	v_fma_f32 v100, v99, v100, v99
	v_mul_f32_e32 v100, 0x3f4c422a, v100
	v_mul_f32_e32 v100, 0xc038aa3b, v100
	v_exp_f32_e32 v100, v100
	s_nop 0
	v_add_f32_e32 v100, 1.0, v100
	v_rcp_f32_e32 v100, v100
	s_nop 0
	v_mul_f32_e32 v99, v99, v100
	v_cvt_pk_bf16_f32 v98, v98, v99
	v_mul_f32_e32 v99, 0x3d372713, v104
	v_mul_f32_e32 v99, v104, v99
	v_mul_f32_e32 v100, 0x3d372713, v105
	v_fma_f32 v99, v104, v99, v104
	v_mul_f32_e32 v100, v105, v100
	v_mul_f32_e32 v99, 0x3f4c422a, v99
	v_fma_f32 v100, v105, v100, v105
	v_mul_f32_e32 v99, 0xc038aa3b, v99
	v_mul_f32_e32 v100, 0x3f4c422a, v100
	v_exp_f32_e32 v99, v99
	v_mul_f32_e32 v100, 0xc038aa3b, v100
	v_exp_f32_e32 v100, v100
	v_add_f32_e32 v99, 1.0, v99
	v_rcp_f32_e32 v99, v99
	v_add_f32_e32 v100, 1.0, v100
	v_rcp_f32_e32 v100, v100
	v_mul_f32_e32 v99, v104, v99
	v_mul_f32_e32 v100, v105, v100
	v_cvt_pk_bf16_f32 v99, v99, v100
	flat_store_dwordx4 v[112:113], v[96:99] offset:256 sc1
.LBB0_276:
	ds_read_b32 v98, v151 offset:128
	s_nop 0
	v_or_b32_e32 v96, 32, v144
	v_ashrrev_i32_e32 v97, 31, v96
	s_and_b64 vcc, exec, s[0:1]
	s_mov_b64 s[16:17], -1
	s_cbranch_vccnz .LBB0_278
	v_lshlrev_b64 v[100:101], 10, v[96:97]
	v_lshl_add_u64 v[100:101], s[42:43], 0, v[100:101]
	s_lshl_b32 s14, s10, 8
	v_lshl_add_u64 v[100:101], v[100:101], 0, s[14:15]
	s_lshl_b32 s14, s58, 1
	v_lshl_add_u64 v[100:101], v[100:101], 0, s[14:15]
	v_mov_b32_e32 v143, v177
	s_waitcnt lgkmcnt(0)
	v_pk_mul_f32 v[112:113], v[84:85], v[98:99] op_sel_hi:[1,0]
	v_lshl_add_u64 v[104:105], v[100:101], 0, v[142:143]
	v_pk_mul_f32 v[102:103], v[94:95], v[98:99] op_sel_hi:[1,0]
	v_pk_mul_f32 v[100:101], v[92:93], v[98:99] op_sel_hi:[1,0]
	v_pk_mul_f32 v[106:107], v[90:91], v[98:99] op_sel_hi:[1,0]
	v_pk_mul_f32 v[108:109], v[88:89], v[98:99] op_sel_hi:[1,0]
	v_pk_mul_f32 v[110:111], v[86:87], v[98:99] op_sel_hi:[1,0]
	v_pk_mul_f32 v[114:115], v[82:83], v[98:99] op_sel_hi:[1,0]
	v_mul_f32_e32 v99, 0xbfb8aa3b, v112
	v_mul_f32_e32 v112, 0xbfb8aa3b, v113
	v_exp_f32_e32 v99, v99
	v_exp_f32_e32 v116, v112
	v_mul_f32_e32 v110, 0xbfb8aa3b, v110
	v_exp_f32_e32 v110, v110
	v_pk_mul_f32 v[112:113], v[80:81], v[98:99] op_sel_hi:[1,0]
	v_add_f32_e32 v99, 1.0, v99
	v_add_f32_e32 v116, 1.0, v116
	v_rcp_f32_e32 v99, v99
	v_rcp_f32_e32 v116, v116
	v_add_co_u32_e32 v104, vcc, 0xfffffc00, v104
	v_mul_f32_e32 v99, v100, v99
	v_mul_f32_e32 v100, v101, v116
	v_mul_f32_e32 v101, 0xbfb8aa3b, v111
	v_cvt_pk_bf16_f32 v100, v99, v100
	v_add_f32_e32 v99, 1.0, v110
	v_exp_f32_e32 v101, v101
	v_mul_f32_e32 v110, 0xbfb8aa3b, v112
	v_rcp_f32_e32 v99, v99
	v_exp_f32_e32 v110, v110
	v_add_f32_e32 v101, 1.0, v101
	v_rcp_f32_e32 v101, v101
	v_mul_f32_e32 v99, v102, v99
	v_add_f32_e32 v102, 1.0, v110
	v_rcp_f32_e32 v102, v102
	v_mul_f32_e32 v110, 0xbfb8aa3b, v113
	v_mul_f32_e32 v101, v103, v101
	v_exp_f32_e32 v110, v110
	v_cvt_pk_bf16_f32 v101, v99, v101
	v_mul_f32_e32 v99, v108, v102
	v_mul_f32_e32 v103, 0xbfb8aa3b, v114
	v_mul_f32_e32 v108, 0xbfb8aa3b, v115
	v_exp_f32_e32 v103, v103
	v_exp_f32_e32 v108, v108
	v_add_f32_e32 v102, 1.0, v110
	v_rcp_f32_e32 v102, v102
	v_add_f32_e32 v103, 1.0, v103
	v_add_f32_e32 v108, 1.0, v108
	v_rcp_f32_e32 v103, v103
	v_rcp_f32_e32 v108, v108
	v_mul_f32_e32 v102, v109, v102
	v_cvt_pk_bf16_f32 v102, v99, v102
	v_mul_f32_e32 v99, v106, v103
	v_mul_f32_e32 v103, v107, v108
	v_addc_co_u32_e32 v105, vcc, -1, v105, vcc
	s_mov_b64 s[16:17], 0
	v_cvt_pk_bf16_f32 v103, v99, v103
	flat_store_dwordx4 v[104:105], v[100:103] sc1
; __device__ __forceinline__ unsigned cvt_pk_bf16(float lo, float hi) { unsigned r; asm volatile("v_cvt_pk_bf16_f32 %0, %1, %2" : "=v"(r) : "v"(lo), "v"(hi)); return r; }
;     __device__ __forceinline__ void operator()(const f32x4 (&acc)[2][2][4][2], const Unit& u, int wr, int wc, int fr, int fq) const {
;     ...
;                 const int row = row0 + ai * HALF + m * 16; const float rs = tb[ai * 64 + m * 16 + fr];
;                 if (u.pn < 4) {
;                     bf16_t* rowp = UV + (size_t)row * 1024 + u.pn * BM + wc * 32 + 8 * fq;
; #pragma unroll
;                     for (int bj = 0; bj < 2; ++bj) { const f32x4 v0 = acc[ai][bj][m][0] * rs, v1 = acc[ai][bj][m][1] * rs; u32x4 w;
;                         w.x = cvt_pk_bf16(gelu_tanh(v0[0]), gelu_tanh(v0[1])); w.y = cvt_pk_bf16(gelu_tanh(v0[2]), gelu_tanh(v0[3]));
;                         w.z = cvt_pk_bf16(gelu_tanh(v1[0]), gelu_tanh(v1[1])); w.w = cvt_pk_bf16(gelu_tanh(v1[2]), gelu_tanh(v1[3]));
;                         *(u32x4*)(rowp + bj * HALF) = w; }
.LBB0_278:
	s_andn2_b64 vcc, exec, s[16:17]
	s_cbranch_vccnz .LBB0_280
	s_waitcnt lgkmcnt(0)
	v_pk_mul_f32 v[92:93], v[92:93], v[98:99] op_sel_hi:[1,0]
	v_pk_mul_f32 v[100:101], v[90:91], v[98:99] op_sel_hi:[1,0]
	v_pk_mul_f32 v[90:91], v[88:89], v[98:99] op_sel_hi:[1,0]
	v_mul_f32_e32 v88, 0x3d372713, v92
	v_mul_f32_e32 v89, 0x3d372713, v93
	v_mul_f32_e32 v88, v92, v88
	v_mul_f32_e32 v89, v93, v89
	v_fma_f32 v88, v92, v88, v92
	v_fma_f32 v89, v93, v89, v93
	v_mul_f32_e32 v88, 0x3f4c422a, v88
	v_mul_f32_e32 v89, 0x3f4c422a, v89
	v_mul_f32_e32 v88, 0xc038aa3b, v88
	v_mul_f32_e32 v89, 0xc038aa3b, v89
	v_exp_f32_e32 v88, v88
	v_exp_f32_e32 v89, v89
	v_pk_mul_f32 v[94:95], v[94:95], v[98:99] op_sel_hi:[1,0]
	v_lshlrev_b64 v[96:97], 11, v[96:97]
	v_add_f32_e32 v88, 1.0, v88
	v_add_f32_e32 v89, 1.0, v89
	v_rcp_f32_e32 v88, v88
	v_rcp_f32_e32 v89, v89
	s_lshl_b32 s16, s10, 8
	v_lshl_add_u64 v[96:97], s[40:41], 0, v[96:97]
	v_mul_f32_e32 v88, v92, v88
	v_mul_f32_e32 v89, v93, v89
	v_cvt_pk_bf16_f32 v88, v88, v89
	v_mul_f32_e32 v89, 0x3d372713, v94
	v_mul_f32_e32 v92, 0x3d372713, v95
	v_mul_f32_e32 v89, v94, v89
	v_mul_f32_e32 v92, v95, v92
	v_fma_f32 v89, v94, v89, v94
	v_fma_f32 v92, v95, v92, v95
	v_mul_f32_e32 v89, 0x3f4c422a, v89
	v_mul_f32_e32 v92, 0x3f4c422a, v92
	v_mul_f32_e32 v89, 0xc038aa3b, v89
	v_mul_f32_e32 v92, 0xc038aa3b, v92
	v_exp_f32_e32 v89, v89
	v_exp_f32_e32 v92, v92
	s_ashr_i32 s17, s16, 31
	v_lshl_add_u64 v[96:97], s[16:17], 1, v[96:97]
	v_add_f32_e32 v89, 1.0, v89
	v_add_f32_e32 v92, 1.0, v92
	v_rcp_f32_e32 v89, v89
	v_rcp_f32_e32 v92, v92
	s_lshl_b32 s14, s58, 1
	v_lshl_add_u64 v[96:97], v[96:97], 0, s[14:15]
	v_mul_f32_e32 v89, v94, v89
	v_mul_f32_e32 v92, v95, v92
	v_cvt_pk_bf16_f32 v89, v89, v92
	v_mul_f32_e32 v92, 0x3d372713, v90
	v_mul_f32_e32 v92, v90, v92
	v_fma_f32 v92, v90, v92, v90
	v_mul_f32_e32 v92, 0x3f4c422a, v92
	v_mul_f32_e32 v92, 0xc038aa3b, v92
	v_exp_f32_e32 v92, v92
	v_mov_b32_e32 v143, v177
	v_lshl_add_u64 v[96:97], v[96:97], 0, v[142:143]
	v_pk_mul_f32 v[84:85], v[84:85], v[98:99] op_sel_hi:[1,0]
	v_add_f32_e32 v92, 1.0, v92
	v_rcp_f32_e32 v92, v92
	v_pk_mul_f32 v[86:87], v[86:87], v[98:99] op_sel_hi:[1,0]
	v_mul_f32_e32 v90, v90, v92
	v_mul_f32_e32 v92, 0x3d372713, v91
	v_mul_f32_e32 v92, v91, v92
	v_fma_f32 v92, v91, v92, v91
	v_mul_f32_e32 v92, 0x3f4c422a, v92
	v_mul_f32_e32 v92, 0xc038aa3b, v92
	v_exp_f32_e32 v92, v92
	s_nop 0
	v_add_f32_e32 v92, 1.0, v92
	v_rcp_f32_e32 v92, v92
	s_nop 0
	v_mul_f32_e32 v91, v91, v92
	v_cvt_pk_bf16_f32 v90, v90, v91
	v_mul_f32_e32 v91, 0x3d372713, v100
	v_mul_f32_e32 v91, v100, v91
	v_mul_f32_e32 v92, 0x3d372713, v101
	v_fma_f32 v91, v100, v91, v100
	v_mul_f32_e32 v92, v101, v92
	v_mul_f32_e32 v91, 0x3f4c422a, v91
	v_fma_f32 v92, v101, v92, v101
	v_mul_f32_e32 v91, 0xc038aa3b, v91
	v_mul_f32_e32 v92, 0x3f4c422a, v92
	v_exp_f32_e32 v91, v91
	v_mul_f32_e32 v92, 0xc038aa3b, v92
	v_exp_f32_e32 v92, v92
	v_add_f32_e32 v91, 1.0, v91
	v_rcp_f32_e32 v91, v91
	v_add_f32_e32 v92, 1.0, v92
	v_rcp_f32_e32 v92, v92
	v_mul_f32_e32 v91, v100, v91
	v_mul_f32_e32 v92, v101, v92
	v_cvt_pk_bf16_f32 v91, v91, v92
	flat_store_dwordx4 v[96:97], v[88:91] sc1
	s_nop 1
	v_pk_mul_f32 v[88:89], v[82:83], v[98:99] op_sel_hi:[1,0]
	v_pk_mul_f32 v[82:83], v[80:81], v[98:99] op_sel_hi:[1,0]
	v_mul_f32_e32 v80, 0x3d372713, v84
	v_mul_f32_e32 v81, 0x3d372713, v85
	v_mul_f32_e32 v80, v84, v80
	v_mul_f32_e32 v81, v85, v81
	v_fma_f32 v80, v84, v80, v84
	v_fma_f32 v81, v85, v81, v85
	v_mul_f32_e32 v80, 0x3f4c422a, v80
	v_mul_f32_e32 v81, 0x3f4c422a, v81
	v_mul_f32_e32 v80, 0xc038aa3b, v80
	v_mul_f32_e32 v81, 0xc038aa3b, v81
	v_exp_f32_e32 v80, v80
	v_exp_f32_e32 v81, v81
	v_add_f32_e32 v80, 1.0, v80
	v_add_f32_e32 v81, 1.0, v81
	v_rcp_f32_e32 v80, v80
	v_rcp_f32_e32 v81, v81
	v_mul_f32_e32 v80, v84, v80
	v_mul_f32_e32 v81, v85, v81
	v_cvt_pk_bf16_f32 v80, v80, v81
	v_mul_f32_e32 v81, 0x3d372713, v86
	v_mul_f32_e32 v84, 0x3d372713, v87
	v_mul_f32_e32 v81, v86, v81
	v_mul_f32_e32 v84, v87, v84
	v_fma_f32 v81, v86, v81, v86
	v_fma_f32 v84, v87, v84, v87
	v_mul_f32_e32 v81, 0x3f4c422a, v81
	v_mul_f32_e32 v84, 0x3f4c422a, v84
	v_mul_f32_e32 v81, 0xc038aa3b, v81
	v_mul_f32_e32 v84, 0xc038aa3b, v84
	v_exp_f32_e32 v81, v81
	v_exp_f32_e32 v84, v84
	v_add_f32_e32 v81, 1.0, v81
	v_add_f32_e32 v84, 1.0, v84
	v_rcp_f32_e32 v81, v81
	v_rcp_f32_e32 v84, v84
	v_mul_f32_e32 v81, v86, v81
	v_mul_f32_e32 v84, v87, v84
	v_cvt_pk_bf16_f32 v81, v81, v84
	v_mul_f32_e32 v84, 0x3d372713, v82
	v_mul_f32_e32 v84, v82, v84
	v_fma_f32 v84, v82, v84, v82
	v_mul_f32_e32 v84, 0x3f4c422a, v84
	v_mul_f32_e32 v84, 0xc038aa3b, v84
	v_exp_f32_e32 v84, v84
	s_nop 0
	v_add_f32_e32 v84, 1.0, v84
	v_rcp_f32_e32 v84, v84
	s_nop 0
	v_mul_f32_e32 v82, v82, v84
	v_mul_f32_e32 v84, 0x3d372713, v83
	v_mul_f32_e32 v84, v83, v84
	v_fma_f32 v84, v83, v84, v83
	v_mul_f32_e32 v84, 0x3f4c422a, v84
	v_mul_f32_e32 v84, 0xc038aa3b, v84
	v_exp_f32_e32 v84, v84
	s_nop 0
	v_add_f32_e32 v84, 1.0, v84
	v_rcp_f32_e32 v84, v84
	s_nop 0
	v_mul_f32_e32 v83, v83, v84
	v_cvt_pk_bf16_f32 v82, v82, v83
	v_mul_f32_e32 v83, 0x3d372713, v88
	v_mul_f32_e32 v83, v88, v83
	v_mul_f32_e32 v84, 0x3d372713, v89
	v_fma_f32 v83, v88, v83, v88
	v_mul_f32_e32 v84, v89, v84
	v_mul_f32_e32 v83, 0x3f4c422a, v83
	v_fma_f32 v84, v89, v84, v89
	v_mul_f32_e32 v83, 0xc038aa3b, v83
	v_mul_f32_e32 v84, 0x3f4c422a, v84
	v_exp_f32_e32 v83, v83
	v_mul_f32_e32 v84, 0xc038aa3b, v84
	v_exp_f32_e32 v84, v84
	v_add_f32_e32 v83, 1.0, v83
	v_rcp_f32_e32 v83, v83
	v_add_f32_e32 v84, 1.0, v84
	v_rcp_f32_e32 v84, v84
	v_mul_f32_e32 v83, v88, v83
	v_mul_f32_e32 v84, v89, v84
	v_cvt_pk_bf16_f32 v83, v83, v84
	flat_store_dwordx4 v[96:97], v[80:83] offset:256 sc1
; __device__ __forceinline__ unsigned cvt_pk_bf16(float lo, float hi) { unsigned r; asm volatile("v_cvt_pk_bf16_f32 %0, %1, %2" : "=v"(r) : "v"(lo), "v"(hi)); return r; }
; __device__ __forceinline__ float sigmoidf_(float x) { return __builtin_amdgcn_rcpf(1.0f + __builtin_amdgcn_exp2f(-1.4426950408889634f * x)); }
;     __device__ __forceinline__ void operator()(const f32x4 (&acc)[2][2][4][2], const Unit& u, int wr, int wc, int fr, int fq) const {
;     ...
;                 const int row = row0 + ai * HALF + m * 16; const float rs = tb[ai * 64 + m * 16 + fr];
;                 if (u.pn < 4) {
;                     bf16_t* rowp = UV + (size_t)row * 1024 + u.pn * BM + wc * 32 + 8 * fq;
; #pragma unroll
;                     for (int bj = 0; bj < 2; ++bj) { const f32x4 v0 = acc[ai][bj][m][0] * rs, v1 = acc[ai][bj][m][1] * rs; u32x4 w;
;                         w.x = cvt_pk_bf16(gelu_tanh(v0[0]), gelu_tanh(v0[1])); w.y = cvt_pk_bf16(gelu_tanh(v0[2]), gelu_tanh(v0[3]));
;                         w.z = cvt_pk_bf16(gelu_tanh(v1[0]), gelu_tanh(v1[1])); w.w = cvt_pk_bf16(gelu_tanh(v1[2]), gelu_tanh(v1[3]));
;                         *(u32x4*)(rowp + bj * HALF) = w; }
;                 } else {
;                     bf16_t* rowp = Gb + (size_t)row * 512 + (u.pn - 4) * 128 + wc * 32 + 8 * fq;
;                     const f32x4 a0 = acc[ai][0][m][0] * rs, a1 = acc[ai][0][m][1] * rs, g0 = acc[ai][1][m][0] * rs, g1 = acc[ai][1][m][1] * rs; u32x4 w;
;                     w.x = cvt_pk_bf16(a0[0] * sigmoidf_(g0[0]), a0[1] * sigmoidf_(g0[1])); w.y = cvt_pk_bf16(a0[2] * sigmoidf_(g0[2]), a0[3] * sigmoidf_(g0[3]));
;                     w.z = cvt_pk_bf16(a1[0] * sigmoidf_(g1[0]), a1[1] * sigmoidf_(g1[1])); w.w = cvt_pk_bf16(a1[2] * sigmoidf_(g1[2]), a1[3] * sigmoidf_(g1[3]));
;                     *(u32x4*)rowp = w;
.LBB0_280:
	ds_read_b32 v82, v151 offset:192
	s_nop 0
	v_or_b32_e32 v80, 48, v144
	v_ashrrev_i32_e32 v81, 31, v80
	s_and_b64 vcc, exec, s[0:1]
	s_mov_b64 s[16:17], -1
	s_cbranch_vccnz .LBB0_282
	v_lshlrev_b64 v[84:85], 10, v[80:81]
	v_lshl_add_u64 v[84:85], s[42:43], 0, v[84:85]
	s_lshl_b32 s14, s10, 8
	v_lshl_add_u64 v[84:85], v[84:85], 0, s[14:15]
	s_lshl_b32 s14, s58, 1
	v_lshl_add_u64 v[84:85], v[84:85], 0, s[14:15]
	v_mov_b32_e32 v143, v177
	s_waitcnt lgkmcnt(0)
	v_pk_mul_f32 v[96:97], v[68:69], v[82:83] op_sel_hi:[1,0]
	v_lshl_add_u64 v[88:89], v[84:85], 0, v[142:143]
	v_pk_mul_f32 v[86:87], v[78:79], v[82:83] op_sel_hi:[1,0]
	v_pk_mul_f32 v[84:85], v[76:77], v[82:83] op_sel_hi:[1,0]
	v_pk_mul_f32 v[90:91], v[74:75], v[82:83] op_sel_hi:[1,0]
	v_pk_mul_f32 v[92:93], v[72:73], v[82:83] op_sel_hi:[1,0]
	v_pk_mul_f32 v[94:95], v[70:71], v[82:83] op_sel_hi:[1,0]
	v_pk_mul_f32 v[98:99], v[66:67], v[82:83] op_sel_hi:[1,0]
	v_mul_f32_e32 v83, 0xbfb8aa3b, v96
	v_mul_f32_e32 v96, 0xbfb8aa3b, v97
	v_exp_f32_e32 v83, v83
	v_exp_f32_e32 v100, v96
	v_mul_f32_e32 v94, 0xbfb8aa3b, v94
	v_exp_f32_e32 v94, v94
	v_pk_mul_f32 v[96:97], v[64:65], v[82:83] op_sel_hi:[1,0]
	v_add_f32_e32 v83, 1.0, v83
	v_add_f32_e32 v100, 1.0, v100
	v_rcp_f32_e32 v83, v83
	v_rcp_f32_e32 v100, v100
	v_add_co_u32_e32 v88, vcc, 0xfffffc00, v88
	v_mul_f32_e32 v83, v84, v83
	v_mul_f32_e32 v84, v85, v100
	v_mul_f32_e32 v85, 0xbfb8aa3b, v95
	v_cvt_pk_bf16_f32 v84, v83, v84
	v_add_f32_e32 v83, 1.0, v94
	v_exp_f32_e32 v85, v85
	v_mul_f32_e32 v94, 0xbfb8aa3b, v96
	v_rcp_f32_e32 v83, v83
	v_exp_f32_e32 v94, v94
	v_add_f32_e32 v85, 1.0, v85
	v_rcp_f32_e32 v85, v85
	v_mul_f32_e32 v83, v86, v83
	v_add_f32_e32 v86, 1.0, v94
	v_rcp_f32_e32 v86, v86
	v_mul_f32_e32 v94, 0xbfb8aa3b, v97
	v_mul_f32_e32 v85, v87, v85
	v_exp_f32_e32 v94, v94
	v_cvt_pk_bf16_f32 v85, v83, v85
	v_mul_f32_e32 v83, v92, v86
	v_mul_f32_e32 v87, 0xbfb8aa3b, v98
	v_mul_f32_e32 v92, 0xbfb8aa3b, v99
	v_exp_f32_e32 v87, v87
	v_exp_f32_e32 v92, v92
	v_add_f32_e32 v86, 1.0, v94
	v_rcp_f32_e32 v86, v86
	v_add_f32_e32 v87, 1.0, v87
	v_add_f32_e32 v92, 1.0, v92
	v_rcp_f32_e32 v87, v87
	v_rcp_f32_e32 v92, v92
	v_mul_f32_e32 v86, v93, v86
	v_cvt_pk_bf16_f32 v86, v83, v86
	v_mul_f32_e32 v83, v90, v87
	v_mul_f32_e32 v87, v91, v92
	v_addc_co_u32_e32 v89, vcc, -1, v89, vcc
	s_mov_b64 s[16:17], 0
	v_cvt_pk_bf16_f32 v87, v83, v87
	flat_store_dwordx4 v[88:89], v[84:87] sc1
.LBB0_282:
	s_andn2_b64 vcc, exec, s[16:17]
	s_cbranch_vccnz .LBB0_284
	s_waitcnt lgkmcnt(0)
	v_pk_mul_f32 v[76:77], v[76:77], v[82:83] op_sel_hi:[1,0]
	v_pk_mul_f32 v[84:85], v[74:75], v[82:83] op_sel_hi:[1,0]
	v_pk_mul_f32 v[74:75], v[72:73], v[82:83] op_sel_hi:[1,0]
	v_mul_f32_e32 v72, 0x3d372713, v76
	v_mul_f32_e32 v73, 0x3d372713, v77
	v_mul_f32_e32 v72, v76, v72
	v_mul_f32_e32 v73, v77, v73
	v_fma_f32 v72, v76, v72, v76
	v_fma_f32 v73, v77, v73, v77
	v_mul_f32_e32 v72, 0x3f4c422a, v72
	v_mul_f32_e32 v73, 0x3f4c422a, v73
	v_mul_f32_e32 v72, 0xc038aa3b, v72
	v_mul_f32_e32 v73, 0xc038aa3b, v73
	v_exp_f32_e32 v72, v72
	v_exp_f32_e32 v73, v73
	v_pk_mul_f32 v[78:79], v[78:79], v[82:83] op_sel_hi:[1,0]
	v_lshlrev_b64 v[80:81], 11, v[80:81]
	v_add_f32_e32 v72, 1.0, v72
	v_add_f32_e32 v73, 1.0, v73
	v_rcp_f32_e32 v72, v72
	v_rcp_f32_e32 v73, v73
	s_lshl_b32 s16, s10, 8
	v_lshl_add_u64 v[80:81], s[40:41], 0, v[80:81]
	v_mul_f32_e32 v72, v76, v72
	v_mul_f32_e32 v73, v77, v73
	v_cvt_pk_bf16_f32 v72, v72, v73
	v_mul_f32_e32 v73, 0x3d372713, v78
	v_mul_f32_e32 v76, 0x3d372713, v79
	v_mul_f32_e32 v73, v78, v73
	v_mul_f32_e32 v76, v79, v76
	v_fma_f32 v73, v78, v73, v78
	v_fma_f32 v76, v79, v76, v79
	v_mul_f32_e32 v73, 0x3f4c422a, v73
	v_mul_f32_e32 v76, 0x3f4c422a, v76
	v_mul_f32_e32 v73, 0xc038aa3b, v73
	v_mul_f32_e32 v76, 0xc038aa3b, v76
	v_exp_f32_e32 v73, v73
	v_exp_f32_e32 v76, v76
	s_ashr_i32 s17, s16, 31
	v_lshl_add_u64 v[80:81], s[16:17], 1, v[80:81]
	v_add_f32_e32 v73, 1.0, v73
	v_add_f32_e32 v76, 1.0, v76
	v_rcp_f32_e32 v73, v73
	v_rcp_f32_e32 v76, v76
	s_lshl_b32 s14, s58, 1
	v_lshl_add_u64 v[80:81], v[80:81], 0, s[14:15]
	v_mul_f32_e32 v73, v78, v73
	v_mul_f32_e32 v76, v79, v76
	v_cvt_pk_bf16_f32 v73, v73, v76
	v_mul_f32_e32 v76, 0x3d372713, v74
	v_mul_f32_e32 v76, v74, v76
	v_fma_f32 v76, v74, v76, v74
	v_mul_f32_e32 v76, 0x3f4c422a, v76
	v_mul_f32_e32 v76, 0xc038aa3b, v76
	v_exp_f32_e32 v76, v76
	v_mov_b32_e32 v143, v177
	v_lshl_add_u64 v[80:81], v[80:81], 0, v[142:143]
	v_pk_mul_f32 v[68:69], v[68:69], v[82:83] op_sel_hi:[1,0]
	v_add_f32_e32 v76, 1.0, v76
	v_rcp_f32_e32 v76, v76
	v_pk_mul_f32 v[70:71], v[70:71], v[82:83] op_sel_hi:[1,0]
	v_mul_f32_e32 v74, v74, v76
	v_mul_f32_e32 v76, 0x3d372713, v75
	v_mul_f32_e32 v76, v75, v76
	v_fma_f32 v76, v75, v76, v75
	v_mul_f32_e32 v76, 0x3f4c422a, v76
	v_mul_f32_e32 v76, 0xc038aa3b, v76
	v_exp_f32_e32 v76, v76
	s_nop 0
	v_add_f32_e32 v76, 1.0, v76
	v_rcp_f32_e32 v76, v76
	s_nop 0
	v_mul_f32_e32 v75, v75, v76
	v_cvt_pk_bf16_f32 v74, v74, v75
	v_mul_f32_e32 v75, 0x3d372713, v84
	v_mul_f32_e32 v75, v84, v75
	v_mul_f32_e32 v76, 0x3d372713, v85
	v_fma_f32 v75, v84, v75, v84
	v_mul_f32_e32 v76, v85, v76
	v_mul_f32_e32 v75, 0x3f4c422a, v75
	v_fma_f32 v76, v85, v76, v85
	v_mul_f32_e32 v75, 0xc038aa3b, v75
	v_mul_f32_e32 v76, 0x3f4c422a, v76
	v_exp_f32_e32 v75, v75
	v_mul_f32_e32 v76, 0xc038aa3b, v76
	v_exp_f32_e32 v76, v76
	v_add_f32_e32 v75, 1.0, v75
	v_rcp_f32_e32 v75, v75
	v_add_f32_e32 v76, 1.0, v76
	v_rcp_f32_e32 v76, v76
	v_mul_f32_e32 v75, v84, v75
	v_mul_f32_e32 v76, v85, v76
	v_cvt_pk_bf16_f32 v75, v75, v76
	flat_store_dwordx4 v[80:81], v[72:75] sc1
	s_nop 1
	v_pk_mul_f32 v[72:73], v[66:67], v[82:83] op_sel_hi:[1,0]
; __device__ __forceinline__ unsigned cvt_pk_bf16(float lo, float hi) { unsigned r; asm volatile("v_cvt_pk_bf16_f32 %0, %1, %2" : "=v"(r) : "v"(lo), "v"(hi)); return r; }
; __device__ __forceinline__ float sigmoidf_(float x) { return __builtin_amdgcn_rcpf(1.0f + __builtin_amdgcn_exp2f(-1.4426950408889634f * x)); }
;     __device__ __forceinline__ void operator()(const f32x4 (&acc)[2][2][4][2], const Unit& u, int wr, int wc, int fr, int fq) const {
;     ...
;                 const int row = row0 + ai * HALF + m * 16; const float rs = tb[ai * 64 + m * 16 + fr];
;                 if (u.pn < 4) {
;                     bf16_t* rowp = UV + (size_t)row * 1024 + u.pn * BM + wc * 32 + 8 * fq;
; #pragma unroll
;                     for (int bj = 0; bj < 2; ++bj) { const f32x4 v0 = acc[ai][bj][m][0] * rs, v1 = acc[ai][bj][m][1] * rs; u32x4 w;
;                         w.x = cvt_pk_bf16(gelu_tanh(v0[0]), gelu_tanh(v0[1])); w.y = cvt_pk_bf16(gelu_tanh(v0[2]), gelu_tanh(v0[3]));
;                         w.z = cvt_pk_bf16(gelu_tanh(v1[0]), gelu_tanh(v1[1])); w.w = cvt_pk_bf16(gelu_tanh(v1[2]), gelu_tanh(v1[3]));
;                         *(u32x4*)(rowp + bj * HALF) = w; }
;                 } else {
;                     bf16_t* rowp = Gb + (size_t)row * 512 + (u.pn - 4) * 128 + wc * 32 + 8 * fq;
;                     const f32x4 a0 = acc[ai][0][m][0] * rs, a1 = acc[ai][0][m][1] * rs, g0 = acc[ai][1][m][0] * rs, g1 = acc[ai][1][m][1] * rs; u32x4 w;
;                     w.x = cvt_pk_bf16(a0[0] * sigmoidf_(g0[0]), a0[1] * sigmoidf_(g0[1])); w.y = cvt_pk_bf16(a0[2] * sigmoidf_(g0[2]), a0[3] * sigmoidf_(g0[3]));
;                     w.z = cvt_pk_bf16(a1[0] * sigmoidf_(g1[0]), a1[1] * sigmoidf_(g1[1])); w.w = cvt_pk_bf16(a1[2] * sigmoidf_(g1[2]), a1[3] * sigmoidf_(g1[3]));
;                     *(u32x4*)rowp = w;
	v_pk_mul_f32 v[66:67], v[64:65], v[82:83] op_sel_hi:[1,0]
	v_mul_f32_e32 v64, 0x3d372713, v68
	v_mul_f32_e32 v65, 0x3d372713, v69
	v_mul_f32_e32 v64, v68, v64
	v_mul_f32_e32 v65, v69, v65
	v_fma_f32 v64, v68, v64, v68
	v_fma_f32 v65, v69, v65, v69
	v_mul_f32_e32 v64, 0x3f4c422a, v64
	v_mul_f32_e32 v65, 0x3f4c422a, v65
	v_mul_f32_e32 v64, 0xc038aa3b, v64
	v_mul_f32_e32 v65, 0xc038aa3b, v65
	v_exp_f32_e32 v64, v64
	v_exp_f32_e32 v65, v65
	v_add_f32_e32 v64, 1.0, v64
	v_add_f32_e32 v65, 1.0, v65
	v_rcp_f32_e32 v64, v64
	v_rcp_f32_e32 v65, v65
	v_mul_f32_e32 v64, v68, v64
	v_mul_f32_e32 v65, v69, v65
	v_cvt_pk_bf16_f32 v64, v64, v65
	v_mul_f32_e32 v65, 0x3d372713, v70
	v_mul_f32_e32 v68, 0x3d372713, v71
	v_mul_f32_e32 v65, v70, v65
	v_mul_f32_e32 v68, v71, v68
	v_fma_f32 v65, v70, v65, v70
	v_fma_f32 v68, v71, v68, v71
	v_mul_f32_e32 v65, 0x3f4c422a, v65
	v_mul_f32_e32 v68, 0x3f4c422a, v68
	v_mul_f32_e32 v65, 0xc038aa3b, v65
	v_mul_f32_e32 v68, 0xc038aa3b, v68
	v_exp_f32_e32 v65, v65
	v_exp_f32_e32 v68, v68
	v_add_f32_e32 v65, 1.0, v65
	v_add_f32_e32 v68, 1.0, v68
	v_rcp_f32_e32 v65, v65
	v_rcp_f32_e32 v68, v68
	v_mul_f32_e32 v65, v70, v65
	v_mul_f32_e32 v68, v71, v68
	v_cvt_pk_bf16_f32 v65, v65, v68
	v_mul_f32_e32 v68, 0x3d372713, v66
	v_mul_f32_e32 v68, v66, v68
	v_fma_f32 v68, v66, v68, v66
	v_mul_f32_e32 v68, 0x3f4c422a, v68
	v_mul_f32_e32 v68, 0xc038aa3b, v68
	v_exp_f32_e32 v68, v68
	s_nop 0
	v_add_f32_e32 v68, 1.0, v68
	v_rcp_f32_e32 v68, v68
	s_nop 0
	v_mul_f32_e32 v66, v66, v68
	v_mul_f32_e32 v68, 0x3d372713, v67
	v_mul_f32_e32 v68, v67, v68
	v_fma_f32 v68, v67, v68, v67
	v_mul_f32_e32 v68, 0x3f4c422a, v68
	v_mul_f32_e32 v68, 0xc038aa3b, v68
	v_exp_f32_e32 v68, v68
	s_nop 0
	v_add_f32_e32 v68, 1.0, v68
	v_rcp_f32_e32 v68, v68
	s_nop 0
	v_mul_f32_e32 v67, v67, v68
	v_cvt_pk_bf16_f32 v66, v66, v67
	v_mul_f32_e32 v67, 0x3d372713, v72
	v_mul_f32_e32 v67, v72, v67
	v_mul_f32_e32 v68, 0x3d372713, v73
	v_fma_f32 v67, v72, v67, v72
	v_mul_f32_e32 v68, v73, v68
	v_mul_f32_e32 v67, 0x3f4c422a, v67
	v_fma_f32 v68, v73, v68, v73
	v_mul_f32_e32 v67, 0xc038aa3b, v67
	v_mul_f32_e32 v68, 0x3f4c422a, v68
	v_exp_f32_e32 v67, v67
	v_mul_f32_e32 v68, 0xc038aa3b, v68
	v_exp_f32_e32 v68, v68
	v_add_f32_e32 v67, 1.0, v67
	v_rcp_f32_e32 v67, v67
	v_add_f32_e32 v68, 1.0, v68
	v_rcp_f32_e32 v68, v68
	v_mul_f32_e32 v67, v72, v67
	v_mul_f32_e32 v68, v73, v68
	v_cvt_pk_bf16_f32 v67, v67, v68
	flat_store_dwordx4 v[80:81], v[64:67] offset:256 sc1
.LBB0_284:
	ds_read_b32 v66, v151 offset:256
	s_nop 0
	v_add_u32_e32 v64, 0x80, v144
	v_ashrrev_i32_e32 v65, 31, v64
	s_and_b64 vcc, exec, s[0:1]
	s_mov_b64 s[16:17], -1
	s_cbranch_vccnz .LBB0_286
	v_lshlrev_b64 v[68:69], 10, v[64:65]
	v_lshl_add_u64 v[68:69], s[42:43], 0, v[68:69]
	s_lshl_b32 s14, s10, 8
	v_lshl_add_u64 v[68:69], v[68:69], 0, s[14:15]
	s_lshl_b32 s14, s58, 1
	v_lshl_add_u64 v[68:69], v[68:69], 0, s[14:15]
	v_mov_b32_e32 v143, v177
	s_waitcnt lgkmcnt(0)
	v_pk_mul_f32 v[80:81], v[52:53], v[66:67] op_sel_hi:[1,0]
	v_lshl_add_u64 v[72:73], v[68:69], 0, v[142:143]
	v_pk_mul_f32 v[70:71], v[62:63], v[66:67] op_sel_hi:[1,0]
	v_pk_mul_f32 v[68:69], v[60:61], v[66:67] op_sel_hi:[1,0]
	v_pk_mul_f32 v[74:75], v[58:59], v[66:67] op_sel_hi:[1,0]
	v_pk_mul_f32 v[76:77], v[56:57], v[66:67] op_sel_hi:[1,0]
	v_pk_mul_f32 v[78:79], v[54:55], v[66:67] op_sel_hi:[1,0]
	v_pk_mul_f32 v[82:83], v[50:51], v[66:67] op_sel_hi:[1,0]
	v_mul_f32_e32 v67, 0xbfb8aa3b, v80
	v_mul_f32_e32 v80, 0xbfb8aa3b, v81
	v_exp_f32_e32 v67, v67
	v_exp_f32_e32 v84, v80
	v_mul_f32_e32 v78, 0xbfb8aa3b, v78
	v_exp_f32_e32 v78, v78
	v_pk_mul_f32 v[80:81], v[48:49], v[66:67] op_sel_hi:[1,0]
	v_add_f32_e32 v67, 1.0, v67
	v_add_f32_e32 v84, 1.0, v84
	v_rcp_f32_e32 v67, v67
	v_rcp_f32_e32 v84, v84
	v_add_co_u32_e32 v72, vcc, 0xfffffc00, v72
	v_mul_f32_e32 v67, v68, v67
	v_mul_f32_e32 v68, v69, v84
	v_mul_f32_e32 v69, 0xbfb8aa3b, v79
	v_cvt_pk_bf16_f32 v68, v67, v68
	v_add_f32_e32 v67, 1.0, v78
	v_exp_f32_e32 v69, v69
	v_mul_f32_e32 v78, 0xbfb8aa3b, v80
	v_rcp_f32_e32 v67, v67
	v_exp_f32_e32 v78, v78
	v_add_f32_e32 v69, 1.0, v69
	v_rcp_f32_e32 v69, v69
	v_mul_f32_e32 v67, v70, v67
	v_add_f32_e32 v70, 1.0, v78
	v_rcp_f32_e32 v70, v70
	v_mul_f32_e32 v78, 0xbfb8aa3b, v81
	v_mul_f32_e32 v69, v71, v69
	v_exp_f32_e32 v78, v78
	v_cvt_pk_bf16_f32 v69, v67, v69
	v_mul_f32_e32 v67, v76, v70
	v_mul_f32_e32 v71, 0xbfb8aa3b, v82
	v_mul_f32_e32 v76, 0xbfb8aa3b, v83
	v_exp_f32_e32 v71, v71
	v_exp_f32_e32 v76, v76
	v_add_f32_e32 v70, 1.0, v78
	v_rcp_f32_e32 v70, v70
	v_add_f32_e32 v71, 1.0, v71
	v_add_f32_e32 v76, 1.0, v76
	v_rcp_f32_e32 v71, v71
	v_rcp_f32_e32 v76, v76
	v_mul_f32_e32 v70, v77, v70
	v_cvt_pk_bf16_f32 v70, v67, v70
	v_mul_f32_e32 v67, v74, v71
	v_mul_f32_e32 v71, v75, v76
	v_addc_co_u32_e32 v73, vcc, -1, v73, vcc
	s_mov_b64 s[16:17], 0
	v_cvt_pk_bf16_f32 v71, v67, v71
	flat_store_dwordx4 v[72:73], v[68:71] sc1
; __device__ __forceinline__ unsigned cvt_pk_bf16(float lo, float hi) { unsigned r; asm volatile("v_cvt_pk_bf16_f32 %0, %1, %2" : "=v"(r) : "v"(lo), "v"(hi)); return r; }
;     __device__ __forceinline__ void operator()(const f32x4 (&acc)[2][2][4][2], const Unit& u, int wr, int wc, int fr, int fq) const {
;     ...
;                 const int row = row0 + ai * HALF + m * 16; const float rs = tb[ai * 64 + m * 16 + fr];
;                 if (u.pn < 4) {
;                     bf16_t* rowp = UV + (size_t)row * 1024 + u.pn * BM + wc * 32 + 8 * fq;
; #pragma unroll
;                     for (int bj = 0; bj < 2; ++bj) { const f32x4 v0 = acc[ai][bj][m][0] * rs, v1 = acc[ai][bj][m][1] * rs; u32x4 w;
;                         w.x = cvt_pk_bf16(gelu_tanh(v0[0]), gelu_tanh(v0[1])); w.y = cvt_pk_bf16(gelu_tanh(v0[2]), gelu_tanh(v0[3]));
;                         w.z = cvt_pk_bf16(gelu_tanh(v1[0]), gelu_tanh(v1[1])); w.w = cvt_pk_bf16(gelu_tanh(v1[2]), gelu_tanh(v1[3]));
;                         *(u32x4*)(rowp + bj * HALF) = w; }
.LBB0_286:
	s_andn2_b64 vcc, exec, s[16:17]
	s_cbranch_vccnz .LBB0_288
	s_waitcnt lgkmcnt(0)
	v_pk_mul_f32 v[60:61], v[60:61], v[66:67] op_sel_hi:[1,0]
	v_pk_mul_f32 v[68:69], v[58:59], v[66:67] op_sel_hi:[1,0]
	v_pk_mul_f32 v[58:59], v[56:57], v[66:67] op_sel_hi:[1,0]
	v_mul_f32_e32 v56, 0x3d372713, v60
	v_mul_f32_e32 v57, 0x3d372713, v61
	v_mul_f32_e32 v56, v60, v56
	v_mul_f32_e32 v57, v61, v57
	v_fma_f32 v56, v60, v56, v60
	v_fma_f32 v57, v61, v57, v61
	v_mul_f32_e32 v56, 0x3f4c422a, v56
	v_mul_f32_e32 v57, 0x3f4c422a, v57
	v_mul_f32_e32 v56, 0xc038aa3b, v56
	v_mul_f32_e32 v57, 0xc038aa3b, v57
	v_exp_f32_e32 v56, v56
	v_exp_f32_e32 v57, v57
	v_pk_mul_f32 v[62:63], v[62:63], v[66:67] op_sel_hi:[1,0]
	v_lshlrev_b64 v[64:65], 11, v[64:65]
	v_add_f32_e32 v56, 1.0, v56
	v_add_f32_e32 v57, 1.0, v57
	v_rcp_f32_e32 v56, v56
	v_rcp_f32_e32 v57, v57
	s_lshl_b32 s16, s10, 8
	v_lshl_add_u64 v[64:65], s[40:41], 0, v[64:65]
	v_mul_f32_e32 v56, v60, v56
	v_mul_f32_e32 v57, v61, v57
	v_cvt_pk_bf16_f32 v56, v56, v57
	v_mul_f32_e32 v57, 0x3d372713, v62
	v_mul_f32_e32 v60, 0x3d372713, v63
	v_mul_f32_e32 v57, v62, v57
	v_mul_f32_e32 v60, v63, v60
	v_fma_f32 v57, v62, v57, v62
	v_fma_f32 v60, v63, v60, v63
	v_mul_f32_e32 v57, 0x3f4c422a, v57
	v_mul_f32_e32 v60, 0x3f4c422a, v60
	v_mul_f32_e32 v57, 0xc038aa3b, v57
	v_mul_f32_e32 v60, 0xc038aa3b, v60
	v_exp_f32_e32 v57, v57
	v_exp_f32_e32 v60, v60
	s_ashr_i32 s17, s16, 31
	v_lshl_add_u64 v[64:65], s[16:17], 1, v[64:65]
	v_add_f32_e32 v57, 1.0, v57
	v_add_f32_e32 v60, 1.0, v60
	v_rcp_f32_e32 v57, v57
	v_rcp_f32_e32 v60, v60
	s_lshl_b32 s14, s58, 1
	v_lshl_add_u64 v[64:65], v[64:65], 0, s[14:15]
	v_mul_f32_e32 v57, v62, v57
	v_mul_f32_e32 v60, v63, v60
	v_cvt_pk_bf16_f32 v57, v57, v60
	v_mul_f32_e32 v60, 0x3d372713, v58
	v_mul_f32_e32 v60, v58, v60
	v_fma_f32 v60, v58, v60, v58
	v_mul_f32_e32 v60, 0x3f4c422a, v60
	v_mul_f32_e32 v60, 0xc038aa3b, v60
	v_exp_f32_e32 v60, v60
	v_mov_b32_e32 v143, v177
	v_lshl_add_u64 v[64:65], v[64:65], 0, v[142:143]
	v_pk_mul_f32 v[52:53], v[52:53], v[66:67] op_sel_hi:[1,0]
	v_add_f32_e32 v60, 1.0, v60
	v_rcp_f32_e32 v60, v60
	v_pk_mul_f32 v[54:55], v[54:55], v[66:67] op_sel_hi:[1,0]
	v_mul_f32_e32 v58, v58, v60
	v_mul_f32_e32 v60, 0x3d372713, v59
	v_mul_f32_e32 v60, v59, v60
	v_fma_f32 v60, v59, v60, v59
	v_mul_f32_e32 v60, 0x3f4c422a, v60
	v_mul_f32_e32 v60, 0xc038aa3b, v60
	v_exp_f32_e32 v60, v60
	s_nop 0
	v_add_f32_e32 v60, 1.0, v60
	v_rcp_f32_e32 v60, v60
	s_nop 0
	v_mul_f32_e32 v59, v59, v60
	v_cvt_pk_bf16_f32 v58, v58, v59
	v_mul_f32_e32 v59, 0x3d372713, v68
	v_mul_f32_e32 v59, v68, v59
	v_mul_f32_e32 v60, 0x3d372713, v69
	v_fma_f32 v59, v68, v59, v68
	v_mul_f32_e32 v60, v69, v60
	v_mul_f32_e32 v59, 0x3f4c422a, v59
	v_fma_f32 v60, v69, v60, v69
	v_mul_f32_e32 v59, 0xc038aa3b, v59
	v_mul_f32_e32 v60, 0x3f4c422a, v60
	v_exp_f32_e32 v59, v59
	v_mul_f32_e32 v60, 0xc038aa3b, v60
	v_exp_f32_e32 v60, v60
	v_add_f32_e32 v59, 1.0, v59
	v_rcp_f32_e32 v59, v59
	v_add_f32_e32 v60, 1.0, v60
	v_rcp_f32_e32 v60, v60
	v_mul_f32_e32 v59, v68, v59
	v_mul_f32_e32 v60, v69, v60
	v_cvt_pk_bf16_f32 v59, v59, v60
	flat_store_dwordx4 v[64:65], v[56:59] sc1
	s_nop 1
	v_pk_mul_f32 v[56:57], v[50:51], v[66:67] op_sel_hi:[1,0]
	v_pk_mul_f32 v[50:51], v[48:49], v[66:67] op_sel_hi:[1,0]
	v_mul_f32_e32 v48, 0x3d372713, v52
	v_mul_f32_e32 v49, 0x3d372713, v53
	v_mul_f32_e32 v48, v52, v48
	v_mul_f32_e32 v49, v53, v49
	v_fma_f32 v48, v52, v48, v52
	v_fma_f32 v49, v53, v49, v53
	v_mul_f32_e32 v48, 0x3f4c422a, v48
	v_mul_f32_e32 v49, 0x3f4c422a, v49
	v_mul_f32_e32 v48, 0xc038aa3b, v48
	v_mul_f32_e32 v49, 0xc038aa3b, v49
	v_exp_f32_e32 v48, v48
	v_exp_f32_e32 v49, v49
	v_add_f32_e32 v48, 1.0, v48
	v_add_f32_e32 v49, 1.0, v49
	v_rcp_f32_e32 v48, v48
	v_rcp_f32_e32 v49, v49
	v_mul_f32_e32 v48, v52, v48
	v_mul_f32_e32 v49, v53, v49
	v_cvt_pk_bf16_f32 v48, v48, v49
	v_mul_f32_e32 v49, 0x3d372713, v54
	v_mul_f32_e32 v52, 0x3d372713, v55
	v_mul_f32_e32 v49, v54, v49
	v_mul_f32_e32 v52, v55, v52
	v_fma_f32 v49, v54, v49, v54
	v_fma_f32 v52, v55, v52, v55
	v_mul_f32_e32 v49, 0x3f4c422a, v49
	v_mul_f32_e32 v52, 0x3f4c422a, v52
	v_mul_f32_e32 v49, 0xc038aa3b, v49
	v_mul_f32_e32 v52, 0xc038aa3b, v52
	v_exp_f32_e32 v49, v49
	v_exp_f32_e32 v52, v52
	v_add_f32_e32 v49, 1.0, v49
	v_add_f32_e32 v52, 1.0, v52
	v_rcp_f32_e32 v49, v49
	v_rcp_f32_e32 v52, v52
	v_mul_f32_e32 v49, v54, v49
	v_mul_f32_e32 v52, v55, v52
	v_cvt_pk_bf16_f32 v49, v49, v52
	v_mul_f32_e32 v52, 0x3d372713, v50
	v_mul_f32_e32 v52, v50, v52
	v_fma_f32 v52, v50, v52, v50
	v_mul_f32_e32 v52, 0x3f4c422a, v52
	v_mul_f32_e32 v52, 0xc038aa3b, v52
	v_exp_f32_e32 v52, v52
	s_nop 0
	v_add_f32_e32 v52, 1.0, v52
	v_rcp_f32_e32 v52, v52
	s_nop 0
	v_mul_f32_e32 v50, v50, v52
	v_mul_f32_e32 v52, 0x3d372713, v51
	v_mul_f32_e32 v52, v51, v52
	v_fma_f32 v52, v51, v52, v51
	v_mul_f32_e32 v52, 0x3f4c422a, v52
	v_mul_f32_e32 v52, 0xc038aa3b, v52
	v_exp_f32_e32 v52, v52
	s_nop 0
	v_add_f32_e32 v52, 1.0, v52
	v_rcp_f32_e32 v52, v52
	s_nop 0
	v_mul_f32_e32 v51, v51, v52
	v_cvt_pk_bf16_f32 v50, v50, v51
	v_mul_f32_e32 v51, 0x3d372713, v56
	v_mul_f32_e32 v51, v56, v51
	v_mul_f32_e32 v52, 0x3d372713, v57
	v_fma_f32 v51, v56, v51, v56
	v_mul_f32_e32 v52, v57, v52
	v_mul_f32_e32 v51, 0x3f4c422a, v51
	v_fma_f32 v52, v57, v52, v57
	v_mul_f32_e32 v51, 0xc038aa3b, v51
	v_mul_f32_e32 v52, 0x3f4c422a, v52
	v_exp_f32_e32 v51, v51
	v_mul_f32_e32 v52, 0xc038aa3b, v52
	v_exp_f32_e32 v52, v52
	v_add_f32_e32 v51, 1.0, v51
	v_rcp_f32_e32 v51, v51
	v_add_f32_e32 v52, 1.0, v52
	v_rcp_f32_e32 v52, v52
	v_mul_f32_e32 v51, v56, v51
	v_mul_f32_e32 v52, v57, v52
	v_cvt_pk_bf16_f32 v51, v51, v52
	flat_store_dwordx4 v[64:65], v[48:51] offset:256 sc1
; __device__ __forceinline__ unsigned cvt_pk_bf16(float lo, float hi) { unsigned r; asm volatile("v_cvt_pk_bf16_f32 %0, %1, %2" : "=v"(r) : "v"(lo), "v"(hi)); return r; }
; __device__ __forceinline__ float sigmoidf_(float x) { return __builtin_amdgcn_rcpf(1.0f + __builtin_amdgcn_exp2f(-1.4426950408889634f * x)); }
;     __device__ __forceinline__ void operator()(const f32x4 (&acc)[2][2][4][2], const Unit& u, int wr, int wc, int fr, int fq) const {
;     ...
;                 const int row = row0 + ai * HALF + m * 16; const float rs = tb[ai * 64 + m * 16 + fr];
;                 if (u.pn < 4) {
;                     bf16_t* rowp = UV + (size_t)row * 1024 + u.pn * BM + wc * 32 + 8 * fq;
; #pragma unroll
;                     for (int bj = 0; bj < 2; ++bj) { const f32x4 v0 = acc[ai][bj][m][0] * rs, v1 = acc[ai][bj][m][1] * rs; u32x4 w;
;                         w.x = cvt_pk_bf16(gelu_tanh(v0[0]), gelu_tanh(v0[1])); w.y = cvt_pk_bf16(gelu_tanh(v0[2]), gelu_tanh(v0[3]));
;                         w.z = cvt_pk_bf16(gelu_tanh(v1[0]), gelu_tanh(v1[1])); w.w = cvt_pk_bf16(gelu_tanh(v1[2]), gelu_tanh(v1[3]));
;                         *(u32x4*)(rowp + bj * HALF) = w; }
;                 } else {
;                     bf16_t* rowp = Gb + (size_t)row * 512 + (u.pn - 4) * 128 + wc * 32 + 8 * fq;
;                     const f32x4 a0 = acc[ai][0][m][0] * rs, a1 = acc[ai][0][m][1] * rs, g0 = acc[ai][1][m][0] * rs, g1 = acc[ai][1][m][1] * rs; u32x4 w;
;                     w.x = cvt_pk_bf16(a0[0] * sigmoidf_(g0[0]), a0[1] * sigmoidf_(g0[1])); w.y = cvt_pk_bf16(a0[2] * sigmoidf_(g0[2]), a0[3] * sigmoidf_(g0[3]));
;                     w.z = cvt_pk_bf16(a1[0] * sigmoidf_(g1[0]), a1[1] * sigmoidf_(g1[1])); w.w = cvt_pk_bf16(a1[2] * sigmoidf_(g1[2]), a1[3] * sigmoidf_(g1[3]));
;                     *(u32x4*)rowp = w;
.LBB0_288:
	ds_read_b32 v50, v151 offset:320
	s_nop 0
	v_add_u32_e32 v48, 0x90, v144
	v_ashrrev_i32_e32 v49, 31, v48
	s_and_b64 vcc, exec, s[0:1]
	s_mov_b64 s[16:17], -1
	s_cbranch_vccnz .LBB0_290
	v_lshlrev_b64 v[52:53], 10, v[48:49]
	v_lshl_add_u64 v[52:53], s[42:43], 0, v[52:53]
	s_lshl_b32 s14, s10, 8
	v_lshl_add_u64 v[52:53], v[52:53], 0, s[14:15]
	s_lshl_b32 s14, s58, 1
	v_lshl_add_u64 v[52:53], v[52:53], 0, s[14:15]
	v_mov_b32_e32 v143, v177
	s_waitcnt lgkmcnt(0)
	v_pk_mul_f32 v[64:65], v[36:37], v[50:51] op_sel_hi:[1,0]
	v_lshl_add_u64 v[56:57], v[52:53], 0, v[142:143]
	v_pk_mul_f32 v[54:55], v[46:47], v[50:51] op_sel_hi:[1,0]
	v_pk_mul_f32 v[52:53], v[44:45], v[50:51] op_sel_hi:[1,0]
	v_pk_mul_f32 v[58:59], v[42:43], v[50:51] op_sel_hi:[1,0]
	v_pk_mul_f32 v[60:61], v[40:41], v[50:51] op_sel_hi:[1,0]
	v_pk_mul_f32 v[62:63], v[38:39], v[50:51] op_sel_hi:[1,0]
	v_pk_mul_f32 v[66:67], v[34:35], v[50:51] op_sel_hi:[1,0]
	v_mul_f32_e32 v51, 0xbfb8aa3b, v64
	v_mul_f32_e32 v64, 0xbfb8aa3b, v65
	v_exp_f32_e32 v51, v51
	v_exp_f32_e32 v68, v64
	v_mul_f32_e32 v62, 0xbfb8aa3b, v62
	v_exp_f32_e32 v62, v62
	v_pk_mul_f32 v[64:65], v[32:33], v[50:51] op_sel_hi:[1,0]
	v_add_f32_e32 v51, 1.0, v51
	v_add_f32_e32 v68, 1.0, v68
	v_rcp_f32_e32 v51, v51
	v_rcp_f32_e32 v68, v68
	v_add_co_u32_e32 v56, vcc, 0xfffffc00, v56
	v_mul_f32_e32 v51, v52, v51
	v_mul_f32_e32 v52, v53, v68
	v_mul_f32_e32 v53, 0xbfb8aa3b, v63
	v_cvt_pk_bf16_f32 v52, v51, v52
	v_add_f32_e32 v51, 1.0, v62
	v_exp_f32_e32 v53, v53
	v_mul_f32_e32 v62, 0xbfb8aa3b, v64
	v_rcp_f32_e32 v51, v51
	v_exp_f32_e32 v62, v62
	v_add_f32_e32 v53, 1.0, v53
	v_rcp_f32_e32 v53, v53
	v_mul_f32_e32 v51, v54, v51
	v_add_f32_e32 v54, 1.0, v62
	v_rcp_f32_e32 v54, v54
	v_mul_f32_e32 v62, 0xbfb8aa3b, v65
	v_mul_f32_e32 v53, v55, v53
	v_exp_f32_e32 v62, v62
	v_cvt_pk_bf16_f32 v53, v51, v53
	v_mul_f32_e32 v51, v60, v54
	v_mul_f32_e32 v55, 0xbfb8aa3b, v66
	v_mul_f32_e32 v60, 0xbfb8aa3b, v67
	v_exp_f32_e32 v55, v55
	v_exp_f32_e32 v60, v60
	v_add_f32_e32 v54, 1.0, v62
	v_rcp_f32_e32 v54, v54
	v_add_f32_e32 v55, 1.0, v55
	v_add_f32_e32 v60, 1.0, v60
	v_rcp_f32_e32 v55, v55
	v_rcp_f32_e32 v60, v60
	v_mul_f32_e32 v54, v61, v54
	v_cvt_pk_bf16_f32 v54, v51, v54
	v_mul_f32_e32 v51, v58, v55
	v_mul_f32_e32 v55, v59, v60
	v_addc_co_u32_e32 v57, vcc, -1, v57, vcc
	s_mov_b64 s[16:17], 0
	v_cvt_pk_bf16_f32 v55, v51, v55
	flat_store_dwordx4 v[56:57], v[52:55] sc1
.LBB0_290:
	s_andn2_b64 vcc, exec, s[16:17]
	s_cbranch_vccnz .LBB0_292
	s_waitcnt lgkmcnt(0)
	v_pk_mul_f32 v[44:45], v[44:45], v[50:51] op_sel_hi:[1,0]
	v_pk_mul_f32 v[52:53], v[42:43], v[50:51] op_sel_hi:[1,0]
	v_pk_mul_f32 v[42:43], v[40:41], v[50:51] op_sel_hi:[1,0]
	v_mul_f32_e32 v40, 0x3d372713, v44
	v_mul_f32_e32 v41, 0x3d372713, v45
	v_mul_f32_e32 v40, v44, v40
	v_mul_f32_e32 v41, v45, v41
	v_fma_f32 v40, v44, v40, v44
	v_fma_f32 v41, v45, v41, v45
	v_mul_f32_e32 v40, 0x3f4c422a, v40
	v_mul_f32_e32 v41, 0x3f4c422a, v41
	v_mul_f32_e32 v40, 0xc038aa3b, v40
	v_mul_f32_e32 v41, 0xc038aa3b, v41
	v_exp_f32_e32 v40, v40
	v_exp_f32_e32 v41, v41
	v_pk_mul_f32 v[46:47], v[46:47], v[50:51] op_sel_hi:[1,0]
	v_lshlrev_b64 v[48:49], 11, v[48:49]
	v_add_f32_e32 v40, 1.0, v40
	v_add_f32_e32 v41, 1.0, v41
	v_rcp_f32_e32 v40, v40
	v_rcp_f32_e32 v41, v41
	s_lshl_b32 s16, s10, 8
	v_lshl_add_u64 v[48:49], s[40:41], 0, v[48:49]
	v_mul_f32_e32 v40, v44, v40
	v_mul_f32_e32 v41, v45, v41
	v_cvt_pk_bf16_f32 v40, v40, v41
	v_mul_f32_e32 v41, 0x3d372713, v46
	v_mul_f32_e32 v44, 0x3d372713, v47
	v_mul_f32_e32 v41, v46, v41
	v_mul_f32_e32 v44, v47, v44
	v_fma_f32 v41, v46, v41, v46
	v_fma_f32 v44, v47, v44, v47
	v_mul_f32_e32 v41, 0x3f4c422a, v41
	v_mul_f32_e32 v44, 0x3f4c422a, v44
	v_mul_f32_e32 v41, 0xc038aa3b, v41
	v_mul_f32_e32 v44, 0xc038aa3b, v44
	v_exp_f32_e32 v41, v41
	v_exp_f32_e32 v44, v44
	s_ashr_i32 s17, s16, 31
	v_lshl_add_u64 v[48:49], s[16:17], 1, v[48:49]
	v_add_f32_e32 v41, 1.0, v41
	v_add_f32_e32 v44, 1.0, v44
	v_rcp_f32_e32 v41, v41
	v_rcp_f32_e32 v44, v44
	s_lshl_b32 s14, s58, 1
	v_lshl_add_u64 v[48:49], v[48:49], 0, s[14:15]
	v_mul_f32_e32 v41, v46, v41
	v_mul_f32_e32 v44, v47, v44
	v_cvt_pk_bf16_f32 v41, v41, v44
	v_mul_f32_e32 v44, 0x3d372713, v42
	v_mul_f32_e32 v44, v42, v44
	v_fma_f32 v44, v42, v44, v42
	v_mul_f32_e32 v44, 0x3f4c422a, v44
	v_mul_f32_e32 v44, 0xc038aa3b, v44
	v_exp_f32_e32 v44, v44
	v_mov_b32_e32 v143, v177
	v_lshl_add_u64 v[48:49], v[48:49], 0, v[142:143]
	v_pk_mul_f32 v[36:37], v[36:37], v[50:51] op_sel_hi:[1,0]
	v_add_f32_e32 v44, 1.0, v44
	v_rcp_f32_e32 v44, v44
	v_pk_mul_f32 v[38:39], v[38:39], v[50:51] op_sel_hi:[1,0]
	v_mul_f32_e32 v42, v42, v44
	v_mul_f32_e32 v44, 0x3d372713, v43
	v_mul_f32_e32 v44, v43, v44
	v_fma_f32 v44, v43, v44, v43
	v_mul_f32_e32 v44, 0x3f4c422a, v44
	v_mul_f32_e32 v44, 0xc038aa3b, v44
	v_exp_f32_e32 v44, v44
	s_nop 0
	v_add_f32_e32 v44, 1.0, v44
	v_rcp_f32_e32 v44, v44
	s_nop 0
	v_mul_f32_e32 v43, v43, v44
	v_cvt_pk_bf16_f32 v42, v42, v43
	v_mul_f32_e32 v43, 0x3d372713, v52
	v_mul_f32_e32 v43, v52, v43
	v_mul_f32_e32 v44, 0x3d372713, v53
	v_fma_f32 v43, v52, v43, v52
	v_mul_f32_e32 v44, v53, v44
	v_mul_f32_e32 v43, 0x3f4c422a, v43
	v_fma_f32 v44, v53, v44, v53
	v_mul_f32_e32 v43, 0xc038aa3b, v43
	v_mul_f32_e32 v44, 0x3f4c422a, v44
	v_exp_f32_e32 v43, v43
	v_mul_f32_e32 v44, 0xc038aa3b, v44
	v_exp_f32_e32 v44, v44
	v_add_f32_e32 v43, 1.0, v43
	v_rcp_f32_e32 v43, v43
	v_add_f32_e32 v44, 1.0, v44
	v_rcp_f32_e32 v44, v44
	v_mul_f32_e32 v43, v52, v43
	v_mul_f32_e32 v44, v53, v44
	v_cvt_pk_bf16_f32 v43, v43, v44
	flat_store_dwordx4 v[48:49], v[40:43] sc1
	s_nop 1
	v_pk_mul_f32 v[40:41], v[34:35], v[50:51] op_sel_hi:[1,0]
; __device__ __forceinline__ unsigned cvt_pk_bf16(float lo, float hi) { unsigned r; asm volatile("v_cvt_pk_bf16_f32 %0, %1, %2" : "=v"(r) : "v"(lo), "v"(hi)); return r; }
; __device__ __forceinline__ float sigmoidf_(float x) { return __builtin_amdgcn_rcpf(1.0f + __builtin_amdgcn_exp2f(-1.4426950408889634f * x)); }
;     __device__ __forceinline__ void operator()(const f32x4 (&acc)[2][2][4][2], const Unit& u, int wr, int wc, int fr, int fq) const {
;     ...
;                 const int row = row0 + ai * HALF + m * 16; const float rs = tb[ai * 64 + m * 16 + fr];
;                 if (u.pn < 4) {
;                     bf16_t* rowp = UV + (size_t)row * 1024 + u.pn * BM + wc * 32 + 8 * fq;
; #pragma unroll
;                     for (int bj = 0; bj < 2; ++bj) { const f32x4 v0 = acc[ai][bj][m][0] * rs, v1 = acc[ai][bj][m][1] * rs; u32x4 w;
;                         w.x = cvt_pk_bf16(gelu_tanh(v0[0]), gelu_tanh(v0[1])); w.y = cvt_pk_bf16(gelu_tanh(v0[2]), gelu_tanh(v0[3]));
;                         w.z = cvt_pk_bf16(gelu_tanh(v1[0]), gelu_tanh(v1[1])); w.w = cvt_pk_bf16(gelu_tanh(v1[2]), gelu_tanh(v1[3]));
;                         *(u32x4*)(rowp + bj * HALF) = w; }
;                 } else {
;                     bf16_t* rowp = Gb + (size_t)row * 512 + (u.pn - 4) * 128 + wc * 32 + 8 * fq;
;                     const f32x4 a0 = acc[ai][0][m][0] * rs, a1 = acc[ai][0][m][1] * rs, g0 = acc[ai][1][m][0] * rs, g1 = acc[ai][1][m][1] * rs; u32x4 w;
;                     w.x = cvt_pk_bf16(a0[0] * sigmoidf_(g0[0]), a0[1] * sigmoidf_(g0[1])); w.y = cvt_pk_bf16(a0[2] * sigmoidf_(g0[2]), a0[3] * sigmoidf_(g0[3]));
;                     w.z = cvt_pk_bf16(a1[0] * sigmoidf_(g1[0]), a1[1] * sigmoidf_(g1[1])); w.w = cvt_pk_bf16(a1[2] * sigmoidf_(g1[2]), a1[3] * sigmoidf_(g1[3]));
;                     *(u32x4*)rowp = w;
	v_pk_mul_f32 v[34:35], v[32:33], v[50:51] op_sel_hi:[1,0]
	v_mul_f32_e32 v32, 0x3d372713, v36
	v_mul_f32_e32 v33, 0x3d372713, v37
	v_mul_f32_e32 v32, v36, v32
	v_mul_f32_e32 v33, v37, v33
	v_fma_f32 v32, v36, v32, v36
	v_fma_f32 v33, v37, v33, v37
	v_mul_f32_e32 v32, 0x3f4c422a, v32
	v_mul_f32_e32 v33, 0x3f4c422a, v33
	v_mul_f32_e32 v32, 0xc038aa3b, v32
	v_mul_f32_e32 v33, 0xc038aa3b, v33
	v_exp_f32_e32 v32, v32
	v_exp_f32_e32 v33, v33
	v_add_f32_e32 v32, 1.0, v32
	v_add_f32_e32 v33, 1.0, v33
	v_rcp_f32_e32 v32, v32
	v_rcp_f32_e32 v33, v33
	v_mul_f32_e32 v32, v36, v32
	v_mul_f32_e32 v33, v37, v33
	v_cvt_pk_bf16_f32 v32, v32, v33
	v_mul_f32_e32 v33, 0x3d372713, v38
	v_mul_f32_e32 v36, 0x3d372713, v39
	v_mul_f32_e32 v33, v38, v33
	v_mul_f32_e32 v36, v39, v36
	v_fma_f32 v33, v38, v33, v38
	v_fma_f32 v36, v39, v36, v39
	v_mul_f32_e32 v33, 0x3f4c422a, v33
	v_mul_f32_e32 v36, 0x3f4c422a, v36
	v_mul_f32_e32 v33, 0xc038aa3b, v33
	v_mul_f32_e32 v36, 0xc038aa3b, v36
	v_exp_f32_e32 v33, v33
	v_exp_f32_e32 v36, v36
	v_add_f32_e32 v33, 1.0, v33
	v_add_f32_e32 v36, 1.0, v36
	v_rcp_f32_e32 v33, v33
	v_rcp_f32_e32 v36, v36
	v_mul_f32_e32 v33, v38, v33
	v_mul_f32_e32 v36, v39, v36
	v_cvt_pk_bf16_f32 v33, v33, v36
	v_mul_f32_e32 v36, 0x3d372713, v34
	v_mul_f32_e32 v36, v34, v36
	v_fma_f32 v36, v34, v36, v34
	v_mul_f32_e32 v36, 0x3f4c422a, v36
	v_mul_f32_e32 v36, 0xc038aa3b, v36
	v_exp_f32_e32 v36, v36
	s_nop 0
	v_add_f32_e32 v36, 1.0, v36
	v_rcp_f32_e32 v36, v36
	s_nop 0
	v_mul_f32_e32 v34, v34, v36
	v_mul_f32_e32 v36, 0x3d372713, v35
	v_mul_f32_e32 v36, v35, v36
	v_fma_f32 v36, v35, v36, v35
	v_mul_f32_e32 v36, 0x3f4c422a, v36
	v_mul_f32_e32 v36, 0xc038aa3b, v36
	v_exp_f32_e32 v36, v36
	s_nop 0
	v_add_f32_e32 v36, 1.0, v36
	v_rcp_f32_e32 v36, v36
	s_nop 0
	v_mul_f32_e32 v35, v35, v36
	v_cvt_pk_bf16_f32 v34, v34, v35
	v_mul_f32_e32 v35, 0x3d372713, v40
	v_mul_f32_e32 v35, v40, v35
	v_mul_f32_e32 v36, 0x3d372713, v41
	v_fma_f32 v35, v40, v35, v40
	v_mul_f32_e32 v36, v41, v36
	v_mul_f32_e32 v35, 0x3f4c422a, v35
	v_fma_f32 v36, v41, v36, v41
	v_mul_f32_e32 v35, 0xc038aa3b, v35
	v_mul_f32_e32 v36, 0x3f4c422a, v36
	v_exp_f32_e32 v35, v35
	v_mul_f32_e32 v36, 0xc038aa3b, v36
	v_exp_f32_e32 v36, v36
	v_add_f32_e32 v35, 1.0, v35
	v_rcp_f32_e32 v35, v35
	v_add_f32_e32 v36, 1.0, v36
	v_rcp_f32_e32 v36, v36
	v_mul_f32_e32 v35, v40, v35
	v_mul_f32_e32 v36, v41, v36
	v_cvt_pk_bf16_f32 v35, v35, v36
	flat_store_dwordx4 v[48:49], v[32:35] offset:256 sc1
.LBB0_292:
	ds_read_b32 v34, v151 offset:384
	s_nop 0
	v_add_u32_e32 v32, 0xa0, v144
	v_ashrrev_i32_e32 v33, 31, v32
	s_and_b64 vcc, exec, s[0:1]
	s_mov_b64 s[16:17], -1
	s_cbranch_vccnz .LBB0_294
	v_lshlrev_b64 v[36:37], 10, v[32:33]
	v_lshl_add_u64 v[36:37], s[42:43], 0, v[36:37]
	s_lshl_b32 s14, s10, 8
	v_lshl_add_u64 v[36:37], v[36:37], 0, s[14:15]
	s_lshl_b32 s14, s58, 1
	v_lshl_add_u64 v[36:37], v[36:37], 0, s[14:15]
	v_mov_b32_e32 v143, v177
	s_waitcnt lgkmcnt(0)
	v_pk_mul_f32 v[48:49], v[20:21], v[34:35] op_sel_hi:[1,0]
	v_lshl_add_u64 v[40:41], v[36:37], 0, v[142:143]
	v_pk_mul_f32 v[38:39], v[30:31], v[34:35] op_sel_hi:[1,0]
	v_pk_mul_f32 v[36:37], v[28:29], v[34:35] op_sel_hi:[1,0]
	v_pk_mul_f32 v[42:43], v[26:27], v[34:35] op_sel_hi:[1,0]
	v_pk_mul_f32 v[44:45], v[24:25], v[34:35] op_sel_hi:[1,0]
	v_pk_mul_f32 v[46:47], v[22:23], v[34:35] op_sel_hi:[1,0]
	v_pk_mul_f32 v[50:51], v[18:19], v[34:35] op_sel_hi:[1,0]
	v_mul_f32_e32 v35, 0xbfb8aa3b, v48
	v_mul_f32_e32 v48, 0xbfb8aa3b, v49
	v_exp_f32_e32 v35, v35
	v_exp_f32_e32 v52, v48
	v_mul_f32_e32 v46, 0xbfb8aa3b, v46
	v_exp_f32_e32 v46, v46
	v_pk_mul_f32 v[48:49], v[16:17], v[34:35] op_sel_hi:[1,0]
	v_add_f32_e32 v35, 1.0, v35
	v_add_f32_e32 v52, 1.0, v52
	v_rcp_f32_e32 v35, v35
	v_rcp_f32_e32 v52, v52
	v_add_co_u32_e32 v40, vcc, 0xfffffc00, v40
	v_mul_f32_e32 v35, v36, v35
	v_mul_f32_e32 v36, v37, v52
	v_mul_f32_e32 v37, 0xbfb8aa3b, v47
	v_cvt_pk_bf16_f32 v36, v35, v36
	v_add_f32_e32 v35, 1.0, v46
	v_exp_f32_e32 v37, v37
	v_mul_f32_e32 v46, 0xbfb8aa3b, v48
	v_rcp_f32_e32 v35, v35
	v_exp_f32_e32 v46, v46
	v_add_f32_e32 v37, 1.0, v37
	v_rcp_f32_e32 v37, v37
	v_mul_f32_e32 v35, v38, v35
	v_add_f32_e32 v38, 1.0, v46
	v_rcp_f32_e32 v38, v38
	v_mul_f32_e32 v46, 0xbfb8aa3b, v49
	v_mul_f32_e32 v37, v39, v37
	v_exp_f32_e32 v46, v46
	v_cvt_pk_bf16_f32 v37, v35, v37
	v_mul_f32_e32 v35, v44, v38
	v_mul_f32_e32 v39, 0xbfb8aa3b, v50
	v_mul_f32_e32 v44, 0xbfb8aa3b, v51
	v_exp_f32_e32 v39, v39
	v_exp_f32_e32 v44, v44
	v_add_f32_e32 v38, 1.0, v46
	v_rcp_f32_e32 v38, v38
	v_add_f32_e32 v39, 1.0, v39
	v_add_f32_e32 v44, 1.0, v44
	v_rcp_f32_e32 v39, v39
	v_rcp_f32_e32 v44, v44
	v_mul_f32_e32 v38, v45, v38
	v_cvt_pk_bf16_f32 v38, v35, v38
	v_mul_f32_e32 v35, v42, v39
	v_mul_f32_e32 v39, v43, v44
	v_addc_co_u32_e32 v41, vcc, -1, v41, vcc
	s_mov_b64 s[16:17], 0
	v_cvt_pk_bf16_f32 v39, v35, v39
	flat_store_dwordx4 v[40:41], v[36:39] sc1
; __device__ __forceinline__ unsigned cvt_pk_bf16(float lo, float hi) { unsigned r; asm volatile("v_cvt_pk_bf16_f32 %0, %1, %2" : "=v"(r) : "v"(lo), "v"(hi)); return r; }
;     __device__ __forceinline__ void operator()(const f32x4 (&acc)[2][2][4][2], const Unit& u, int wr, int wc, int fr, int fq) const {
;     ...
;                 const int row = row0 + ai * HALF + m * 16; const float rs = tb[ai * 64 + m * 16 + fr];
;                 if (u.pn < 4) {
;                     bf16_t* rowp = UV + (size_t)row * 1024 + u.pn * BM + wc * 32 + 8 * fq;
; #pragma unroll
;                     for (int bj = 0; bj < 2; ++bj) { const f32x4 v0 = acc[ai][bj][m][0] * rs, v1 = acc[ai][bj][m][1] * rs; u32x4 w;
;                         w.x = cvt_pk_bf16(gelu_tanh(v0[0]), gelu_tanh(v0[1])); w.y = cvt_pk_bf16(gelu_tanh(v0[2]), gelu_tanh(v0[3]));
;                         w.z = cvt_pk_bf16(gelu_tanh(v1[0]), gelu_tanh(v1[1])); w.w = cvt_pk_bf16(gelu_tanh(v1[2]), gelu_tanh(v1[3]));
;                         *(u32x4*)(rowp + bj * HALF) = w; }
.LBB0_294:
	s_andn2_b64 vcc, exec, s[16:17]
	s_cbranch_vccnz .LBB0_296
	s_waitcnt lgkmcnt(0)
	v_pk_mul_f32 v[28:29], v[28:29], v[34:35] op_sel_hi:[1,0]
	v_pk_mul_f32 v[36:37], v[26:27], v[34:35] op_sel_hi:[1,0]
	v_pk_mul_f32 v[26:27], v[24:25], v[34:35] op_sel_hi:[1,0]
	v_mul_f32_e32 v24, 0x3d372713, v28
	v_mul_f32_e32 v25, 0x3d372713, v29
	v_mul_f32_e32 v24, v28, v24
	v_mul_f32_e32 v25, v29, v25
	v_fma_f32 v24, v28, v24, v28
	v_fma_f32 v25, v29, v25, v29
	v_mul_f32_e32 v24, 0x3f4c422a, v24
	v_mul_f32_e32 v25, 0x3f4c422a, v25
	v_mul_f32_e32 v24, 0xc038aa3b, v24
	v_mul_f32_e32 v25, 0xc038aa3b, v25
	v_exp_f32_e32 v24, v24
	v_exp_f32_e32 v25, v25
	v_pk_mul_f32 v[30:31], v[30:31], v[34:35] op_sel_hi:[1,0]
	v_lshlrev_b64 v[32:33], 11, v[32:33]
	v_add_f32_e32 v24, 1.0, v24
	v_add_f32_e32 v25, 1.0, v25
	v_rcp_f32_e32 v24, v24
	v_rcp_f32_e32 v25, v25
	s_lshl_b32 s16, s10, 8
	v_lshl_add_u64 v[32:33], s[40:41], 0, v[32:33]
	v_mul_f32_e32 v24, v28, v24
	v_mul_f32_e32 v25, v29, v25
	v_cvt_pk_bf16_f32 v24, v24, v25
	v_mul_f32_e32 v25, 0x3d372713, v30
	v_mul_f32_e32 v28, 0x3d372713, v31
	v_mul_f32_e32 v25, v30, v25
	v_mul_f32_e32 v28, v31, v28
	v_fma_f32 v25, v30, v25, v30
	v_fma_f32 v28, v31, v28, v31
	v_mul_f32_e32 v25, 0x3f4c422a, v25
	v_mul_f32_e32 v28, 0x3f4c422a, v28
	v_mul_f32_e32 v25, 0xc038aa3b, v25
	v_mul_f32_e32 v28, 0xc038aa3b, v28
	v_exp_f32_e32 v25, v25
	v_exp_f32_e32 v28, v28
	s_ashr_i32 s17, s16, 31
	v_lshl_add_u64 v[32:33], s[16:17], 1, v[32:33]
	v_add_f32_e32 v25, 1.0, v25
	v_add_f32_e32 v28, 1.0, v28
	v_rcp_f32_e32 v25, v25
	v_rcp_f32_e32 v28, v28
	s_lshl_b32 s14, s58, 1
	v_lshl_add_u64 v[32:33], v[32:33], 0, s[14:15]
	v_mul_f32_e32 v25, v30, v25
	v_mul_f32_e32 v28, v31, v28
	v_cvt_pk_bf16_f32 v25, v25, v28
	v_mul_f32_e32 v28, 0x3d372713, v26
	v_mul_f32_e32 v28, v26, v28
	v_fma_f32 v28, v26, v28, v26
	v_mul_f32_e32 v28, 0x3f4c422a, v28
	v_mul_f32_e32 v28, 0xc038aa3b, v28
	v_exp_f32_e32 v28, v28
	v_mov_b32_e32 v143, v177
	v_lshl_add_u64 v[32:33], v[32:33], 0, v[142:143]
	v_pk_mul_f32 v[20:21], v[20:21], v[34:35] op_sel_hi:[1,0]
	v_add_f32_e32 v28, 1.0, v28
	v_rcp_f32_e32 v28, v28
	v_pk_mul_f32 v[22:23], v[22:23], v[34:35] op_sel_hi:[1,0]
	v_mul_f32_e32 v26, v26, v28
	v_mul_f32_e32 v28, 0x3d372713, v27
	v_mul_f32_e32 v28, v27, v28
	v_fma_f32 v28, v27, v28, v27
	v_mul_f32_e32 v28, 0x3f4c422a, v28
	v_mul_f32_e32 v28, 0xc038aa3b, v28
	v_exp_f32_e32 v28, v28
	s_nop 0
	v_add_f32_e32 v28, 1.0, v28
	v_rcp_f32_e32 v28, v28
	s_nop 0
	v_mul_f32_e32 v27, v27, v28
	v_cvt_pk_bf16_f32 v26, v26, v27
	v_mul_f32_e32 v27, 0x3d372713, v36
	v_mul_f32_e32 v27, v36, v27
	v_mul_f32_e32 v28, 0x3d372713, v37
	v_fma_f32 v27, v36, v27, v36
	v_mul_f32_e32 v28, v37, v28
	v_mul_f32_e32 v27, 0x3f4c422a, v27
	v_fma_f32 v28, v37, v28, v37
	v_mul_f32_e32 v27, 0xc038aa3b, v27
	v_mul_f32_e32 v28, 0x3f4c422a, v28
	v_exp_f32_e32 v27, v27
	v_mul_f32_e32 v28, 0xc038aa3b, v28
	v_exp_f32_e32 v28, v28
	v_add_f32_e32 v27, 1.0, v27
	v_rcp_f32_e32 v27, v27
	v_add_f32_e32 v28, 1.0, v28
	v_rcp_f32_e32 v28, v28
	v_mul_f32_e32 v27, v36, v27
	v_mul_f32_e32 v28, v37, v28
	v_cvt_pk_bf16_f32 v27, v27, v28
	flat_store_dwordx4 v[32:33], v[24:27] sc1
	s_nop 1
	v_pk_mul_f32 v[24:25], v[18:19], v[34:35] op_sel_hi:[1,0]
	v_pk_mul_f32 v[18:19], v[16:17], v[34:35] op_sel_hi:[1,0]
	v_mul_f32_e32 v16, 0x3d372713, v20
	v_mul_f32_e32 v17, 0x3d372713, v21
	v_mul_f32_e32 v16, v20, v16
	v_mul_f32_e32 v17, v21, v17
	v_fma_f32 v16, v20, v16, v20
	v_fma_f32 v17, v21, v17, v21
	v_mul_f32_e32 v16, 0x3f4c422a, v16
	v_mul_f32_e32 v17, 0x3f4c422a, v17
	v_mul_f32_e32 v16, 0xc038aa3b, v16
	v_mul_f32_e32 v17, 0xc038aa3b, v17
	v_exp_f32_e32 v16, v16
	v_exp_f32_e32 v17, v17
	v_add_f32_e32 v16, 1.0, v16
	v_add_f32_e32 v17, 1.0, v17
	v_rcp_f32_e32 v16, v16
	v_rcp_f32_e32 v17, v17
	v_mul_f32_e32 v16, v20, v16
	v_mul_f32_e32 v17, v21, v17
	v_cvt_pk_bf16_f32 v16, v16, v17
	v_mul_f32_e32 v17, 0x3d372713, v22
	v_mul_f32_e32 v20, 0x3d372713, v23
	v_mul_f32_e32 v17, v22, v17
	v_mul_f32_e32 v20, v23, v20
	v_fma_f32 v17, v22, v17, v22
	v_fma_f32 v20, v23, v20, v23
	v_mul_f32_e32 v17, 0x3f4c422a, v17
	v_mul_f32_e32 v20, 0x3f4c422a, v20
	v_mul_f32_e32 v17, 0xc038aa3b, v17
	v_mul_f32_e32 v20, 0xc038aa3b, v20
	v_exp_f32_e32 v17, v17
	v_exp_f32_e32 v20, v20
	v_add_f32_e32 v17, 1.0, v17
	v_add_f32_e32 v20, 1.0, v20
	v_rcp_f32_e32 v17, v17
	v_rcp_f32_e32 v20, v20
	v_mul_f32_e32 v17, v22, v17
	v_mul_f32_e32 v20, v23, v20
	v_cvt_pk_bf16_f32 v17, v17, v20
	v_mul_f32_e32 v20, 0x3d372713, v18
	v_mul_f32_e32 v20, v18, v20
	v_fma_f32 v20, v18, v20, v18
	v_mul_f32_e32 v20, 0x3f4c422a, v20
	v_mul_f32_e32 v20, 0xc038aa3b, v20
	v_exp_f32_e32 v20, v20
	s_nop 0
	v_add_f32_e32 v20, 1.0, v20
	v_rcp_f32_e32 v20, v20
	s_nop 0
	v_mul_f32_e32 v18, v18, v20
	v_mul_f32_e32 v20, 0x3d372713, v19
	v_mul_f32_e32 v20, v19, v20
	v_fma_f32 v20, v19, v20, v19
	v_mul_f32_e32 v20, 0x3f4c422a, v20
	v_mul_f32_e32 v20, 0xc038aa3b, v20
	v_exp_f32_e32 v20, v20
	s_nop 0
	v_add_f32_e32 v20, 1.0, v20
	v_rcp_f32_e32 v20, v20
	s_nop 0
	v_mul_f32_e32 v19, v19, v20
	v_cvt_pk_bf16_f32 v18, v18, v19
	v_mul_f32_e32 v19, 0x3d372713, v24
	v_mul_f32_e32 v19, v24, v19
	v_mul_f32_e32 v20, 0x3d372713, v25
	v_fma_f32 v19, v24, v19, v24
	v_mul_f32_e32 v20, v25, v20
	v_mul_f32_e32 v19, 0x3f4c422a, v19
	v_fma_f32 v20, v25, v20, v25
	v_mul_f32_e32 v19, 0xc038aa3b, v19
	v_mul_f32_e32 v20, 0x3f4c422a, v20
	v_exp_f32_e32 v19, v19
	v_mul_f32_e32 v20, 0xc038aa3b, v20
	v_exp_f32_e32 v20, v20
	v_add_f32_e32 v19, 1.0, v19
	v_rcp_f32_e32 v19, v19
	v_add_f32_e32 v20, 1.0, v20
	v_rcp_f32_e32 v20, v20
	v_mul_f32_e32 v19, v24, v19
	v_mul_f32_e32 v20, v25, v20
	v_cvt_pk_bf16_f32 v19, v19, v20
	flat_store_dwordx4 v[32:33], v[16:19] offset:256 sc1
; __device__ __forceinline__ unsigned cvt_pk_bf16(float lo, float hi) { unsigned r; asm volatile("v_cvt_pk_bf16_f32 %0, %1, %2" : "=v"(r) : "v"(lo), "v"(hi)); return r; }
; __device__ __forceinline__ float sigmoidf_(float x) { return __builtin_amdgcn_rcpf(1.0f + __builtin_amdgcn_exp2f(-1.4426950408889634f * x)); }
;     __device__ __forceinline__ void operator()(const f32x4 (&acc)[2][2][4][2], const Unit& u, int wr, int wc, int fr, int fq) const {
;     ...
;                 const int row = row0 + ai * HALF + m * 16; const float rs = tb[ai * 64 + m * 16 + fr];
;                 if (u.pn < 4) {
;                     bf16_t* rowp = UV + (size_t)row * 1024 + u.pn * BM + wc * 32 + 8 * fq;
; #pragma unroll
;                     for (int bj = 0; bj < 2; ++bj) { const f32x4 v0 = acc[ai][bj][m][0] * rs, v1 = acc[ai][bj][m][1] * rs; u32x4 w;
;                         w.x = cvt_pk_bf16(gelu_tanh(v0[0]), gelu_tanh(v0[1])); w.y = cvt_pk_bf16(gelu_tanh(v0[2]), gelu_tanh(v0[3]));
;                         w.z = cvt_pk_bf16(gelu_tanh(v1[0]), gelu_tanh(v1[1])); w.w = cvt_pk_bf16(gelu_tanh(v1[2]), gelu_tanh(v1[3]));
;                         *(u32x4*)(rowp + bj * HALF) = w; }
;                 } else {
;                     bf16_t* rowp = Gb + (size_t)row * 512 + (u.pn - 4) * 128 + wc * 32 + 8 * fq;
;                     const f32x4 a0 = acc[ai][0][m][0] * rs, a1 = acc[ai][0][m][1] * rs, g0 = acc[ai][1][m][0] * rs, g1 = acc[ai][1][m][1] * rs; u32x4 w;
;                     w.x = cvt_pk_bf16(a0[0] * sigmoidf_(g0[0]), a0[1] * sigmoidf_(g0[1])); w.y = cvt_pk_bf16(a0[2] * sigmoidf_(g0[2]), a0[3] * sigmoidf_(g0[3]));
;                     w.z = cvt_pk_bf16(a1[0] * sigmoidf_(g1[0]), a1[1] * sigmoidf_(g1[1])); w.w = cvt_pk_bf16(a1[2] * sigmoidf_(g1[2]), a1[3] * sigmoidf_(g1[3]));
;                     *(u32x4*)rowp = w;
.LBB0_296:
	ds_read_b32 v16, v151 offset:448
	s_nop 0
	v_add_u32_e32 v18, 0xb0, v144
	v_ashrrev_i32_e32 v19, 31, v18
	s_and_b64 vcc, exec, s[0:1]
	s_mov_b64 s[0:1], -1
	s_cbranch_vccnz .LBB0_299
	v_lshlrev_b64 v[20:21], 10, v[18:19]
	v_lshl_add_u64 v[20:21], s[42:43], 0, v[20:21]
	s_lshl_b32 s14, s10, 8
	v_lshl_add_u64 v[20:21], v[20:21], 0, s[14:15]
	s_lshl_b32 s14, s58, 1
	v_lshl_add_u64 v[20:21], v[20:21], 0, s[14:15]
	v_mov_b32_e32 v143, v177
	s_waitcnt lgkmcnt(0)
	v_pk_mul_f32 v[32:33], v[4:5], v[16:17] op_sel_hi:[1,0]
	v_lshl_add_u64 v[24:25], v[20:21], 0, v[142:143]
	v_pk_mul_f32 v[22:23], v[14:15], v[16:17] op_sel_hi:[1,0]
	v_pk_mul_f32 v[20:21], v[12:13], v[16:17] op_sel_hi:[1,0]
	v_pk_mul_f32 v[26:27], v[10:11], v[16:17] op_sel_hi:[1,0]
	v_pk_mul_f32 v[28:29], v[8:9], v[16:17] op_sel_hi:[1,0]
	v_pk_mul_f32 v[30:31], v[6:7], v[16:17] op_sel_hi:[1,0]
	v_pk_mul_f32 v[34:35], v[2:3], v[16:17] op_sel_hi:[1,0]
	v_mul_f32_e32 v17, 0xbfb8aa3b, v32
	v_mul_f32_e32 v32, 0xbfb8aa3b, v33
	v_exp_f32_e32 v17, v17
	v_exp_f32_e32 v36, v32
	v_mul_f32_e32 v30, 0xbfb8aa3b, v30
	v_exp_f32_e32 v30, v30
	v_pk_mul_f32 v[32:33], v[0:1], v[16:17] op_sel_hi:[1,0]
	v_add_f32_e32 v17, 1.0, v17
	v_add_f32_e32 v36, 1.0, v36
	v_rcp_f32_e32 v17, v17
	v_rcp_f32_e32 v36, v36
	v_add_co_u32_e32 v24, vcc, 0xfffffc00, v24
	v_mul_f32_e32 v17, v20, v17
	v_mul_f32_e32 v20, v21, v36
	v_mul_f32_e32 v21, 0xbfb8aa3b, v31
	v_cvt_pk_bf16_f32 v20, v17, v20
	v_add_f32_e32 v17, 1.0, v30
	v_exp_f32_e32 v21, v21
	v_mul_f32_e32 v30, 0xbfb8aa3b, v32
	v_rcp_f32_e32 v17, v17
	v_exp_f32_e32 v30, v30
	v_add_f32_e32 v21, 1.0, v21
	v_rcp_f32_e32 v21, v21
	v_mul_f32_e32 v17, v22, v17
	v_add_f32_e32 v22, 1.0, v30
	v_rcp_f32_e32 v22, v22
	v_mul_f32_e32 v30, 0xbfb8aa3b, v33
	v_mul_f32_e32 v21, v23, v21
	v_exp_f32_e32 v30, v30
	v_cvt_pk_bf16_f32 v21, v17, v21
	v_mul_f32_e32 v17, v28, v22
	v_mul_f32_e32 v23, 0xbfb8aa3b, v34
	v_mul_f32_e32 v28, 0xbfb8aa3b, v35
	v_exp_f32_e32 v23, v23
	v_exp_f32_e32 v28, v28
	v_add_f32_e32 v22, 1.0, v30
	v_rcp_f32_e32 v22, v22
	v_add_f32_e32 v23, 1.0, v23
	v_add_f32_e32 v28, 1.0, v28
	v_rcp_f32_e32 v23, v23
	v_rcp_f32_e32 v28, v28
	v_mul_f32_e32 v22, v29, v22
	v_cvt_pk_bf16_f32 v22, v17, v22
	v_mul_f32_e32 v17, v26, v23
	v_mul_f32_e32 v23, v27, v28
	v_addc_co_u32_e32 v25, vcc, -1, v25, vcc
	v_cvt_pk_bf16_f32 v23, v17, v23
	flat_store_dwordx4 v[24:25], v[20:23] sc1
	s_cbranch_execz .LBB0_300

; __device__ __forceinline__ unsigned cvt_pk_bf16(float lo, float hi) { unsigned r; asm volatile("v_cvt_pk_bf16_f32 %0, %1, %2" : "=v"(r) : "v"(lo), "v"(hi)); return r; }
;     __device__ __forceinline__ void operator()(const f32x4 (&acc)[2][2][4][2], const Unit& u, int wr, int wc, int fr, int fq) const {
;     ...
;                     bf16_t* rowp = UV + (size_t)row * 1024 + u.pn * BM + wc * 32 + 8 * fq;
; #pragma unroll
;                     for (int bj = 0; bj < 2; ++bj) { const f32x4 v0 = acc[ai][bj][m][0] * rs, v1 = acc[ai][bj][m][1] * rs; u32x4 w;
;                         w.x = cvt_pk_bf16(gelu_tanh(v0[0]), gelu_tanh(v0[1])); w.y = cvt_pk_bf16(gelu_tanh(v0[2]), gelu_tanh(v0[3]));
;                         w.z = cvt_pk_bf16(gelu_tanh(v1[0]), gelu_tanh(v1[1])); w.w = cvt_pk_bf16(gelu_tanh(v1[2]), gelu_tanh(v1[3]));
;                         *(u32x4*)(rowp + bj * HALF) = w; }
; template <class Epi, class Sched, bool ALIGN_EPI = false, bool SP2 = false>
; __device__ __forceinline__ void gemm_phase(PG8_LAS unsigned char* lds, const Gemm g, const Sched& S, const Epi& E) {
;     ...
;         if constexpr (!Epi::AFTER_DRAIN) { E(acc, cur, wr, wc, fr, fq); S.done(cur); }
;         if (!has_next) break;
; #pragma unroll
;         for (int a = 0; a < 2; ++a)
; #pragma unroll
;             for (int b = 0; b < 2; ++b)
; #pragma unroll
;                 for (int m = 0; m < 4; ++m)
; #pragma unroll
;                     for (int n = 0; n < 2; ++n) acc[a][b][m][n] = (f32x4){0.f, 0.f, 0.f, 0.f};
;         cur = nxt; cA = nA; cB = nB; ++ui;
.LBB0_300:
	s_waitcnt lgkmcnt(0)
	v_pk_mul_f32 v[12:13], v[12:13], v[16:17] op_sel_hi:[1,0]
	v_pk_mul_f32 v[20:21], v[10:11], v[16:17] op_sel_hi:[1,0]
	v_mul_f32_e32 v10, 0x3d372713, v12
	v_mul_f32_e32 v10, v12, v10
	v_fma_f32 v10, v12, v10, v12
	v_mul_f32_e32 v10, 0x3f4c422a, v10
	v_mul_f32_e32 v10, 0xc038aa3b, v10
	v_pk_mul_f32 v[14:15], v[14:15], v[16:17] op_sel_hi:[1,0]
	v_exp_f32_e32 v17, v10
	v_mul_f32_e32 v10, 0x3d372713, v13
	v_mul_f32_e32 v10, v13, v10
	v_fma_f32 v10, v13, v10, v13
	v_mul_f32_e32 v10, 0x3f4c422a, v10
	v_mul_f32_e32 v10, 0xc038aa3b, v10
	v_exp_f32_e32 v22, v10
	v_pk_mul_f32 v[10:11], v[8:9], v[16:17] op_sel_hi:[1,0]
	v_add_f32_e32 v8, 1.0, v17
	v_mul_f32_e32 v17, 0x3d372713, v14
	v_mul_f32_e32 v17, v14, v17
	v_fma_f32 v17, v14, v17, v14
	v_add_f32_e32 v9, 1.0, v22
	v_mul_f32_e32 v17, 0x3f4c422a, v17
	v_rcp_f32_e32 v8, v8
	v_rcp_f32_e32 v9, v9
	v_mul_f32_e32 v17, 0xc038aa3b, v17
	v_exp_f32_e32 v17, v17
	v_mul_f32_e32 v8, v12, v8
	v_mul_f32_e32 v9, v13, v9
	v_mul_f32_e32 v12, 0x3d372713, v15
	v_mul_f32_e32 v13, 0x3d372713, v10
	v_cvt_pk_bf16_f32 v8, v8, v9
	v_add_f32_e32 v9, 1.0, v17
	v_mul_f32_e32 v12, v15, v12
	v_mul_f32_e32 v13, v10, v13
	v_rcp_f32_e32 v9, v9
	v_fma_f32 v12, v15, v12, v15
	v_fma_f32 v13, v10, v13, v10
	v_mul_f32_e32 v12, 0x3f4c422a, v12
	v_mul_f32_e32 v13, 0x3f4c422a, v13
	v_mul_f32_e32 v12, 0xc038aa3b, v12
	v_mul_f32_e32 v13, 0xc038aa3b, v13
	v_exp_f32_e32 v12, v12
	v_exp_f32_e32 v13, v13
	v_mul_f32_e32 v9, v14, v9
	v_mul_f32_e32 v14, 0x3d372713, v11
	v_mul_f32_e32 v14, v11, v14
	v_fma_f32 v14, v11, v14, v11
	v_add_f32_e32 v12, 1.0, v12
	v_add_f32_e32 v13, 1.0, v13
	v_mul_f32_e32 v14, 0x3f4c422a, v14
	v_rcp_f32_e32 v12, v12
	v_rcp_f32_e32 v13, v13
	v_mul_f32_e32 v14, 0xc038aa3b, v14
	v_exp_f32_e32 v14, v14
	v_mul_f32_e32 v12, v15, v12
	v_mul_f32_e32 v10, v10, v13
	v_mul_f32_e32 v13, 0x3d372713, v20
	v_cvt_pk_bf16_f32 v9, v9, v12
	v_add_f32_e32 v12, 1.0, v14
	v_mul_f32_e32 v13, v20, v13
	v_mul_f32_e32 v14, 0x3d372713, v21
	v_fma_f32 v13, v20, v13, v20
	v_mul_f32_e32 v14, v21, v14
	v_mul_f32_e32 v13, 0x3f4c422a, v13
	v_fma_f32 v14, v21, v14, v21
	v_mul_f32_e32 v13, 0xc038aa3b, v13
	v_mul_f32_e32 v14, 0x3f4c422a, v14
	v_exp_f32_e32 v13, v13
	v_mul_f32_e32 v14, 0xc038aa3b, v14
	v_exp_f32_e32 v14, v14
	v_rcp_f32_e32 v12, v12
	v_add_f32_e32 v13, 1.0, v13
	v_lshlrev_b64 v[18:19], 11, v[18:19]
	s_lshl_b32 s0, s10, 8
	v_rcp_f32_e32 v13, v13
	v_add_f32_e32 v14, 1.0, v14
	v_lshl_add_u64 v[18:19], s[40:41], 0, v[18:19]
	s_ashr_i32 s1, s0, 31
	v_rcp_f32_e32 v14, v14
	v_lshl_add_u64 v[18:19], s[0:1], 1, v[18:19]
	s_lshl_b32 s14, s58, 1
	v_lshl_add_u64 v[18:19], v[18:19], 0, s[14:15]
	v_mov_b32_e32 v143, v177
	v_mul_f32_e32 v11, v11, v12
	v_lshl_add_u64 v[18:19], v[18:19], 0, v[142:143]
	v_cvt_pk_bf16_f32 v10, v10, v11
	v_mul_f32_e32 v11, v20, v13
	v_pk_mul_f32 v[4:5], v[4:5], v[16:17] op_sel_hi:[1,0]
	v_mul_f32_e32 v12, v21, v14
	v_cvt_pk_bf16_f32 v11, v11, v12
	flat_store_dwordx4 v[18:19], v[8:11] sc1
	v_pk_mul_f32 v[6:7], v[6:7], v[16:17] op_sel_hi:[1,0]
	s_nop 0
	v_pk_mul_f32 v[8:9], v[2:3], v[16:17] op_sel_hi:[1,0]
	v_mul_f32_e32 v2, 0x3d372713, v4
	v_mul_f32_e32 v2, v4, v2
	v_fma_f32 v2, v4, v2, v4
	v_mul_f32_e32 v2, 0x3f4c422a, v2
	v_mul_f32_e32 v2, 0xc038aa3b, v2
	v_exp_f32_e32 v10, v2
	v_mul_f32_e32 v2, 0x3d372713, v5
	v_mul_f32_e32 v2, v5, v2
	v_fma_f32 v2, v5, v2, v5
	v_mul_f32_e32 v2, 0x3f4c422a, v2
	v_mul_f32_e32 v2, 0xc038aa3b, v2
	v_exp_f32_e32 v11, v2
	v_pk_mul_f32 v[2:3], v[0:1], v[16:17] op_sel_hi:[1,0]
	v_add_f32_e32 v0, 1.0, v10
	v_mul_f32_e32 v10, 0x3d372713, v6
	v_mul_f32_e32 v10, v6, v10
	v_fma_f32 v10, v6, v10, v6
	v_add_f32_e32 v1, 1.0, v11
	v_mul_f32_e32 v10, 0x3f4c422a, v10
	v_rcp_f32_e32 v0, v0
	v_rcp_f32_e32 v1, v1
	v_mul_f32_e32 v10, 0xc038aa3b, v10
	v_exp_f32_e32 v10, v10
	v_mul_f32_e32 v0, v4, v0
	v_mul_f32_e32 v1, v5, v1
	v_mul_f32_e32 v4, 0x3d372713, v7
	v_mul_f32_e32 v5, 0x3d372713, v2
	v_cvt_pk_bf16_f32 v0, v0, v1
	v_add_f32_e32 v1, 1.0, v10
	v_mul_f32_e32 v4, v7, v4
	v_mul_f32_e32 v5, v2, v5
	v_rcp_f32_e32 v1, v1
	v_fma_f32 v4, v7, v4, v7
	v_fma_f32 v5, v2, v5, v2
	v_mul_f32_e32 v4, 0x3f4c422a, v4
	v_mul_f32_e32 v5, 0x3f4c422a, v5
	v_mul_f32_e32 v4, 0xc038aa3b, v4
	v_mul_f32_e32 v5, 0xc038aa3b, v5
	v_exp_f32_e32 v4, v4
	v_exp_f32_e32 v5, v5
	v_mul_f32_e32 v1, v6, v1
	v_mul_f32_e32 v6, 0x3d372713, v3
	v_mul_f32_e32 v6, v3, v6
	v_fma_f32 v6, v3, v6, v3
	v_add_f32_e32 v4, 1.0, v4
	v_add_f32_e32 v5, 1.0, v5
	v_mul_f32_e32 v6, 0x3f4c422a, v6
	v_rcp_f32_e32 v4, v4
	v_rcp_f32_e32 v5, v5
	v_mul_f32_e32 v6, 0xc038aa3b, v6
	v_exp_f32_e32 v6, v6
	v_mul_f32_e32 v4, v7, v4
	v_mul_f32_e32 v2, v2, v5
	v_mul_f32_e32 v5, 0x3d372713, v8
	v_cvt_pk_bf16_f32 v1, v1, v4
	v_add_f32_e32 v4, 1.0, v6
	v_mul_f32_e32 v5, v8, v5
	v_mul_f32_e32 v6, 0x3d372713, v9
	v_fma_f32 v5, v8, v5, v8
	v_mul_f32_e32 v6, v9, v6
	v_mul_f32_e32 v5, 0x3f4c422a, v5
	v_fma_f32 v6, v9, v6, v9
	v_mul_f32_e32 v5, 0xc038aa3b, v5
	v_mul_f32_e32 v6, 0x3f4c422a, v6
	v_exp_f32_e32 v5, v5
	v_mul_f32_e32 v6, 0xc038aa3b, v6
	v_exp_f32_e32 v6, v6
	v_rcp_f32_e32 v4, v4
	v_add_f32_e32 v5, 1.0, v5
	v_rcp_f32_e32 v5, v5
	v_add_f32_e32 v6, 1.0, v6
	v_rcp_f32_e32 v6, v6
	v_mul_f32_e32 v3, v3, v4
	v_cvt_pk_bf16_f32 v2, v2, v3
	v_mul_f32_e32 v3, v8, v5
	v_mul_f32_e32 v4, v9, v6
	v_cvt_pk_bf16_f32 v3, v3, v4
	flat_store_dwordx4 v[18:19], v[0:3] offset:256 sc1
	s_andn2_b64 vcc, exec, s[38:39]
	s_mov_b64 s[0:1], -1
	s_cbranch_vccnz .LBB0_257

; #define LAS __attribute__((address_space(3)))
; __device__ __forceinline__ void attn_phase(const Args& A, LAS unsigned char* lds, int tid, int lane, int wave, int bx, int G) {
;     ...
;         {
;             bf16_t* Op = (bf16_t*)(A.ws + WS_O) + (size_t)(bh >> 4) * SEQ * 1024 + (bh & 15) * 64;
; #pragma unroll
;             for (int rd = 0; rd < 8; ++rd) { const int idx = rd * NTHR + tid, row = idx >> 3, ch = idx & 7;
;                 const u32x4 v = *(const LAS u32x4*)(lds + row * OB_STRIDE + ch * 16);
;                 *(u32x4*)(Op + (size_t)(pos0 + row) * 1024 + ch * 8) = v; }
;         }
;         __syncthreads();
.LBB0_430:
	v_readlane_b32 s2, v254, 59
	s_ashr_i32 s6, s2, 8
	s_ashr_i32 s7, s6, 31
	s_lshl_b64 s[6:7], s[6:7], 24
	v_readlane_b32 s3, v253, 60
	s_add_u32 s3, s3, s6
	v_readlane_b32 s6, v253, 61
	s_addc_u32 s7, s6, s7
	s_lshl_b32 s6, s24, 7
	s_and_b32 s6, s6, 0x780
	ds_read_b128 v[0:3], v203
	s_add_u32 s6, s3, s6
	v_add_u32_e32 v6, s10, v175
	s_addc_u32 s7, s7, 0
	v_mov_b32_e32 v159, v177
	v_ashrrev_i32_e32 v7, 31, v6
	v_lshl_add_u64 v[4:5], s[6:7], 0, v[158:159]
	v_lshlrev_b64 v[6:7], 11, v[6:7]
	v_lshl_add_u64 v[6:7], v[4:5], 0, v[6:7]
	s_waitcnt lgkmcnt(0)
	global_store_dwordx4 v[6:7], v[0:3], off sc1
	ds_read_b128 v[0:3], v204
	v_add_u32_e32 v6, s10, v194
	v_ashrrev_i32_e32 v7, 31, v6
	v_lshlrev_b64 v[6:7], 11, v[6:7]
	v_lshl_add_u64 v[6:7], v[4:5], 0, v[6:7]
	s_waitcnt lgkmcnt(0)
	global_store_dwordx4 v[6:7], v[0:3], off sc1
	ds_read_b128 v[0:3], v205
	v_add_u32_e32 v6, s10, v195
	v_ashrrev_i32_e32 v7, 31, v6
	v_lshlrev_b64 v[6:7], 11, v[6:7]
	v_lshl_add_u64 v[6:7], v[4:5], 0, v[6:7]
	s_waitcnt lgkmcnt(0)
	global_store_dwordx4 v[6:7], v[0:3], off sc1
	ds_read_b128 v[0:3], v206
	v_add_u32_e32 v6, s10, v196
	v_ashrrev_i32_e32 v7, 31, v6
	v_lshlrev_b64 v[6:7], 11, v[6:7]
	v_lshl_add_u64 v[6:7], v[4:5], 0, v[6:7]
	s_waitcnt lgkmcnt(0)
	global_store_dwordx4 v[6:7], v[0:3], off sc1
	ds_read_b128 v[0:3], v207
	v_add_u32_e32 v6, s10, v197
	v_ashrrev_i32_e32 v7, 31, v6
	v_lshlrev_b64 v[6:7], 11, v[6:7]
	v_lshl_add_u64 v[6:7], v[4:5], 0, v[6:7]
	s_waitcnt lgkmcnt(0)
	global_store_dwordx4 v[6:7], v[0:3], off sc1
	ds_read_b128 v[0:3], v208
	v_add_u32_e32 v6, s10, v198
	v_ashrrev_i32_e32 v7, 31, v6
	v_lshlrev_b64 v[6:7], 11, v[6:7]
	v_lshl_add_u64 v[6:7], v[4:5], 0, v[6:7]
	s_waitcnt lgkmcnt(0)
	global_store_dwordx4 v[6:7], v[0:3], off sc1
	ds_read_b128 v[0:3], v209
	v_add_u32_e32 v6, s10, v199
	v_ashrrev_i32_e32 v7, 31, v6
	v_lshlrev_b64 v[6:7], 11, v[6:7]
	v_lshl_add_u64 v[6:7], v[4:5], 0, v[6:7]
	s_waitcnt lgkmcnt(0)
	global_store_dwordx4 v[6:7], v[0:3], off sc1
	ds_read_b128 v[0:3], v210
	v_add_u32_e32 v6, s10, v200
	v_ashrrev_i32_e32 v7, 31, v6
	v_lshlrev_b64 v[6:7], 11, v[6:7]
	v_lshl_add_u64 v[4:5], v[4:5], 0, v[6:7]
	s_mov_b64 s[6:7], 0
	v_readlane_b32 s2, v254, 62
	s_waitcnt lgkmcnt(0)
	global_store_dwordx4 v[4:5], v[0:3], off sc1
	s_barrier
	s_branch .LBB0_374
